# compute segments: s_setprio 1 moved before the opening barrier, duplicate lgkmcnt(0) wait after the barrier removed, s_setprio 0 moved behind the closing barrier (MFMA-wave path is the critical one)
# speedup vs baseline: 1.0298x; 1.0131x over previous
; #define PG8_STAGE(bufoff, gbase, voff) do { _Pragma("unroll") for (int _i = 0; _i < 2; ++_i) { \
;         const unsigned _m0 = ldsb + (unsigned)((bufoff) + _i * 8192); const char* _gb = (const char*)(gbase); \
;         asm volatile("s_mov_b32 m0, %0\n\ts_nop 0\n\tglobal_load_lds_dwordx4 %1, %2" :: "s"(_m0), "v"((voff)[_i]), "s"(_gb) : "m0", "memory"); } } while (0)
; #define PG8_LDA(dst, b, h) do { _Pragma("unroll") for (int m = 0; m < 4; ++m) _Pragma("unroll") for (int k = 0; k < 2; ++k) dst[m][k] = *(const LAS bf16x8*)(lds + PG8_SA(b, h) + aoff + m * 2048 + k * 1024); } while (0)
; #define PG8_LDB(dst, b, h) do { _Pragma("unroll") for (int n = 0; n < 2; ++n) _Pragma("unroll") for (int k = 0; k < 2; ++k) dst[n][k] = *(const LAS bf16x8*)(lds + PG8_SB(b, h) + boff + n * 2048 + k * 1024); } while (0)
; #define PG8_WAIT_V(n) asm volatile("s_waitcnt vmcnt(" #n ")" ::: "memory")
; #define PG8_WAIT_L(n) asm volatile("s_waitcnt lgkmcnt(" #n ")" ::: "memory")
; #define PG8_BAR __builtin_amdgcn_s_barrier()
; #define PG8_SCHED __builtin_amdgcn_sched_barrier(0)
; template <class Epi, bool ALIGN_EPI>
; __device__ __forceinline__ void gemm_phase(LAS unsigned char* lds, const Gemm g, const StaticOrder& S, const Epi& E) {
;     ...
;         const char* nA = has_next ? (const char*)g.A + (size_t)nxt.pm * tstepA + (size_t)nxt.pn * g.a_pn_off * 2 + (size_t)(nxt.pm >> 4) * g.a_adj : cA; const char* nB = has_next ? (const char*)g.Bt + (size_t)nxt.pn * tstepB : cB;
;         for (int t = 0; t < nt; t += 2) {
;             const bool last = (t == nt - 2);
;             const char* a1 = cA + (size_t)(t + 1) * kstep;
;             const char* a2 = last ? nA : cA + (size_t)(t + 2) * kstep; const char* b2 = last ? nB : cB + (size_t)(t + 2) * kstep;
;             const char* a3 = a2 + kstep; const char* b3 = b2 + kstep;
;             PG8_LDB(B0, 0, 0); PG8_LDB(B1, 0, 1); PG8_SCHED; PG8_LDA(At, 0, 0); PG8_STAGE(PG8_SA(1, 1), a1 + hstepA, voffA);
;             PG8_WAIT_V(8); PG8_WAIT_L(0); PG8_BAR; PG8_MMA(0, 0, At, B0); PG8_MMA(0, 1, At, B1); PG8_BAR; PG8_SCHED;
;             PG8_LDA(At, 0, 1); PG8_STAGE(PG8_SB(0, 0), b2, voffB); PG8_STAGE(PG8_SB(0, 1), b2 + hstepB, voffB); PG8_STAGE(PG8_SA(0, 0), a2, voffA);
;             PG8_WAIT_V(8); PG8_WAIT_L(0); PG8_BAR; PG8_MMA(1, 0, At, B0); PG8_MMA(1, 1, At, B1); PG8_BAR; PG8_SCHED;
.LBB0_150:
	s_add_u32 s4, s48, 0x100
	s_addc_u32 s5, s49, 0
	s_add_u32 s37, s54, 0x100
	s_addc_u32 s44, s55, 0
	s_mov_b32 s45, 0
	s_waitcnt lgkmcnt(0)
	s_add_i32 s51, s45, 2
	s_cmp_eq_u32 s67, s45
	s_cselect_b32 s56, s0, s37
	s_cselect_b32 s57, s1, s44
	s_cselect_b32 s54, s94, s4
	s_cselect_b32 s55, s95, s5
	s_add_u32 s48, s56, 0x80
	s_addc_u32 s49, s57, 0
	s_add_u32 s45, s37, s15
	s_addc_u32 s59, s44, 0
	s_add_u32 s58, s45, 0xffffff80
	s_addc_u32 s59, s59, -1
	s_mov_b32 m0, s68
	s_nop 0
	global_load_lds_dwordx4 v0, s[58:59]
	s_nop 0
	s_mov_b32 m0, s85
	s_nop 0
	global_load_lds_dwordx4 v240, s[58:59]
	s_waitcnt vmcnt(8)
	s_waitcnt lgkmcnt(0)
	s_setprio 1
	s_barrier
	v_mfma_f32_16x16x32_bf16 v[172:175], v[108:111], v[156:159], 0
	v_mfma_f32_16x16x32_bf16 v[172:175], v[120:123], v[160:163], v[172:175]
	v_mfma_f32_16x16x32_bf16 v[168:171], v[128:131], v[156:159], 0
	v_mfma_f32_16x16x32_bf16 v[168:171], v[132:135], v[160:163], v[168:171]
	v_mfma_f32_16x16x32_bf16 v[140:143], v[136:139], v[156:159], 0
	v_mfma_f32_16x16x32_bf16 v[140:143], v[144:147], v[160:163], v[140:143]
	v_mfma_f32_16x16x32_bf16 v[124:127], v[148:151], v[156:159], 0
	v_mfma_f32_16x16x32_bf16 v[124:127], v[152:155], v[160:163], v[124:127]
	v_mfma_f32_16x16x32_bf16 v[100:103], v[148:151], v[164:167], 0
	v_mfma_f32_16x16x32_bf16 v[100:103], v[152:155], v[176:179], v[100:103]
	v_mfma_f32_16x16x32_bf16 v[104:107], v[136:139], v[164:167], 0
	v_mfma_f32_16x16x32_bf16 v[104:107], v[144:147], v[176:179], v[104:107]
	v_mfma_f32_16x16x32_bf16 v[112:115], v[128:131], v[164:167], 0
	v_mfma_f32_16x16x32_bf16 v[112:115], v[132:135], v[176:179], v[112:115]
	v_mfma_f32_16x16x32_bf16 v[116:119], v[108:111], v[164:167], 0
	v_mfma_f32_16x16x32_bf16 v[116:119], v[120:123], v[176:179], v[116:119]
	v_mfma_f32_16x16x32_bf16 v[96:99], v[108:111], v[180:183], 0
	v_mfma_f32_16x16x32_bf16 v[96:99], v[120:123], v[184:187], v[96:99]
	v_mfma_f32_16x16x32_bf16 v[92:95], v[128:131], v[180:183], 0
	v_mfma_f32_16x16x32_bf16 v[92:95], v[132:135], v[184:187], v[92:95]
	v_mfma_f32_16x16x32_bf16 v[88:91], v[136:139], v[180:183], 0
	v_mfma_f32_16x16x32_bf16 v[88:91], v[144:147], v[184:187], v[88:91]
	v_mfma_f32_16x16x32_bf16 v[84:87], v[148:151], v[180:183], 0
	v_mfma_f32_16x16x32_bf16 v[84:87], v[152:155], v[184:187], v[84:87]
	v_mfma_f32_16x16x32_bf16 v[68:71], v[148:151], v[188:191], 0
	v_mfma_f32_16x16x32_bf16 v[68:71], v[152:155], v[202:205], v[68:71]
	v_mfma_f32_16x16x32_bf16 v[72:75], v[136:139], v[188:191], 0
	v_mfma_f32_16x16x32_bf16 v[72:75], v[144:147], v[202:205], v[72:75]
	v_mfma_f32_16x16x32_bf16 v[76:79], v[128:131], v[188:191], 0
	v_mfma_f32_16x16x32_bf16 v[76:79], v[132:135], v[202:205], v[76:79]
	v_mfma_f32_16x16x32_bf16 v[80:83], v[108:111], v[188:191], 0
	v_mfma_f32_16x16x32_bf16 v[80:83], v[120:123], v[202:205], v[80:83]
	s_barrier
	s_setprio 0
	ds_read_b128 v[156:159], v245 offset:16384
	ds_read_b128 v[160:163], v245 offset:17408
	ds_read_b128 v[164:167], v245 offset:18432
	ds_read_b128 v[176:179], v245 offset:19456
	ds_read_b128 v[180:183], v245 offset:20480
	ds_read_b128 v[184:187], v245 offset:21504
	ds_read_b128 v[188:191], v245 offset:22528
	ds_read_b128 v[202:205], v245 offset:23552
	s_mov_b32 m0, s27
	s_nop 0
	global_load_lds_dwordx4 v195, s[54:55]
	s_add_u32 s58, s54, s15
	s_mov_b32 m0, s28
	s_nop 0
	global_load_lds_dwordx4 v241, s[54:55]
	s_addc_u32 s59, s55, 0
	s_mov_b32 m0, s29
	s_nop 0
	global_load_lds_dwordx4 v195, s[58:59]
	s_nop 0
	s_mov_b32 m0, s30
	s_nop 0
	global_load_lds_dwordx4 v241, s[58:59]
	s_nop 0
	s_mov_b32 m0, s26
	s_nop 0
	global_load_lds_dwordx4 v0, s[56:57]
	s_nop 0
	s_mov_b32 m0, s31
	s_nop 0
	global_load_lds_dwordx4 v240, s[56:57]
	s_waitcnt vmcnt(8)
	s_waitcnt lgkmcnt(0)
	s_setprio 1
	s_barrier
	v_mfma_f32_16x16x32_bf16 v[64:67], v[108:111], v[156:159], 0
	v_mfma_f32_16x16x32_bf16 v[64:67], v[120:123], v[160:163], v[64:67]
	v_mfma_f32_16x16x32_bf16 v[60:63], v[128:131], v[156:159], 0
	v_mfma_f32_16x16x32_bf16 v[60:63], v[132:135], v[160:163], v[60:63]
	v_mfma_f32_16x16x32_bf16 v[56:59], v[136:139], v[156:159], 0
	v_mfma_f32_16x16x32_bf16 v[56:59], v[144:147], v[160:163], v[56:59]
	v_mfma_f32_16x16x32_bf16 v[52:55], v[148:151], v[156:159], 0
	v_mfma_f32_16x16x32_bf16 v[52:55], v[152:155], v[160:163], v[52:55]
	v_mfma_f32_16x16x32_bf16 v[36:39], v[148:151], v[164:167], 0
	v_mfma_f32_16x16x32_bf16 v[36:39], v[152:155], v[176:179], v[36:39]
	v_mfma_f32_16x16x32_bf16 v[40:43], v[136:139], v[164:167], 0
	v_mfma_f32_16x16x32_bf16 v[40:43], v[144:147], v[176:179], v[40:43]
	v_mfma_f32_16x16x32_bf16 v[44:47], v[128:131], v[164:167], 0
	v_mfma_f32_16x16x32_bf16 v[44:47], v[132:135], v[176:179], v[44:47]
	v_mfma_f32_16x16x32_bf16 v[48:51], v[108:111], v[164:167], 0
	v_mfma_f32_16x16x32_bf16 v[48:51], v[120:123], v[176:179], v[48:51]
	v_mfma_f32_16x16x32_bf16 v[32:35], v[108:111], v[180:183], 0
	v_mfma_f32_16x16x32_bf16 v[32:35], v[120:123], v[184:187], v[32:35]
	v_mfma_f32_16x16x32_bf16 v[28:31], v[128:131], v[180:183], 0
	v_mfma_f32_16x16x32_bf16 v[28:31], v[132:135], v[184:187], v[28:31]
	v_mfma_f32_16x16x32_bf16 v[24:27], v[136:139], v[180:183], 0
	v_mfma_f32_16x16x32_bf16 v[24:27], v[144:147], v[184:187], v[24:27]
	v_mfma_f32_16x16x32_bf16 v[20:23], v[148:151], v[180:183], 0
	v_mfma_f32_16x16x32_bf16 v[20:23], v[152:155], v[184:187], v[20:23]
	v_mfma_f32_16x16x32_bf16 v[4:7], v[148:151], v[188:191], 0
	v_mfma_f32_16x16x32_bf16 v[4:7], v[152:155], v[202:205], v[4:7]
	v_mfma_f32_16x16x32_bf16 v[8:11], v[136:139], v[188:191], 0
	v_mfma_f32_16x16x32_bf16 v[8:11], v[144:147], v[202:205], v[8:11]
	v_mfma_f32_16x16x32_bf16 v[12:15], v[128:131], v[188:191], 0
	v_mfma_f32_16x16x32_bf16 v[12:15], v[132:135], v[202:205], v[12:15]
	v_mfma_f32_16x16x32_bf16 v[16:19], v[108:111], v[188:191], 0
	v_mfma_f32_16x16x32_bf16 v[16:19], v[120:123], v[202:205], v[16:19]
	s_barrier
; #define PG8_STAGE(bufoff, gbase, voff) do { _Pragma("unroll") for (int _i = 0; _i < 2; ++_i) { \
;         const unsigned _m0 = ldsb + (unsigned)((bufoff) + _i * 8192); const char* _gb = (const char*)(gbase); \
;         asm volatile("s_mov_b32 m0, %0\n\ts_nop 0\n\tglobal_load_lds_dwordx4 %1, %2" :: "s"(_m0), "v"((voff)[_i]), "s"(_gb) : "m0", "memory"); } } while (0)
; #define PG8_LDA(dst, b, h) do { _Pragma("unroll") for (int m = 0; m < 4; ++m) _Pragma("unroll") for (int k = 0; k < 2; ++k) dst[m][k] = *(const LAS bf16x8*)(lds + PG8_SA(b, h) + aoff + m * 2048 + k * 1024); } while (0)
; #define PG8_LDB(dst, b, h) do { _Pragma("unroll") for (int n = 0; n < 2; ++n) _Pragma("unroll") for (int k = 0; k < 2; ++k) dst[n][k] = *(const LAS bf16x8*)(lds + PG8_SB(b, h) + boff + n * 2048 + k * 1024); } while (0)
; #define PG8_MMA(ai, bj, At, Bt) do { __builtin_amdgcn_s_setprio(1); _Pragma("unroll") for (int m = 0; m < 4; ++m) _Pragma("unroll") for (int n = 0; n < 2; ++n) _Pragma("unroll") for (int k = 0; k < 2; ++k) \
;         acc[ai][bj][m][n] = __builtin_amdgcn_mfma_f32_16x16x32_bf16(Bt[n][k], At[m][k], acc[ai][bj][m][n], 0, 0, 0); __builtin_amdgcn_s_setprio(0); } while (0)
; #define PG8_WAIT_V(n) asm volatile("s_waitcnt vmcnt(" #n ")" ::: "memory")
; #define PG8_WAIT_L(n) asm volatile("s_waitcnt lgkmcnt(" #n ")" ::: "memory")
; #define PG8_BAR __builtin_amdgcn_s_barrier()
; #define PG8_SCHED __builtin_amdgcn_sched_barrier(0)
; template <class Epi, bool ALIGN_EPI>
; __device__ __forceinline__ void gemm_phase(LAS unsigned char* lds, const Gemm g, const StaticOrder& S, const Epi& E) {
;     ...
;             PG8_LDB(B0, 1, 0); PG8_LDB(B1, 1, 1); PG8_SCHED; PG8_LDA(At, 1, 0); PG8_STAGE(PG8_SA(0, 1), a2 + hstepA, voffA);
;             PG8_WAIT_V(8); PG8_WAIT_L(0); PG8_BAR; PG8_MMA(0, 0, At, B0); PG8_MMA(0, 1, At, B1); PG8_BAR; PG8_SCHED;
;             PG8_LDA(At, 1, 1); PG8_STAGE(PG8_SB(1, 0), b3, voffB); PG8_STAGE(PG8_SB(1, 1), b3 + hstepB, voffB); PG8_STAGE(PG8_SA(1, 0), a3, voffA);
;             PG8_WAIT_V(8); PG8_WAIT_L(0); PG8_BAR; PG8_MMA(1, 0, At, B0); PG8_MMA(1, 1, At, B1); PG8_BAR; PG8_SCHED;
	s_setprio 0
	v_add_u32_e32 v132, 0x18000, v244
	v_add_u32_e32 v152, 0x1c000, v244
	ds_read_b128 v[108:111], v132
	ds_read_b128 v[120:123], v132 offset:1024
	ds_read_b128 v[128:131], v132 offset:2048
	ds_read_b128 v[132:135], v132 offset:3072
	ds_read_b128 v[136:139], v152
	ds_read_b128 v[144:147], v152 offset:1024
	ds_read_b128 v[148:151], v152 offset:2048
	ds_read_b128 v[152:155], v152 offset:3072
	ds_read_b128 v[156:159], v245 offset:32768
	ds_read_b128 v[160:163], v245 offset:33792
	ds_read_b128 v[164:167], v245 offset:34816
	ds_read_b128 v[176:179], v245 offset:35840
	ds_read_b128 v[180:183], v245 offset:36864
	ds_read_b128 v[184:187], v245 offset:37888
	ds_read_b128 v[188:191], v245 offset:38912
	ds_read_b128 v[202:205], v245 offset:39936
	s_add_u32 s56, s56, s15
	s_addc_u32 s57, s57, 0
	s_mov_b32 m0, s41
	s_nop 0
	global_load_lds_dwordx4 v0, s[56:57]
	s_nop 0
	s_mov_b32 m0, s42
	s_nop 0
	global_load_lds_dwordx4 v240, s[56:57]
	s_waitcnt vmcnt(8)
	s_waitcnt lgkmcnt(0)
	s_setprio 1
	s_barrier
	v_mfma_f32_16x16x32_bf16 v[172:175], v[108:111], v[156:159], v[172:175]
	v_mfma_f32_16x16x32_bf16 v[172:175], v[120:123], v[160:163], v[172:175]
	v_mfma_f32_16x16x32_bf16 v[168:171], v[128:131], v[156:159], v[168:171]
	v_mfma_f32_16x16x32_bf16 v[168:171], v[132:135], v[160:163], v[168:171]
	v_mfma_f32_16x16x32_bf16 v[140:143], v[136:139], v[156:159], v[140:143]
	v_mfma_f32_16x16x32_bf16 v[140:143], v[144:147], v[160:163], v[140:143]
	v_mfma_f32_16x16x32_bf16 v[124:127], v[148:151], v[156:159], v[124:127]
	v_mfma_f32_16x16x32_bf16 v[124:127], v[152:155], v[160:163], v[124:127]
	v_mfma_f32_16x16x32_bf16 v[100:103], v[148:151], v[164:167], v[100:103]
	v_mfma_f32_16x16x32_bf16 v[100:103], v[152:155], v[176:179], v[100:103]
	v_mfma_f32_16x16x32_bf16 v[104:107], v[136:139], v[164:167], v[104:107]
	v_mfma_f32_16x16x32_bf16 v[104:107], v[144:147], v[176:179], v[104:107]
	v_mfma_f32_16x16x32_bf16 v[112:115], v[128:131], v[164:167], v[112:115]
	v_mfma_f32_16x16x32_bf16 v[112:115], v[132:135], v[176:179], v[112:115]
	v_mfma_f32_16x16x32_bf16 v[116:119], v[108:111], v[164:167], v[116:119]
	v_mfma_f32_16x16x32_bf16 v[116:119], v[120:123], v[176:179], v[116:119]
	v_mfma_f32_16x16x32_bf16 v[96:99], v[108:111], v[180:183], v[96:99]
	v_mfma_f32_16x16x32_bf16 v[96:99], v[120:123], v[184:187], v[96:99]
	v_mfma_f32_16x16x32_bf16 v[92:95], v[128:131], v[180:183], v[92:95]
	v_mfma_f32_16x16x32_bf16 v[92:95], v[132:135], v[184:187], v[92:95]
	v_mfma_f32_16x16x32_bf16 v[88:91], v[136:139], v[180:183], v[88:91]
	v_mfma_f32_16x16x32_bf16 v[88:91], v[144:147], v[184:187], v[88:91]
	v_mfma_f32_16x16x32_bf16 v[84:87], v[148:151], v[180:183], v[84:87]
	v_mfma_f32_16x16x32_bf16 v[84:87], v[152:155], v[184:187], v[84:87]
	v_mfma_f32_16x16x32_bf16 v[68:71], v[148:151], v[188:191], v[68:71]
	v_mfma_f32_16x16x32_bf16 v[68:71], v[152:155], v[202:205], v[68:71]
	v_mfma_f32_16x16x32_bf16 v[72:75], v[136:139], v[188:191], v[72:75]
	v_mfma_f32_16x16x32_bf16 v[72:75], v[144:147], v[202:205], v[72:75]
	v_mfma_f32_16x16x32_bf16 v[76:79], v[128:131], v[188:191], v[76:79]
	v_mfma_f32_16x16x32_bf16 v[76:79], v[132:135], v[202:205], v[76:79]
	v_mfma_f32_16x16x32_bf16 v[80:83], v[108:111], v[188:191], v[80:83]
	v_mfma_f32_16x16x32_bf16 v[80:83], v[120:123], v[202:205], v[80:83]
	s_barrier
	s_setprio 0
	ds_read_b128 v[156:159], v245 offset:49152
	ds_read_b128 v[160:163], v245 offset:50176
	ds_read_b128 v[164:167], v245 offset:51200
	ds_read_b128 v[176:179], v245 offset:52224
	ds_read_b128 v[180:183], v245 offset:53248
	ds_read_b128 v[184:187], v245 offset:54272
	ds_read_b128 v[188:191], v245 offset:55296
	ds_read_b128 v[202:205], v245 offset:56320
	s_add_u32 s54, s54, 0x80
	s_addc_u32 s55, s55, 0
	s_mov_b32 m0, s46
	s_nop 0
	global_load_lds_dwordx4 v195, s[54:55]
	s_nop 0
	s_mov_b32 m0, s50
	s_nop 0
	global_load_lds_dwordx4 v241, s[54:55]
	s_add_u32 s54, s58, 0x80
	s_addc_u32 s55, s59, 0
	s_mov_b32 m0, s61
	s_nop 0
	global_load_lds_dwordx4 v195, s[54:55]
	s_nop 0
	s_mov_b32 m0, s65
	s_nop 0
	global_load_lds_dwordx4 v241, s[54:55]
	s_nop 0
	s_mov_b32 m0, s53
	s_nop 0
	global_load_lds_dwordx4 v0, s[48:49]
	s_nop 0
	s_mov_b32 m0, s60
	s_nop 0
	global_load_lds_dwordx4 v240, s[48:49]
	s_waitcnt vmcnt(8)
	s_waitcnt lgkmcnt(0)
	s_setprio 1
	s_barrier
	v_mfma_f32_16x16x32_bf16 v[64:67], v[108:111], v[156:159], v[64:67]
	v_mfma_f32_16x16x32_bf16 v[64:67], v[120:123], v[160:163], v[64:67]
	v_mfma_f32_16x16x32_bf16 v[60:63], v[128:131], v[156:159], v[60:63]
	v_mfma_f32_16x16x32_bf16 v[60:63], v[132:135], v[160:163], v[60:63]
	v_mfma_f32_16x16x32_bf16 v[56:59], v[136:139], v[156:159], v[56:59]
	v_mfma_f32_16x16x32_bf16 v[56:59], v[144:147], v[160:163], v[56:59]
	v_mfma_f32_16x16x32_bf16 v[52:55], v[148:151], v[156:159], v[52:55]
	v_mfma_f32_16x16x32_bf16 v[52:55], v[152:155], v[160:163], v[52:55]
	v_mfma_f32_16x16x32_bf16 v[36:39], v[148:151], v[164:167], v[36:39]
	v_mfma_f32_16x16x32_bf16 v[36:39], v[152:155], v[176:179], v[36:39]
	v_mfma_f32_16x16x32_bf16 v[40:43], v[136:139], v[164:167], v[40:43]
	v_mfma_f32_16x16x32_bf16 v[40:43], v[144:147], v[176:179], v[40:43]
	v_mfma_f32_16x16x32_bf16 v[44:47], v[128:131], v[164:167], v[44:47]
	v_mfma_f32_16x16x32_bf16 v[44:47], v[132:135], v[176:179], v[44:47]
	v_mfma_f32_16x16x32_bf16 v[48:51], v[108:111], v[164:167], v[48:51]
	v_mfma_f32_16x16x32_bf16 v[48:51], v[120:123], v[176:179], v[48:51]
	v_mfma_f32_16x16x32_bf16 v[32:35], v[108:111], v[180:183], v[32:35]
	v_mfma_f32_16x16x32_bf16 v[32:35], v[120:123], v[184:187], v[32:35]
	v_mfma_f32_16x16x32_bf16 v[28:31], v[128:131], v[180:183], v[28:31]
	v_mfma_f32_16x16x32_bf16 v[28:31], v[132:135], v[184:187], v[28:31]
	v_mfma_f32_16x16x32_bf16 v[24:27], v[136:139], v[180:183], v[24:27]
	v_mfma_f32_16x16x32_bf16 v[24:27], v[144:147], v[184:187], v[24:27]
	v_mfma_f32_16x16x32_bf16 v[20:23], v[148:151], v[180:183], v[20:23]
	v_mfma_f32_16x16x32_bf16 v[20:23], v[152:155], v[184:187], v[20:23]
	v_mfma_f32_16x16x32_bf16 v[4:7], v[148:151], v[188:191], v[4:7]
	v_mfma_f32_16x16x32_bf16 v[4:7], v[152:155], v[202:205], v[4:7]
	v_mfma_f32_16x16x32_bf16 v[8:11], v[136:139], v[188:191], v[8:11]
	v_mfma_f32_16x16x32_bf16 v[8:11], v[144:147], v[202:205], v[8:11]
	v_mfma_f32_16x16x32_bf16 v[12:15], v[128:131], v[188:191], v[12:15]
	v_mfma_f32_16x16x32_bf16 v[12:15], v[132:135], v[202:205], v[12:15]
	v_mfma_f32_16x16x32_bf16 v[16:19], v[108:111], v[188:191], v[16:19]
	v_mfma_f32_16x16x32_bf16 v[16:19], v[120:123], v[202:205], v[16:19]
	s_barrier
	s_setprio 0
	s_add_u32 s4, s4, 0x100
	s_addc_u32 s5, s5, 0
	s_add_u32 s37, s37, 0x100
	s_addc_u32 s44, s44, 0
	s_cmp_ge_u32 s51, s43
	s_mov_b32 s45, s51
; #define PG8_STAGE(bufoff, gbase, voff) do { _Pragma("unroll") for (int _i = 0; _i < 2; ++_i) { \
;         const unsigned _m0 = ldsb + (unsigned)((bufoff) + _i * 8192); const char* _gb = (const char*)(gbase); \
;         asm volatile("s_mov_b32 m0, %0\n\ts_nop 0\n\tglobal_load_lds_dwordx4 %1, %2" :: "s"(_m0), "v"((voff)[_i]), "s"(_gb) : "m0", "memory"); } } while (0)
; #define PG8_LDA(dst, b, h) do { _Pragma("unroll") for (int m = 0; m < 4; ++m) _Pragma("unroll") for (int k = 0; k < 2; ++k) dst[m][k] = *(const LAS bf16x8*)(lds + PG8_SA(b, h) + aoff + m * 2048 + k * 1024); } while (0)
; #define PG8_LDB(dst, b, h) do { _Pragma("unroll") for (int n = 0; n < 2; ++n) _Pragma("unroll") for (int k = 0; k < 2; ++k) dst[n][k] = *(const LAS bf16x8*)(lds + PG8_SB(b, h) + boff + n * 2048 + k * 1024); } while (0)
; #define PG8_MMA(ai, bj, At, Bt) do { __builtin_amdgcn_s_setprio(1); _Pragma("unroll") for (int m = 0; m < 4; ++m) _Pragma("unroll") for (int n = 0; n < 2; ++n) _Pragma("unroll") for (int k = 0; k < 2; ++k) \
;         acc[ai][bj][m][n] = __builtin_amdgcn_mfma_f32_16x16x32_bf16(Bt[n][k], At[m][k], acc[ai][bj][m][n], 0, 0, 0); __builtin_amdgcn_s_setprio(0); } while (0)
; #define PG8_WAIT_V(n) asm volatile("s_waitcnt vmcnt(" #n ")" ::: "memory")
; #define PG8_WAIT_L(n) asm volatile("s_waitcnt lgkmcnt(" #n ")" ::: "memory")
; template <class Epi, bool ALIGN_EPI>
; __device__ __forceinline__ void gemm_phase(LAS unsigned char* lds, const Gemm g, const StaticOrder& S, const Epi& E) {
;     ...
;         for (int t = 0; t < nt; t += 2) {
;             const bool last = (t == nt - 2);
;             const char* a1 = cA + (size_t)(t + 1) * kstep;
;             const char* a2 = last ? nA : cA + (size_t)(t + 2) * kstep; const char* b2 = last ? nB : cB + (size_t)(t + 2) * kstep;
;             const char* a3 = a2 + kstep; const char* b3 = b2 + kstep;
;             PG8_LDB(B0, 0, 0); PG8_LDB(B1, 0, 1); PG8_SCHED; PG8_LDA(At, 0, 0); PG8_STAGE(PG8_SA(1, 1), a1 + hstepA, voffA);
;             PG8_WAIT_V(8); PG8_WAIT_L(0); PG8_BAR; PG8_MMA(0, 0, At, B0); PG8_MMA(0, 1, At, B1); PG8_BAR; PG8_SCHED;
;             PG8_LDA(At, 0, 1); PG8_STAGE(PG8_SB(0, 0), b2, voffB); PG8_STAGE(PG8_SB(0, 1), b2 + hstepB, voffB); PG8_STAGE(PG8_SA(0, 0), a2, voffA);
;             PG8_WAIT_V(8); PG8_WAIT_L(0); PG8_BAR; PG8_MMA(1, 0, At, B0); PG8_MMA(1, 1, At, B1); PG8_BAR; PG8_SCHED;
.LBB0_151:
	v_add_u32_e32 v132, 0x10000, v244
	v_add_u32_e32 v152, 0x14000, v244
	ds_read_b128 v[108:111], v132
	ds_read_b128 v[120:123], v132 offset:1024
	ds_read_b128 v[128:131], v132 offset:2048
	ds_read_b128 v[132:135], v132 offset:3072
	ds_read_b128 v[136:139], v152
	ds_read_b128 v[144:147], v152 offset:1024
	ds_read_b128 v[148:151], v152 offset:2048
	ds_read_b128 v[152:155], v152 offset:3072
	s_add_i32 s51, s45, 2
	s_cmp_eq_u32 s67, s45
	s_cselect_b32 s56, s0, s37
	s_cselect_b32 s57, s1, s44
	s_cselect_b32 s54, s94, s4
	s_cselect_b32 s55, s95, s5
	s_add_u32 s48, s56, 0x80
	s_addc_u32 s49, s57, 0
	ds_read_b128 v[156:159], v245
	ds_read_b128 v[160:163], v245 offset:1024
	ds_read_b128 v[164:167], v245 offset:2048
	ds_read_b128 v[176:179], v245 offset:3072
	ds_read_b128 v[180:183], v245 offset:4096
	ds_read_b128 v[184:187], v245 offset:5120
	ds_read_b128 v[188:191], v245 offset:6144
	ds_read_b128 v[202:205], v245 offset:7168
	s_add_u32 s45, s37, s15
	s_addc_u32 s59, s44, 0
	s_add_u32 s58, s45, 0xffffff80
	s_addc_u32 s59, s59, -1
	s_mov_b32 m0, s68
	s_nop 0
	global_load_lds_dwordx4 v0, s[58:59]
	s_nop 0
	s_mov_b32 m0, s85
	s_nop 0
	global_load_lds_dwordx4 v240, s[58:59]
	s_waitcnt vmcnt(8)
	s_waitcnt lgkmcnt(0)
	s_setprio 1
	s_barrier
	v_mfma_f32_16x16x32_bf16 v[172:175], v[108:111], v[156:159], v[172:175]
	v_mfma_f32_16x16x32_bf16 v[172:175], v[120:123], v[160:163], v[172:175]
	v_mfma_f32_16x16x32_bf16 v[168:171], v[128:131], v[156:159], v[168:171]
	v_mfma_f32_16x16x32_bf16 v[168:171], v[132:135], v[160:163], v[168:171]
	v_mfma_f32_16x16x32_bf16 v[140:143], v[136:139], v[156:159], v[140:143]
	v_mfma_f32_16x16x32_bf16 v[140:143], v[144:147], v[160:163], v[140:143]
	v_mfma_f32_16x16x32_bf16 v[124:127], v[148:151], v[156:159], v[124:127]
	v_mfma_f32_16x16x32_bf16 v[124:127], v[152:155], v[160:163], v[124:127]
	v_mfma_f32_16x16x32_bf16 v[100:103], v[148:151], v[164:167], v[100:103]
	v_mfma_f32_16x16x32_bf16 v[100:103], v[152:155], v[176:179], v[100:103]
	v_mfma_f32_16x16x32_bf16 v[104:107], v[136:139], v[164:167], v[104:107]
	v_mfma_f32_16x16x32_bf16 v[104:107], v[144:147], v[176:179], v[104:107]
	v_mfma_f32_16x16x32_bf16 v[112:115], v[128:131], v[164:167], v[112:115]
	v_mfma_f32_16x16x32_bf16 v[112:115], v[132:135], v[176:179], v[112:115]
	v_mfma_f32_16x16x32_bf16 v[116:119], v[108:111], v[164:167], v[116:119]
	v_mfma_f32_16x16x32_bf16 v[116:119], v[120:123], v[176:179], v[116:119]
	v_mfma_f32_16x16x32_bf16 v[96:99], v[108:111], v[180:183], v[96:99]
	v_mfma_f32_16x16x32_bf16 v[96:99], v[120:123], v[184:187], v[96:99]
	v_mfma_f32_16x16x32_bf16 v[92:95], v[128:131], v[180:183], v[92:95]
	v_mfma_f32_16x16x32_bf16 v[92:95], v[132:135], v[184:187], v[92:95]
	v_mfma_f32_16x16x32_bf16 v[88:91], v[136:139], v[180:183], v[88:91]
	v_mfma_f32_16x16x32_bf16 v[88:91], v[144:147], v[184:187], v[88:91]
	v_mfma_f32_16x16x32_bf16 v[84:87], v[148:151], v[180:183], v[84:87]
	v_mfma_f32_16x16x32_bf16 v[84:87], v[152:155], v[184:187], v[84:87]
	v_mfma_f32_16x16x32_bf16 v[68:71], v[148:151], v[188:191], v[68:71]
	v_mfma_f32_16x16x32_bf16 v[68:71], v[152:155], v[202:205], v[68:71]
	v_mfma_f32_16x16x32_bf16 v[72:75], v[136:139], v[188:191], v[72:75]
	v_mfma_f32_16x16x32_bf16 v[72:75], v[144:147], v[202:205], v[72:75]
	v_mfma_f32_16x16x32_bf16 v[76:79], v[128:131], v[188:191], v[76:79]
	v_mfma_f32_16x16x32_bf16 v[76:79], v[132:135], v[202:205], v[76:79]
	v_mfma_f32_16x16x32_bf16 v[80:83], v[108:111], v[188:191], v[80:83]
	v_mfma_f32_16x16x32_bf16 v[80:83], v[120:123], v[202:205], v[80:83]
	s_barrier
	s_setprio 0
	ds_read_b128 v[156:159], v245 offset:16384
	ds_read_b128 v[160:163], v245 offset:17408
	ds_read_b128 v[164:167], v245 offset:18432
	ds_read_b128 v[176:179], v245 offset:19456
	ds_read_b128 v[180:183], v245 offset:20480
	ds_read_b128 v[184:187], v245 offset:21504
	ds_read_b128 v[188:191], v245 offset:22528
	ds_read_b128 v[202:205], v245 offset:23552
	s_mov_b32 m0, s27
	s_nop 0
	global_load_lds_dwordx4 v195, s[54:55]
	s_add_u32 s58, s54, s15
	s_mov_b32 m0, s28
	s_nop 0
	global_load_lds_dwordx4 v241, s[54:55]
	s_addc_u32 s59, s55, 0
	s_mov_b32 m0, s29
	s_nop 0
	global_load_lds_dwordx4 v195, s[58:59]
	s_nop 0
	s_mov_b32 m0, s30
	s_nop 0
	global_load_lds_dwordx4 v241, s[58:59]
	s_nop 0
	s_mov_b32 m0, s26
	s_nop 0
	global_load_lds_dwordx4 v0, s[56:57]
	s_nop 0
	s_mov_b32 m0, s31
	s_nop 0
	global_load_lds_dwordx4 v240, s[56:57]
	s_waitcnt vmcnt(8)
	s_waitcnt lgkmcnt(0)
	s_setprio 1
	s_barrier
	v_mfma_f32_16x16x32_bf16 v[64:67], v[108:111], v[156:159], v[64:67]
	v_mfma_f32_16x16x32_bf16 v[64:67], v[120:123], v[160:163], v[64:67]
	v_mfma_f32_16x16x32_bf16 v[60:63], v[128:131], v[156:159], v[60:63]
	v_mfma_f32_16x16x32_bf16 v[60:63], v[132:135], v[160:163], v[60:63]
	v_mfma_f32_16x16x32_bf16 v[56:59], v[136:139], v[156:159], v[56:59]
	v_mfma_f32_16x16x32_bf16 v[56:59], v[144:147], v[160:163], v[56:59]
	v_mfma_f32_16x16x32_bf16 v[52:55], v[148:151], v[156:159], v[52:55]
	v_mfma_f32_16x16x32_bf16 v[52:55], v[152:155], v[160:163], v[52:55]
	v_mfma_f32_16x16x32_bf16 v[36:39], v[148:151], v[164:167], v[36:39]
	v_mfma_f32_16x16x32_bf16 v[36:39], v[152:155], v[176:179], v[36:39]
	v_mfma_f32_16x16x32_bf16 v[40:43], v[136:139], v[164:167], v[40:43]
	v_mfma_f32_16x16x32_bf16 v[40:43], v[144:147], v[176:179], v[40:43]
	v_mfma_f32_16x16x32_bf16 v[44:47], v[128:131], v[164:167], v[44:47]
	v_mfma_f32_16x16x32_bf16 v[44:47], v[132:135], v[176:179], v[44:47]
	v_mfma_f32_16x16x32_bf16 v[48:51], v[108:111], v[164:167], v[48:51]
	v_mfma_f32_16x16x32_bf16 v[48:51], v[120:123], v[176:179], v[48:51]
	v_mfma_f32_16x16x32_bf16 v[32:35], v[108:111], v[180:183], v[32:35]
	v_mfma_f32_16x16x32_bf16 v[32:35], v[120:123], v[184:187], v[32:35]
	v_mfma_f32_16x16x32_bf16 v[28:31], v[128:131], v[180:183], v[28:31]
	v_mfma_f32_16x16x32_bf16 v[28:31], v[132:135], v[184:187], v[28:31]
	v_mfma_f32_16x16x32_bf16 v[24:27], v[136:139], v[180:183], v[24:27]
	v_mfma_f32_16x16x32_bf16 v[24:27], v[144:147], v[184:187], v[24:27]
	v_mfma_f32_16x16x32_bf16 v[20:23], v[148:151], v[180:183], v[20:23]
	v_mfma_f32_16x16x32_bf16 v[20:23], v[152:155], v[184:187], v[20:23]
	v_mfma_f32_16x16x32_bf16 v[4:7], v[148:151], v[188:191], v[4:7]
	v_mfma_f32_16x16x32_bf16 v[4:7], v[152:155], v[202:205], v[4:7]
	v_mfma_f32_16x16x32_bf16 v[8:11], v[136:139], v[188:191], v[8:11]
	v_mfma_f32_16x16x32_bf16 v[8:11], v[144:147], v[202:205], v[8:11]
	v_mfma_f32_16x16x32_bf16 v[12:15], v[128:131], v[188:191], v[12:15]
	v_mfma_f32_16x16x32_bf16 v[12:15], v[132:135], v[202:205], v[12:15]
	v_mfma_f32_16x16x32_bf16 v[16:19], v[108:111], v[188:191], v[16:19]
	v_mfma_f32_16x16x32_bf16 v[16:19], v[120:123], v[202:205], v[16:19]
	s_barrier
; #define PG8_STAGE(bufoff, gbase, voff) do { _Pragma("unroll") for (int _i = 0; _i < 2; ++_i) { \
;         const unsigned _m0 = ldsb + (unsigned)((bufoff) + _i * 8192); const char* _gb = (const char*)(gbase); \
;         asm volatile("s_mov_b32 m0, %0\n\ts_nop 0\n\tglobal_load_lds_dwordx4 %1, %2" :: "s"(_m0), "v"((voff)[_i]), "s"(_gb) : "m0", "memory"); } } while (0)
; #define PG8_LDA(dst, b, h) do { _Pragma("unroll") for (int m = 0; m < 4; ++m) _Pragma("unroll") for (int k = 0; k < 2; ++k) dst[m][k] = *(const LAS bf16x8*)(lds + PG8_SA(b, h) + aoff + m * 2048 + k * 1024); } while (0)
; #define PG8_LDB(dst, b, h) do { _Pragma("unroll") for (int n = 0; n < 2; ++n) _Pragma("unroll") for (int k = 0; k < 2; ++k) dst[n][k] = *(const LAS bf16x8*)(lds + PG8_SB(b, h) + boff + n * 2048 + k * 1024); } while (0)
; #define PG8_MMA(ai, bj, At, Bt) do { __builtin_amdgcn_s_setprio(1); _Pragma("unroll") for (int m = 0; m < 4; ++m) _Pragma("unroll") for (int n = 0; n < 2; ++n) _Pragma("unroll") for (int k = 0; k < 2; ++k) \
;         acc[ai][bj][m][n] = __builtin_amdgcn_mfma_f32_16x16x32_bf16(Bt[n][k], At[m][k], acc[ai][bj][m][n], 0, 0, 0); __builtin_amdgcn_s_setprio(0); } while (0)
; #define PG8_WAIT_V(n) asm volatile("s_waitcnt vmcnt(" #n ")" ::: "memory")
; #define PG8_WAIT_L(n) asm volatile("s_waitcnt lgkmcnt(" #n ")" ::: "memory")
; #define PG8_BAR __builtin_amdgcn_s_barrier()
; #define PG8_SCHED __builtin_amdgcn_sched_barrier(0)
; template <class Epi, bool ALIGN_EPI>
; __device__ __forceinline__ void gemm_phase(LAS unsigned char* lds, const Gemm g, const StaticOrder& S, const Epi& E) {
;     ...
;             PG8_LDB(B0, 1, 0); PG8_LDB(B1, 1, 1); PG8_SCHED; PG8_LDA(At, 1, 0); PG8_STAGE(PG8_SA(0, 1), a2 + hstepA, voffA);
;             PG8_WAIT_V(8); PG8_WAIT_L(0); PG8_BAR; PG8_MMA(0, 0, At, B0); PG8_MMA(0, 1, At, B1); PG8_BAR; PG8_SCHED;
;             PG8_LDA(At, 1, 1); PG8_STAGE(PG8_SB(1, 0), b3, voffB); PG8_STAGE(PG8_SB(1, 1), b3 + hstepB, voffB); PG8_STAGE(PG8_SA(1, 0), a3, voffA);
;             PG8_WAIT_V(8); PG8_WAIT_L(0); PG8_BAR; PG8_MMA(1, 0, At, B0); PG8_MMA(1, 1, At, B1); PG8_BAR; PG8_SCHED;
;         }
;         if constexpr (ALIGN_EPI) { if (wr == 0) PG8_BAR; }
	s_setprio 0
	v_add_u32_e32 v132, 0x18000, v244
	v_add_u32_e32 v152, 0x1c000, v244
	ds_read_b128 v[108:111], v132
	ds_read_b128 v[120:123], v132 offset:1024
	ds_read_b128 v[128:131], v132 offset:2048
	ds_read_b128 v[132:135], v132 offset:3072
	ds_read_b128 v[136:139], v152
	ds_read_b128 v[144:147], v152 offset:1024
	ds_read_b128 v[148:151], v152 offset:2048
	ds_read_b128 v[152:155], v152 offset:3072
	ds_read_b128 v[156:159], v245 offset:32768
	ds_read_b128 v[160:163], v245 offset:33792
	ds_read_b128 v[164:167], v245 offset:34816
	ds_read_b128 v[176:179], v245 offset:35840
	ds_read_b128 v[180:183], v245 offset:36864
	ds_read_b128 v[184:187], v245 offset:37888
	ds_read_b128 v[188:191], v245 offset:38912
	ds_read_b128 v[202:205], v245 offset:39936
	s_add_u32 s56, s56, s15
	s_addc_u32 s57, s57, 0
	s_mov_b32 m0, s41
	s_nop 0
	global_load_lds_dwordx4 v0, s[56:57]
	s_nop 0
	s_mov_b32 m0, s42
	s_nop 0
	global_load_lds_dwordx4 v240, s[56:57]
	s_waitcnt vmcnt(8)
	s_waitcnt lgkmcnt(0)
	s_setprio 1
	s_barrier
	v_mfma_f32_16x16x32_bf16 v[172:175], v[108:111], v[156:159], v[172:175]
	v_mfma_f32_16x16x32_bf16 v[172:175], v[120:123], v[160:163], v[172:175]
	v_mfma_f32_16x16x32_bf16 v[168:171], v[128:131], v[156:159], v[168:171]
	v_mfma_f32_16x16x32_bf16 v[168:171], v[132:135], v[160:163], v[168:171]
	v_mfma_f32_16x16x32_bf16 v[140:143], v[136:139], v[156:159], v[140:143]
	v_mfma_f32_16x16x32_bf16 v[140:143], v[144:147], v[160:163], v[140:143]
	v_mfma_f32_16x16x32_bf16 v[124:127], v[148:151], v[156:159], v[124:127]
	v_mfma_f32_16x16x32_bf16 v[124:127], v[152:155], v[160:163], v[124:127]
	v_mfma_f32_16x16x32_bf16 v[100:103], v[148:151], v[164:167], v[100:103]
	v_mfma_f32_16x16x32_bf16 v[100:103], v[152:155], v[176:179], v[100:103]
	v_mfma_f32_16x16x32_bf16 v[104:107], v[136:139], v[164:167], v[104:107]
	v_mfma_f32_16x16x32_bf16 v[104:107], v[144:147], v[176:179], v[104:107]
	v_mfma_f32_16x16x32_bf16 v[112:115], v[128:131], v[164:167], v[112:115]
	v_mfma_f32_16x16x32_bf16 v[112:115], v[132:135], v[176:179], v[112:115]
	v_mfma_f32_16x16x32_bf16 v[116:119], v[108:111], v[164:167], v[116:119]
	v_mfma_f32_16x16x32_bf16 v[116:119], v[120:123], v[176:179], v[116:119]
	v_mfma_f32_16x16x32_bf16 v[96:99], v[108:111], v[180:183], v[96:99]
	v_mfma_f32_16x16x32_bf16 v[96:99], v[120:123], v[184:187], v[96:99]
	v_mfma_f32_16x16x32_bf16 v[92:95], v[128:131], v[180:183], v[92:95]
	v_mfma_f32_16x16x32_bf16 v[92:95], v[132:135], v[184:187], v[92:95]
	v_mfma_f32_16x16x32_bf16 v[88:91], v[136:139], v[180:183], v[88:91]
	v_mfma_f32_16x16x32_bf16 v[88:91], v[144:147], v[184:187], v[88:91]
	v_mfma_f32_16x16x32_bf16 v[84:87], v[148:151], v[180:183], v[84:87]
	v_mfma_f32_16x16x32_bf16 v[84:87], v[152:155], v[184:187], v[84:87]
	v_mfma_f32_16x16x32_bf16 v[68:71], v[148:151], v[188:191], v[68:71]
	v_mfma_f32_16x16x32_bf16 v[68:71], v[152:155], v[202:205], v[68:71]
	v_mfma_f32_16x16x32_bf16 v[72:75], v[136:139], v[188:191], v[72:75]
	v_mfma_f32_16x16x32_bf16 v[72:75], v[144:147], v[202:205], v[72:75]
	v_mfma_f32_16x16x32_bf16 v[76:79], v[128:131], v[188:191], v[76:79]
	v_mfma_f32_16x16x32_bf16 v[76:79], v[132:135], v[202:205], v[76:79]
	v_mfma_f32_16x16x32_bf16 v[80:83], v[108:111], v[188:191], v[80:83]
	v_mfma_f32_16x16x32_bf16 v[80:83], v[120:123], v[202:205], v[80:83]
	s_barrier
	s_setprio 0
	ds_read_b128 v[156:159], v245 offset:49152
	ds_read_b128 v[160:163], v245 offset:50176
	ds_read_b128 v[164:167], v245 offset:51200
	ds_read_b128 v[176:179], v245 offset:52224
	ds_read_b128 v[180:183], v245 offset:53248
	ds_read_b128 v[184:187], v245 offset:54272
	ds_read_b128 v[188:191], v245 offset:55296
	ds_read_b128 v[202:205], v245 offset:56320
	s_add_u32 s54, s54, 0x80
	s_addc_u32 s55, s55, 0
	s_mov_b32 m0, s46
	s_nop 0
	global_load_lds_dwordx4 v195, s[54:55]
	s_nop 0
	s_mov_b32 m0, s50
	s_nop 0
	global_load_lds_dwordx4 v241, s[54:55]
	s_add_u32 s54, s58, 0x80
	s_addc_u32 s55, s59, 0
	s_mov_b32 m0, s61
	s_nop 0
	global_load_lds_dwordx4 v195, s[54:55]
	s_nop 0
	s_mov_b32 m0, s65
	s_nop 0
	global_load_lds_dwordx4 v241, s[54:55]
	s_nop 0
	s_mov_b32 m0, s53
	s_nop 0
	global_load_lds_dwordx4 v0, s[48:49]
	s_nop 0
	s_mov_b32 m0, s60
	s_nop 0
	global_load_lds_dwordx4 v240, s[48:49]
	s_waitcnt vmcnt(8)
	s_waitcnt lgkmcnt(0)
	s_setprio 1
	s_barrier
	v_mfma_f32_16x16x32_bf16 v[64:67], v[108:111], v[156:159], v[64:67]
	v_mfma_f32_16x16x32_bf16 v[64:67], v[120:123], v[160:163], v[64:67]
	v_mfma_f32_16x16x32_bf16 v[60:63], v[128:131], v[156:159], v[60:63]
	v_mfma_f32_16x16x32_bf16 v[60:63], v[132:135], v[160:163], v[60:63]
	v_mfma_f32_16x16x32_bf16 v[56:59], v[136:139], v[156:159], v[56:59]
	v_mfma_f32_16x16x32_bf16 v[56:59], v[144:147], v[160:163], v[56:59]
	v_mfma_f32_16x16x32_bf16 v[52:55], v[148:151], v[156:159], v[52:55]
	v_mfma_f32_16x16x32_bf16 v[52:55], v[152:155], v[160:163], v[52:55]
	v_mfma_f32_16x16x32_bf16 v[36:39], v[148:151], v[164:167], v[36:39]
	v_mfma_f32_16x16x32_bf16 v[36:39], v[152:155], v[176:179], v[36:39]
	v_mfma_f32_16x16x32_bf16 v[40:43], v[136:139], v[164:167], v[40:43]
	v_mfma_f32_16x16x32_bf16 v[40:43], v[144:147], v[176:179], v[40:43]
	v_mfma_f32_16x16x32_bf16 v[44:47], v[128:131], v[164:167], v[44:47]
	v_mfma_f32_16x16x32_bf16 v[44:47], v[132:135], v[176:179], v[44:47]
	v_mfma_f32_16x16x32_bf16 v[48:51], v[108:111], v[164:167], v[48:51]
	v_mfma_f32_16x16x32_bf16 v[48:51], v[120:123], v[176:179], v[48:51]
	v_mfma_f32_16x16x32_bf16 v[32:35], v[108:111], v[180:183], v[32:35]
	v_mfma_f32_16x16x32_bf16 v[32:35], v[120:123], v[184:187], v[32:35]
	v_mfma_f32_16x16x32_bf16 v[28:31], v[128:131], v[180:183], v[28:31]
	v_mfma_f32_16x16x32_bf16 v[28:31], v[132:135], v[184:187], v[28:31]
	v_mfma_f32_16x16x32_bf16 v[24:27], v[136:139], v[180:183], v[24:27]
	v_mfma_f32_16x16x32_bf16 v[24:27], v[144:147], v[184:187], v[24:27]
	v_mfma_f32_16x16x32_bf16 v[20:23], v[148:151], v[180:183], v[20:23]
	v_mfma_f32_16x16x32_bf16 v[20:23], v[152:155], v[184:187], v[20:23]
	v_mfma_f32_16x16x32_bf16 v[4:7], v[148:151], v[188:191], v[4:7]
	v_mfma_f32_16x16x32_bf16 v[4:7], v[152:155], v[202:205], v[4:7]
	v_mfma_f32_16x16x32_bf16 v[8:11], v[136:139], v[188:191], v[8:11]
	v_mfma_f32_16x16x32_bf16 v[8:11], v[144:147], v[202:205], v[8:11]
	v_mfma_f32_16x16x32_bf16 v[12:15], v[128:131], v[188:191], v[12:15]
	v_mfma_f32_16x16x32_bf16 v[12:15], v[132:135], v[202:205], v[12:15]
	v_mfma_f32_16x16x32_bf16 v[16:19], v[108:111], v[188:191], v[16:19]
	v_mfma_f32_16x16x32_bf16 v[16:19], v[120:123], v[202:205], v[16:19]
	s_barrier
	s_setprio 0
	s_add_u32 s4, s4, 0x100
	s_addc_u32 s5, s5, 0
	s_add_u32 s37, s37, 0x100
	s_addc_u32 s44, s44, 0
	s_cmp_ge_u32 s51, s43
	s_mov_b32 s45, s51
	s_cbranch_scc0 .LBB0_151
	s_and_b64 vcc, exec, s[92:93]
	s_cbranch_vccz .LBB0_154
	s_barrier

; #define PG8_STAGE(bufoff, gbase, voff) do { _Pragma("unroll") for (int _i = 0; _i < 2; ++_i) { \
;         const unsigned _m0 = ldsb + (unsigned)((bufoff) + _i * 8192); const char* _gb = (const char*)(gbase); \
;         asm volatile("s_mov_b32 m0, %0\n\ts_nop 0\n\tglobal_load_lds_dwordx4 %1, %2" :: "s"(_m0), "v"((voff)[_i]), "s"(_gb) : "m0", "memory"); } } while (0)
; #define PG8_LDA(dst, b, h) do { _Pragma("unroll") for (int m = 0; m < 4; ++m) _Pragma("unroll") for (int k = 0; k < 2; ++k) dst[m][k] = *(const LAS bf16x8*)(lds + PG8_SA(b, h) + aoff + m * 2048 + k * 1024); } while (0)
; #define PG8_LDB(dst, b, h) do { _Pragma("unroll") for (int n = 0; n < 2; ++n) _Pragma("unroll") for (int k = 0; k < 2; ++k) dst[n][k] = *(const LAS bf16x8*)(lds + PG8_SB(b, h) + boff + n * 2048 + k * 1024); } while (0)
; #define PG8_WAIT_V(n) asm volatile("s_waitcnt vmcnt(" #n ")" ::: "memory")
; #define PG8_WAIT_L(n) asm volatile("s_waitcnt lgkmcnt(" #n ")" ::: "memory")
; #define PG8_BAR __builtin_amdgcn_s_barrier()
; #define PG8_SCHED __builtin_amdgcn_sched_barrier(0)
; template <class Epi, bool ALIGN_EPI>
; __device__ __forceinline__ void gemm_phase(LAS unsigned char* lds, const Gemm g, const StaticOrder& S, const Epi& E) {
;     ...
;         const char* nA = has_next ? (const char*)g.A + (size_t)nxt.pm * tstepA + (size_t)nxt.pn * g.a_pn_off * 2 + (size_t)(nxt.pm >> 4) * g.a_adj : cA; const char* nB = has_next ? (const char*)g.Bt + (size_t)nxt.pn * tstepB : cB;
;         for (int t = 0; t < nt; t += 2) {
;             const bool last = (t == nt - 2);
;             const char* a1 = cA + (size_t)(t + 1) * kstep;
;             const char* a2 = last ? nA : cA + (size_t)(t + 2) * kstep; const char* b2 = last ? nB : cB + (size_t)(t + 2) * kstep;
;             const char* a3 = a2 + kstep; const char* b3 = b2 + kstep;
;             PG8_LDB(B0, 0, 0); PG8_LDB(B1, 0, 1); PG8_SCHED; PG8_LDA(At, 0, 0); PG8_STAGE(PG8_SA(1, 1), a1 + hstepA, voffA);
;             PG8_WAIT_V(8); PG8_WAIT_L(0); PG8_BAR; PG8_MMA(0, 0, At, B0); PG8_MMA(0, 1, At, B1); PG8_BAR; PG8_SCHED;
;             PG8_LDA(At, 0, 1); PG8_STAGE(PG8_SB(0, 0), b2, voffB); PG8_STAGE(PG8_SB(0, 1), b2 + hstepB, voffB); PG8_STAGE(PG8_SA(0, 0), a2, voffA);
;             PG8_WAIT_V(8); PG8_WAIT_L(0); PG8_BAR; PG8_MMA(1, 0, At, B0); PG8_MMA(1, 1, At, B1); PG8_BAR; PG8_SCHED;
.LBB0_200:
	s_add_u32 s4, s48, 0x100
	s_addc_u32 s5, s49, 0
	s_add_u32 s15, s54, 0x100
	s_addc_u32 s42, s55, 0
	s_mov_b32 s43, 0
	s_add_i32 s44, s43, 2
	s_cmp_eq_u32 s68, s43
	s_cselect_b32 s56, s0, s15
	s_cselect_b32 s57, s1, s42
	s_cselect_b32 s54, s94, s4
	s_cselect_b32 s55, s95, s5
	s_add_u32 s48, s56, 0x80
	s_addc_u32 s49, s57, 0
	s_add_u32 s43, s15, s38
	s_addc_u32 s45, s42, 0
	s_add_u32 s58, s43, 0xffffff80
	s_addc_u32 s59, s45, -1
	s_mov_b32 m0, s37
	s_nop 0
	global_load_lds_dwordx4 v0, s[58:59]
	s_nop 0
	s_mov_b32 m0, s41
	s_nop 0
	global_load_lds_dwordx4 v206, s[58:59]
	s_waitcnt vmcnt(8)
	s_waitcnt lgkmcnt(0)
	s_setprio 1
	s_barrier
	v_mfma_f32_16x16x32_bf16 v[126:129], v[130:133], v[162:165], 0
	v_mfma_f32_16x16x32_bf16 v[126:129], v[134:137], v[166:169], v[126:129]
	v_mfma_f32_16x16x32_bf16 v[122:125], v[138:141], v[162:165], 0
	v_mfma_f32_16x16x32_bf16 v[122:125], v[142:145], v[166:169], v[122:125]
	v_mfma_f32_16x16x32_bf16 v[118:121], v[146:149], v[162:165], 0
	v_mfma_f32_16x16x32_bf16 v[118:121], v[150:153], v[166:169], v[118:121]
	v_mfma_f32_16x16x32_bf16 v[114:117], v[154:157], v[162:165], 0
	v_mfma_f32_16x16x32_bf16 v[114:117], v[158:161], v[166:169], v[114:117]
	v_mfma_f32_16x16x32_bf16 v[98:101], v[154:157], v[170:173], 0
	v_mfma_f32_16x16x32_bf16 v[98:101], v[158:161], v[174:177], v[98:101]
	v_mfma_f32_16x16x32_bf16 v[102:105], v[146:149], v[170:173], 0
	v_mfma_f32_16x16x32_bf16 v[102:105], v[150:153], v[174:177], v[102:105]
	v_mfma_f32_16x16x32_bf16 v[106:109], v[138:141], v[170:173], 0
	v_mfma_f32_16x16x32_bf16 v[106:109], v[142:145], v[174:177], v[106:109]
	v_mfma_f32_16x16x32_bf16 v[110:113], v[130:133], v[170:173], 0
	v_mfma_f32_16x16x32_bf16 v[110:113], v[134:137], v[174:177], v[110:113]
	v_mfma_f32_16x16x32_bf16 v[94:97], v[130:133], v[178:181], 0
	v_mfma_f32_16x16x32_bf16 v[94:97], v[134:137], v[182:185], v[94:97]
	v_mfma_f32_16x16x32_bf16 v[90:93], v[138:141], v[178:181], 0
	v_mfma_f32_16x16x32_bf16 v[90:93], v[142:145], v[182:185], v[90:93]
	v_mfma_f32_16x16x32_bf16 v[86:89], v[146:149], v[178:181], 0
	v_mfma_f32_16x16x32_bf16 v[86:89], v[150:153], v[182:185], v[86:89]
	v_mfma_f32_16x16x32_bf16 v[82:85], v[154:157], v[178:181], 0
	v_mfma_f32_16x16x32_bf16 v[82:85], v[158:161], v[182:185], v[82:85]
	v_mfma_f32_16x16x32_bf16 v[66:69], v[154:157], v[186:189], 0
	v_mfma_f32_16x16x32_bf16 v[66:69], v[158:161], v[190:193], v[66:69]
	v_mfma_f32_16x16x32_bf16 v[70:73], v[146:149], v[186:189], 0
	v_mfma_f32_16x16x32_bf16 v[70:73], v[150:153], v[190:193], v[70:73]
	v_mfma_f32_16x16x32_bf16 v[74:77], v[138:141], v[186:189], 0
	v_mfma_f32_16x16x32_bf16 v[74:77], v[142:145], v[190:193], v[74:77]
	v_mfma_f32_16x16x32_bf16 v[78:81], v[130:133], v[186:189], 0
	v_mfma_f32_16x16x32_bf16 v[78:81], v[134:137], v[190:193], v[78:81]
	s_barrier
	s_setprio 0
	ds_read_b128 v[162:165], v246 offset:16384
	ds_read_b128 v[166:169], v246 offset:17408
	ds_read_b128 v[170:173], v246 offset:18432
	ds_read_b128 v[174:177], v246 offset:19456
	ds_read_b128 v[178:181], v246 offset:20480
	ds_read_b128 v[182:185], v246 offset:21504
	ds_read_b128 v[186:189], v246 offset:22528
	ds_read_b128 v[190:193], v246 offset:23552
	s_mov_b32 m0, s46
	s_nop 0
	global_load_lds_dwordx4 v195, s[54:55]
	s_add_u32 s58, s54, s38
	s_mov_b32 m0, s26
	s_nop 0
	global_load_lds_dwordx4 v207, s[54:55]
	s_addc_u32 s59, s55, 0
	s_mov_b32 m0, s27
	s_nop 0
	global_load_lds_dwordx4 v195, s[58:59]
	s_nop 0
	s_mov_b32 m0, s30
	s_nop 0
	global_load_lds_dwordx4 v207, s[58:59]
	s_nop 0
	s_mov_b32 m0, s29
	s_nop 0
	global_load_lds_dwordx4 v0, s[56:57]
	s_nop 0
	s_mov_b32 m0, s17
	s_nop 0
	global_load_lds_dwordx4 v206, s[56:57]
	s_waitcnt vmcnt(8)
	s_waitcnt lgkmcnt(0)
	s_setprio 1
	s_barrier
	v_mfma_f32_16x16x32_bf16 v[62:65], v[130:133], v[162:165], 0
	v_mfma_f32_16x16x32_bf16 v[62:65], v[134:137], v[166:169], v[62:65]
	v_mfma_f32_16x16x32_bf16 v[58:61], v[138:141], v[162:165], 0
	v_mfma_f32_16x16x32_bf16 v[58:61], v[142:145], v[166:169], v[58:61]
	v_mfma_f32_16x16x32_bf16 v[54:57], v[146:149], v[162:165], 0
	v_mfma_f32_16x16x32_bf16 v[54:57], v[150:153], v[166:169], v[54:57]
	v_mfma_f32_16x16x32_bf16 v[50:53], v[154:157], v[162:165], 0
	v_mfma_f32_16x16x32_bf16 v[50:53], v[158:161], v[166:169], v[50:53]
	v_mfma_f32_16x16x32_bf16 v[34:37], v[154:157], v[170:173], 0
	v_mfma_f32_16x16x32_bf16 v[34:37], v[158:161], v[174:177], v[34:37]
	v_mfma_f32_16x16x32_bf16 v[38:41], v[146:149], v[170:173], 0
	v_mfma_f32_16x16x32_bf16 v[38:41], v[150:153], v[174:177], v[38:41]
	v_mfma_f32_16x16x32_bf16 v[42:45], v[138:141], v[170:173], 0
	v_mfma_f32_16x16x32_bf16 v[42:45], v[142:145], v[174:177], v[42:45]
	v_mfma_f32_16x16x32_bf16 v[46:49], v[130:133], v[170:173], 0
	v_mfma_f32_16x16x32_bf16 v[46:49], v[134:137], v[174:177], v[46:49]
	v_mfma_f32_16x16x32_bf16 v[30:33], v[130:133], v[178:181], 0
	v_mfma_f32_16x16x32_bf16 v[30:33], v[134:137], v[182:185], v[30:33]
	v_mfma_f32_16x16x32_bf16 v[26:29], v[138:141], v[178:181], 0
	v_mfma_f32_16x16x32_bf16 v[26:29], v[142:145], v[182:185], v[26:29]
	v_mfma_f32_16x16x32_bf16 v[22:25], v[146:149], v[178:181], 0
	v_mfma_f32_16x16x32_bf16 v[22:25], v[150:153], v[182:185], v[22:25]
	v_mfma_f32_16x16x32_bf16 v[18:21], v[154:157], v[178:181], 0
	v_mfma_f32_16x16x32_bf16 v[18:21], v[158:161], v[182:185], v[18:21]
	v_mfma_f32_16x16x32_bf16 v[2:5], v[154:157], v[186:189], 0
	v_mfma_f32_16x16x32_bf16 v[2:5], v[158:161], v[190:193], v[2:5]
	v_mfma_f32_16x16x32_bf16 v[6:9], v[146:149], v[186:189], 0
	v_mfma_f32_16x16x32_bf16 v[6:9], v[150:153], v[190:193], v[6:9]
	v_mfma_f32_16x16x32_bf16 v[10:13], v[138:141], v[186:189], 0
	v_mfma_f32_16x16x32_bf16 v[10:13], v[142:145], v[190:193], v[10:13]
	v_mfma_f32_16x16x32_bf16 v[14:17], v[130:133], v[186:189], 0
	v_mfma_f32_16x16x32_bf16 v[14:17], v[134:137], v[190:193], v[14:17]
	s_barrier
; #define PG8_STAGE(bufoff, gbase, voff) do { _Pragma("unroll") for (int _i = 0; _i < 2; ++_i) { \
;         const unsigned _m0 = ldsb + (unsigned)((bufoff) + _i * 8192); const char* _gb = (const char*)(gbase); \
;         asm volatile("s_mov_b32 m0, %0\n\ts_nop 0\n\tglobal_load_lds_dwordx4 %1, %2" :: "s"(_m0), "v"((voff)[_i]), "s"(_gb) : "m0", "memory"); } } while (0)
; #define PG8_LDA(dst, b, h) do { _Pragma("unroll") for (int m = 0; m < 4; ++m) _Pragma("unroll") for (int k = 0; k < 2; ++k) dst[m][k] = *(const LAS bf16x8*)(lds + PG8_SA(b, h) + aoff + m * 2048 + k * 1024); } while (0)
; #define PG8_LDB(dst, b, h) do { _Pragma("unroll") for (int n = 0; n < 2; ++n) _Pragma("unroll") for (int k = 0; k < 2; ++k) dst[n][k] = *(const LAS bf16x8*)(lds + PG8_SB(b, h) + boff + n * 2048 + k * 1024); } while (0)
; #define PG8_MMA(ai, bj, At, Bt) do { __builtin_amdgcn_s_setprio(1); _Pragma("unroll") for (int m = 0; m < 4; ++m) _Pragma("unroll") for (int n = 0; n < 2; ++n) _Pragma("unroll") for (int k = 0; k < 2; ++k) \
;         acc[ai][bj][m][n] = __builtin_amdgcn_mfma_f32_16x16x32_bf16(Bt[n][k], At[m][k], acc[ai][bj][m][n], 0, 0, 0); __builtin_amdgcn_s_setprio(0); } while (0)
; #define PG8_WAIT_V(n) asm volatile("s_waitcnt vmcnt(" #n ")" ::: "memory")
; #define PG8_WAIT_L(n) asm volatile("s_waitcnt lgkmcnt(" #n ")" ::: "memory")
; #define PG8_BAR __builtin_amdgcn_s_barrier()
; #define PG8_SCHED __builtin_amdgcn_sched_barrier(0)
; template <class Epi, bool ALIGN_EPI>
; __device__ __forceinline__ void gemm_phase(LAS unsigned char* lds, const Gemm g, const StaticOrder& S, const Epi& E) {
;     ...
;             PG8_LDB(B0, 1, 0); PG8_LDB(B1, 1, 1); PG8_SCHED; PG8_LDA(At, 1, 0); PG8_STAGE(PG8_SA(0, 1), a2 + hstepA, voffA);
;             PG8_WAIT_V(8); PG8_WAIT_L(0); PG8_BAR; PG8_MMA(0, 0, At, B0); PG8_MMA(0, 1, At, B1); PG8_BAR; PG8_SCHED;
;             PG8_LDA(At, 1, 1); PG8_STAGE(PG8_SB(1, 0), b3, voffB); PG8_STAGE(PG8_SB(1, 1), b3 + hstepB, voffB); PG8_STAGE(PG8_SA(1, 0), a3, voffA);
;             PG8_WAIT_V(8); PG8_WAIT_L(0); PG8_BAR; PG8_MMA(1, 0, At, B0); PG8_MMA(1, 1, At, B1); PG8_BAR; PG8_SCHED;
	s_setprio 0
	v_add_u32_e32 v142, 0x18000, v245
	v_add_u32_e32 v158, 0x1c000, v245
	ds_read_b128 v[130:133], v142
	ds_read_b128 v[134:137], v142 offset:1024
	ds_read_b128 v[138:141], v142 offset:2048
	ds_read_b128 v[142:145], v142 offset:3072
	ds_read_b128 v[146:149], v158
	ds_read_b128 v[150:153], v158 offset:1024
	ds_read_b128 v[154:157], v158 offset:2048
	ds_read_b128 v[158:161], v158 offset:3072
	ds_read_b128 v[162:165], v246 offset:32768
	ds_read_b128 v[166:169], v246 offset:33792
	ds_read_b128 v[170:173], v246 offset:34816
	ds_read_b128 v[174:177], v246 offset:35840
	ds_read_b128 v[178:181], v246 offset:36864
	ds_read_b128 v[182:185], v246 offset:37888
	ds_read_b128 v[186:189], v246 offset:38912
	ds_read_b128 v[190:193], v246 offset:39936
	s_add_u32 s56, s56, s38
	s_addc_u32 s57, s57, 0
	s_mov_b32 m0, s31
	s_nop 0
	global_load_lds_dwordx4 v0, s[56:57]
	s_nop 0
	s_mov_b32 m0, s53
	s_nop 0
	global_load_lds_dwordx4 v206, s[56:57]
	s_waitcnt vmcnt(8)
	s_waitcnt lgkmcnt(0)
	s_setprio 1
	s_barrier
	v_mfma_f32_16x16x32_bf16 v[126:129], v[130:133], v[162:165], v[126:129]
	v_mfma_f32_16x16x32_bf16 v[126:129], v[134:137], v[166:169], v[126:129]
	v_mfma_f32_16x16x32_bf16 v[122:125], v[138:141], v[162:165], v[122:125]
	v_mfma_f32_16x16x32_bf16 v[122:125], v[142:145], v[166:169], v[122:125]
	v_mfma_f32_16x16x32_bf16 v[118:121], v[146:149], v[162:165], v[118:121]
	v_mfma_f32_16x16x32_bf16 v[118:121], v[150:153], v[166:169], v[118:121]
	v_mfma_f32_16x16x32_bf16 v[114:117], v[154:157], v[162:165], v[114:117]
	v_mfma_f32_16x16x32_bf16 v[114:117], v[158:161], v[166:169], v[114:117]
	v_mfma_f32_16x16x32_bf16 v[98:101], v[154:157], v[170:173], v[98:101]
	v_mfma_f32_16x16x32_bf16 v[98:101], v[158:161], v[174:177], v[98:101]
	v_mfma_f32_16x16x32_bf16 v[102:105], v[146:149], v[170:173], v[102:105]
	v_mfma_f32_16x16x32_bf16 v[102:105], v[150:153], v[174:177], v[102:105]
	v_mfma_f32_16x16x32_bf16 v[106:109], v[138:141], v[170:173], v[106:109]
	v_mfma_f32_16x16x32_bf16 v[106:109], v[142:145], v[174:177], v[106:109]
	v_mfma_f32_16x16x32_bf16 v[110:113], v[130:133], v[170:173], v[110:113]
	v_mfma_f32_16x16x32_bf16 v[110:113], v[134:137], v[174:177], v[110:113]
	v_mfma_f32_16x16x32_bf16 v[94:97], v[130:133], v[178:181], v[94:97]
	v_mfma_f32_16x16x32_bf16 v[94:97], v[134:137], v[182:185], v[94:97]
	v_mfma_f32_16x16x32_bf16 v[90:93], v[138:141], v[178:181], v[90:93]
	v_mfma_f32_16x16x32_bf16 v[90:93], v[142:145], v[182:185], v[90:93]
	v_mfma_f32_16x16x32_bf16 v[86:89], v[146:149], v[178:181], v[86:89]
	v_mfma_f32_16x16x32_bf16 v[86:89], v[150:153], v[182:185], v[86:89]
	v_mfma_f32_16x16x32_bf16 v[82:85], v[154:157], v[178:181], v[82:85]
	v_mfma_f32_16x16x32_bf16 v[82:85], v[158:161], v[182:185], v[82:85]
	v_mfma_f32_16x16x32_bf16 v[66:69], v[154:157], v[186:189], v[66:69]
	v_mfma_f32_16x16x32_bf16 v[66:69], v[158:161], v[190:193], v[66:69]
	v_mfma_f32_16x16x32_bf16 v[70:73], v[146:149], v[186:189], v[70:73]
	v_mfma_f32_16x16x32_bf16 v[70:73], v[150:153], v[190:193], v[70:73]
	v_mfma_f32_16x16x32_bf16 v[74:77], v[138:141], v[186:189], v[74:77]
	v_mfma_f32_16x16x32_bf16 v[74:77], v[142:145], v[190:193], v[74:77]
	v_mfma_f32_16x16x32_bf16 v[78:81], v[130:133], v[186:189], v[78:81]
	v_mfma_f32_16x16x32_bf16 v[78:81], v[134:137], v[190:193], v[78:81]
	s_barrier
	s_setprio 0
	ds_read_b128 v[162:165], v246 offset:49152
	ds_read_b128 v[166:169], v246 offset:50176
	ds_read_b128 v[170:173], v246 offset:51200
	ds_read_b128 v[174:177], v246 offset:52224
	ds_read_b128 v[178:181], v246 offset:53248
	ds_read_b128 v[182:185], v246 offset:54272
	ds_read_b128 v[186:189], v246 offset:55296
	ds_read_b128 v[190:193], v246 offset:56320
	s_add_u32 s54, s54, 0x80
	s_addc_u32 s55, s55, 0
	s_mov_b32 m0, s85
	s_nop 0
	global_load_lds_dwordx4 v195, s[54:55]
	s_nop 0
	s_mov_b32 m0, s65
	s_nop 0
	global_load_lds_dwordx4 v207, s[54:55]
	s_add_u32 s54, s58, 0x80
	s_addc_u32 s55, s59, 0
	s_mov_b32 m0, s93
	s_nop 0
	global_load_lds_dwordx4 v195, s[54:55]
	s_nop 0
	s_mov_b32 m0, s28
	s_nop 0
	global_load_lds_dwordx4 v207, s[54:55]
	s_nop 0
	s_mov_b32 m0, s67
	s_nop 0
	global_load_lds_dwordx4 v0, s[48:49]
	s_nop 0
	s_mov_b32 m0, s92
	s_nop 0
	global_load_lds_dwordx4 v206, s[48:49]
	s_waitcnt vmcnt(8)
	s_waitcnt lgkmcnt(0)
	s_setprio 1
	s_barrier
	v_mfma_f32_16x16x32_bf16 v[62:65], v[130:133], v[162:165], v[62:65]
	v_mfma_f32_16x16x32_bf16 v[62:65], v[134:137], v[166:169], v[62:65]
	v_mfma_f32_16x16x32_bf16 v[58:61], v[138:141], v[162:165], v[58:61]
	v_mfma_f32_16x16x32_bf16 v[58:61], v[142:145], v[166:169], v[58:61]
	v_mfma_f32_16x16x32_bf16 v[54:57], v[146:149], v[162:165], v[54:57]
	v_mfma_f32_16x16x32_bf16 v[54:57], v[150:153], v[166:169], v[54:57]
	v_mfma_f32_16x16x32_bf16 v[50:53], v[154:157], v[162:165], v[50:53]
	v_mfma_f32_16x16x32_bf16 v[50:53], v[158:161], v[166:169], v[50:53]
	v_mfma_f32_16x16x32_bf16 v[34:37], v[154:157], v[170:173], v[34:37]
	v_mfma_f32_16x16x32_bf16 v[34:37], v[158:161], v[174:177], v[34:37]
	v_mfma_f32_16x16x32_bf16 v[38:41], v[146:149], v[170:173], v[38:41]
	v_mfma_f32_16x16x32_bf16 v[38:41], v[150:153], v[174:177], v[38:41]
	v_mfma_f32_16x16x32_bf16 v[42:45], v[138:141], v[170:173], v[42:45]
	v_mfma_f32_16x16x32_bf16 v[42:45], v[142:145], v[174:177], v[42:45]
	v_mfma_f32_16x16x32_bf16 v[46:49], v[130:133], v[170:173], v[46:49]
	v_mfma_f32_16x16x32_bf16 v[46:49], v[134:137], v[174:177], v[46:49]
	v_mfma_f32_16x16x32_bf16 v[30:33], v[130:133], v[178:181], v[30:33]
	v_mfma_f32_16x16x32_bf16 v[30:33], v[134:137], v[182:185], v[30:33]
	v_mfma_f32_16x16x32_bf16 v[26:29], v[138:141], v[178:181], v[26:29]
	v_mfma_f32_16x16x32_bf16 v[26:29], v[142:145], v[182:185], v[26:29]
	v_mfma_f32_16x16x32_bf16 v[22:25], v[146:149], v[178:181], v[22:25]
	v_mfma_f32_16x16x32_bf16 v[22:25], v[150:153], v[182:185], v[22:25]
	v_mfma_f32_16x16x32_bf16 v[18:21], v[154:157], v[178:181], v[18:21]
	v_mfma_f32_16x16x32_bf16 v[18:21], v[158:161], v[182:185], v[18:21]
	v_mfma_f32_16x16x32_bf16 v[2:5], v[154:157], v[186:189], v[2:5]
	v_mfma_f32_16x16x32_bf16 v[2:5], v[158:161], v[190:193], v[2:5]
	v_mfma_f32_16x16x32_bf16 v[6:9], v[146:149], v[186:189], v[6:9]
	v_mfma_f32_16x16x32_bf16 v[6:9], v[150:153], v[190:193], v[6:9]
	v_mfma_f32_16x16x32_bf16 v[10:13], v[138:141], v[186:189], v[10:13]
	v_mfma_f32_16x16x32_bf16 v[10:13], v[142:145], v[190:193], v[10:13]
	v_mfma_f32_16x16x32_bf16 v[14:17], v[130:133], v[186:189], v[14:17]
	v_mfma_f32_16x16x32_bf16 v[14:17], v[134:137], v[190:193], v[14:17]
	s_barrier
	s_setprio 0
	s_add_u32 s4, s4, 0x100
	s_addc_u32 s5, s5, 0
	s_add_u32 s15, s15, 0x100
	s_addc_u32 s42, s42, 0
	s_cmp_ge_u32 s44, s36
	s_mov_b32 s43, s44
; #define PG8_STAGE(bufoff, gbase, voff) do { _Pragma("unroll") for (int _i = 0; _i < 2; ++_i) { \
;         const unsigned _m0 = ldsb + (unsigned)((bufoff) + _i * 8192); const char* _gb = (const char*)(gbase); \
;         asm volatile("s_mov_b32 m0, %0\n\ts_nop 0\n\tglobal_load_lds_dwordx4 %1, %2" :: "s"(_m0), "v"((voff)[_i]), "s"(_gb) : "m0", "memory"); } } while (0)
; #define PG8_LDA(dst, b, h) do { _Pragma("unroll") for (int m = 0; m < 4; ++m) _Pragma("unroll") for (int k = 0; k < 2; ++k) dst[m][k] = *(const LAS bf16x8*)(lds + PG8_SA(b, h) + aoff + m * 2048 + k * 1024); } while (0)
; #define PG8_LDB(dst, b, h) do { _Pragma("unroll") for (int n = 0; n < 2; ++n) _Pragma("unroll") for (int k = 0; k < 2; ++k) dst[n][k] = *(const LAS bf16x8*)(lds + PG8_SB(b, h) + boff + n * 2048 + k * 1024); } while (0)
; #define PG8_MMA(ai, bj, At, Bt) do { __builtin_amdgcn_s_setprio(1); _Pragma("unroll") for (int m = 0; m < 4; ++m) _Pragma("unroll") for (int n = 0; n < 2; ++n) _Pragma("unroll") for (int k = 0; k < 2; ++k) \
;         acc[ai][bj][m][n] = __builtin_amdgcn_mfma_f32_16x16x32_bf16(Bt[n][k], At[m][k], acc[ai][bj][m][n], 0, 0, 0); __builtin_amdgcn_s_setprio(0); } while (0)
; #define PG8_WAIT_V(n) asm volatile("s_waitcnt vmcnt(" #n ")" ::: "memory")
; #define PG8_WAIT_L(n) asm volatile("s_waitcnt lgkmcnt(" #n ")" ::: "memory")
; template <class Epi, bool ALIGN_EPI>
; __device__ __forceinline__ void gemm_phase(LAS unsigned char* lds, const Gemm g, const StaticOrder& S, const Epi& E) {
;     ...
;         for (int t = 0; t < nt; t += 2) {
;             const bool last = (t == nt - 2);
;             const char* a1 = cA + (size_t)(t + 1) * kstep;
;             const char* a2 = last ? nA : cA + (size_t)(t + 2) * kstep; const char* b2 = last ? nB : cB + (size_t)(t + 2) * kstep;
;             const char* a3 = a2 + kstep; const char* b3 = b2 + kstep;
;             PG8_LDB(B0, 0, 0); PG8_LDB(B1, 0, 1); PG8_SCHED; PG8_LDA(At, 0, 0); PG8_STAGE(PG8_SA(1, 1), a1 + hstepA, voffA);
;             PG8_WAIT_V(8); PG8_WAIT_L(0); PG8_BAR; PG8_MMA(0, 0, At, B0); PG8_MMA(0, 1, At, B1); PG8_BAR; PG8_SCHED;
;             PG8_LDA(At, 0, 1); PG8_STAGE(PG8_SB(0, 0), b2, voffB); PG8_STAGE(PG8_SB(0, 1), b2 + hstepB, voffB); PG8_STAGE(PG8_SA(0, 0), a2, voffA);
;             PG8_WAIT_V(8); PG8_WAIT_L(0); PG8_BAR; PG8_MMA(1, 0, At, B0); PG8_MMA(1, 1, At, B1); PG8_BAR; PG8_SCHED;
.LBB0_201:
	v_add_u32_e32 v142, 0x10000, v245
	v_add_u32_e32 v158, 0x14000, v245
	ds_read_b128 v[130:133], v142
	ds_read_b128 v[134:137], v142 offset:1024
	ds_read_b128 v[138:141], v142 offset:2048
	ds_read_b128 v[142:145], v142 offset:3072
	ds_read_b128 v[146:149], v158
	ds_read_b128 v[150:153], v158 offset:1024
	ds_read_b128 v[154:157], v158 offset:2048
	ds_read_b128 v[158:161], v158 offset:3072
	s_add_i32 s44, s43, 2
	s_cmp_eq_u32 s68, s43
	s_cselect_b32 s56, s0, s15
	s_cselect_b32 s57, s1, s42
	s_cselect_b32 s54, s94, s4
	s_cselect_b32 s55, s95, s5
	s_add_u32 s48, s56, 0x80
	s_addc_u32 s49, s57, 0
	ds_read_b128 v[162:165], v246
	ds_read_b128 v[166:169], v246 offset:1024
	ds_read_b128 v[170:173], v246 offset:2048
	ds_read_b128 v[174:177], v246 offset:3072
	ds_read_b128 v[178:181], v246 offset:4096
	ds_read_b128 v[182:185], v246 offset:5120
	ds_read_b128 v[186:189], v246 offset:6144
	ds_read_b128 v[190:193], v246 offset:7168
	s_add_u32 s43, s15, s38
	s_addc_u32 s45, s42, 0
	s_add_u32 s58, s43, 0xffffff80
	s_addc_u32 s59, s45, -1
	s_mov_b32 m0, s37
	s_nop 0
	global_load_lds_dwordx4 v0, s[58:59]
	s_nop 0
	s_mov_b32 m0, s41
	s_nop 0
	global_load_lds_dwordx4 v206, s[58:59]
	s_waitcnt vmcnt(8)
	s_waitcnt lgkmcnt(0)
	s_setprio 1
	s_barrier
	v_mfma_f32_16x16x32_bf16 v[126:129], v[130:133], v[162:165], v[126:129]
	v_mfma_f32_16x16x32_bf16 v[126:129], v[134:137], v[166:169], v[126:129]
	v_mfma_f32_16x16x32_bf16 v[122:125], v[138:141], v[162:165], v[122:125]
	v_mfma_f32_16x16x32_bf16 v[122:125], v[142:145], v[166:169], v[122:125]
	v_mfma_f32_16x16x32_bf16 v[118:121], v[146:149], v[162:165], v[118:121]
	v_mfma_f32_16x16x32_bf16 v[118:121], v[150:153], v[166:169], v[118:121]
	v_mfma_f32_16x16x32_bf16 v[114:117], v[154:157], v[162:165], v[114:117]
	v_mfma_f32_16x16x32_bf16 v[114:117], v[158:161], v[166:169], v[114:117]
	v_mfma_f32_16x16x32_bf16 v[98:101], v[154:157], v[170:173], v[98:101]
	v_mfma_f32_16x16x32_bf16 v[98:101], v[158:161], v[174:177], v[98:101]
	v_mfma_f32_16x16x32_bf16 v[102:105], v[146:149], v[170:173], v[102:105]
	v_mfma_f32_16x16x32_bf16 v[102:105], v[150:153], v[174:177], v[102:105]
	v_mfma_f32_16x16x32_bf16 v[106:109], v[138:141], v[170:173], v[106:109]
	v_mfma_f32_16x16x32_bf16 v[106:109], v[142:145], v[174:177], v[106:109]
	v_mfma_f32_16x16x32_bf16 v[110:113], v[130:133], v[170:173], v[110:113]
	v_mfma_f32_16x16x32_bf16 v[110:113], v[134:137], v[174:177], v[110:113]
	v_mfma_f32_16x16x32_bf16 v[94:97], v[130:133], v[178:181], v[94:97]
	v_mfma_f32_16x16x32_bf16 v[94:97], v[134:137], v[182:185], v[94:97]
	v_mfma_f32_16x16x32_bf16 v[90:93], v[138:141], v[178:181], v[90:93]
	v_mfma_f32_16x16x32_bf16 v[90:93], v[142:145], v[182:185], v[90:93]
	v_mfma_f32_16x16x32_bf16 v[86:89], v[146:149], v[178:181], v[86:89]
	v_mfma_f32_16x16x32_bf16 v[86:89], v[150:153], v[182:185], v[86:89]
	v_mfma_f32_16x16x32_bf16 v[82:85], v[154:157], v[178:181], v[82:85]
	v_mfma_f32_16x16x32_bf16 v[82:85], v[158:161], v[182:185], v[82:85]
	v_mfma_f32_16x16x32_bf16 v[66:69], v[154:157], v[186:189], v[66:69]
	v_mfma_f32_16x16x32_bf16 v[66:69], v[158:161], v[190:193], v[66:69]
	v_mfma_f32_16x16x32_bf16 v[70:73], v[146:149], v[186:189], v[70:73]
	v_mfma_f32_16x16x32_bf16 v[70:73], v[150:153], v[190:193], v[70:73]
	v_mfma_f32_16x16x32_bf16 v[74:77], v[138:141], v[186:189], v[74:77]
	v_mfma_f32_16x16x32_bf16 v[74:77], v[142:145], v[190:193], v[74:77]
	v_mfma_f32_16x16x32_bf16 v[78:81], v[130:133], v[186:189], v[78:81]
	v_mfma_f32_16x16x32_bf16 v[78:81], v[134:137], v[190:193], v[78:81]
	s_barrier
	s_setprio 0
	ds_read_b128 v[162:165], v246 offset:16384
	ds_read_b128 v[166:169], v246 offset:17408
	ds_read_b128 v[170:173], v246 offset:18432
	ds_read_b128 v[174:177], v246 offset:19456
	ds_read_b128 v[178:181], v246 offset:20480
	ds_read_b128 v[182:185], v246 offset:21504
	ds_read_b128 v[186:189], v246 offset:22528
	ds_read_b128 v[190:193], v246 offset:23552
	s_mov_b32 m0, s46
	s_nop 0
	global_load_lds_dwordx4 v195, s[54:55]
	s_add_u32 s58, s54, s38
	s_mov_b32 m0, s26
	s_nop 0
	global_load_lds_dwordx4 v207, s[54:55]
	s_addc_u32 s59, s55, 0
	s_mov_b32 m0, s27
	s_nop 0
	global_load_lds_dwordx4 v195, s[58:59]
	s_nop 0
	s_mov_b32 m0, s30
	s_nop 0
	global_load_lds_dwordx4 v207, s[58:59]
	s_nop 0
	s_mov_b32 m0, s29
	s_nop 0
	global_load_lds_dwordx4 v0, s[56:57]
	s_nop 0
	s_mov_b32 m0, s17
	s_nop 0
	global_load_lds_dwordx4 v206, s[56:57]
	s_waitcnt vmcnt(8)
	s_waitcnt lgkmcnt(0)
	s_setprio 1
	s_barrier
	v_mfma_f32_16x16x32_bf16 v[62:65], v[130:133], v[162:165], v[62:65]
	v_mfma_f32_16x16x32_bf16 v[62:65], v[134:137], v[166:169], v[62:65]
	v_mfma_f32_16x16x32_bf16 v[58:61], v[138:141], v[162:165], v[58:61]
	v_mfma_f32_16x16x32_bf16 v[58:61], v[142:145], v[166:169], v[58:61]
	v_mfma_f32_16x16x32_bf16 v[54:57], v[146:149], v[162:165], v[54:57]
	v_mfma_f32_16x16x32_bf16 v[54:57], v[150:153], v[166:169], v[54:57]
	v_mfma_f32_16x16x32_bf16 v[50:53], v[154:157], v[162:165], v[50:53]
	v_mfma_f32_16x16x32_bf16 v[50:53], v[158:161], v[166:169], v[50:53]
	v_mfma_f32_16x16x32_bf16 v[34:37], v[154:157], v[170:173], v[34:37]
	v_mfma_f32_16x16x32_bf16 v[34:37], v[158:161], v[174:177], v[34:37]
	v_mfma_f32_16x16x32_bf16 v[38:41], v[146:149], v[170:173], v[38:41]
	v_mfma_f32_16x16x32_bf16 v[38:41], v[150:153], v[174:177], v[38:41]
	v_mfma_f32_16x16x32_bf16 v[42:45], v[138:141], v[170:173], v[42:45]
	v_mfma_f32_16x16x32_bf16 v[42:45], v[142:145], v[174:177], v[42:45]
	v_mfma_f32_16x16x32_bf16 v[46:49], v[130:133], v[170:173], v[46:49]
	v_mfma_f32_16x16x32_bf16 v[46:49], v[134:137], v[174:177], v[46:49]
	v_mfma_f32_16x16x32_bf16 v[30:33], v[130:133], v[178:181], v[30:33]
	v_mfma_f32_16x16x32_bf16 v[30:33], v[134:137], v[182:185], v[30:33]
	v_mfma_f32_16x16x32_bf16 v[26:29], v[138:141], v[178:181], v[26:29]
	v_mfma_f32_16x16x32_bf16 v[26:29], v[142:145], v[182:185], v[26:29]
	v_mfma_f32_16x16x32_bf16 v[22:25], v[146:149], v[178:181], v[22:25]
	v_mfma_f32_16x16x32_bf16 v[22:25], v[150:153], v[182:185], v[22:25]
	v_mfma_f32_16x16x32_bf16 v[18:21], v[154:157], v[178:181], v[18:21]
	v_mfma_f32_16x16x32_bf16 v[18:21], v[158:161], v[182:185], v[18:21]
	v_mfma_f32_16x16x32_bf16 v[2:5], v[154:157], v[186:189], v[2:5]
	v_mfma_f32_16x16x32_bf16 v[2:5], v[158:161], v[190:193], v[2:5]
	v_mfma_f32_16x16x32_bf16 v[6:9], v[146:149], v[186:189], v[6:9]
	v_mfma_f32_16x16x32_bf16 v[6:9], v[150:153], v[190:193], v[6:9]
	v_mfma_f32_16x16x32_bf16 v[10:13], v[138:141], v[186:189], v[10:13]
	v_mfma_f32_16x16x32_bf16 v[10:13], v[142:145], v[190:193], v[10:13]
	v_mfma_f32_16x16x32_bf16 v[14:17], v[130:133], v[186:189], v[14:17]
	v_mfma_f32_16x16x32_bf16 v[14:17], v[134:137], v[190:193], v[14:17]
	s_barrier
; #define PG8_STAGE(bufoff, gbase, voff) do { _Pragma("unroll") for (int _i = 0; _i < 2; ++_i) { \
;         const unsigned _m0 = ldsb + (unsigned)((bufoff) + _i * 8192); const char* _gb = (const char*)(gbase); \
;         asm volatile("s_mov_b32 m0, %0\n\ts_nop 0\n\tglobal_load_lds_dwordx4 %1, %2" :: "s"(_m0), "v"((voff)[_i]), "s"(_gb) : "m0", "memory"); } } while (0)
; #define PG8_LDA(dst, b, h) do { _Pragma("unroll") for (int m = 0; m < 4; ++m) _Pragma("unroll") for (int k = 0; k < 2; ++k) dst[m][k] = *(const LAS bf16x8*)(lds + PG8_SA(b, h) + aoff + m * 2048 + k * 1024); } while (0)
; #define PG8_LDB(dst, b, h) do { _Pragma("unroll") for (int n = 0; n < 2; ++n) _Pragma("unroll") for (int k = 0; k < 2; ++k) dst[n][k] = *(const LAS bf16x8*)(lds + PG8_SB(b, h) + boff + n * 2048 + k * 1024); } while (0)
; #define PG8_MMA(ai, bj, At, Bt) do { __builtin_amdgcn_s_setprio(1); _Pragma("unroll") for (int m = 0; m < 4; ++m) _Pragma("unroll") for (int n = 0; n < 2; ++n) _Pragma("unroll") for (int k = 0; k < 2; ++k) \
;         acc[ai][bj][m][n] = __builtin_amdgcn_mfma_f32_16x16x32_bf16(Bt[n][k], At[m][k], acc[ai][bj][m][n], 0, 0, 0); __builtin_amdgcn_s_setprio(0); } while (0)
; #define PG8_WAIT_V(n) asm volatile("s_waitcnt vmcnt(" #n ")" ::: "memory")
; #define PG8_WAIT_L(n) asm volatile("s_waitcnt lgkmcnt(" #n ")" ::: "memory")
; #define PG8_BAR __builtin_amdgcn_s_barrier()
; #define PG8_SCHED __builtin_amdgcn_sched_barrier(0)
; template <class Epi, bool ALIGN_EPI>
; __device__ __forceinline__ void gemm_phase(LAS unsigned char* lds, const Gemm g, const StaticOrder& S, const Epi& E) {
;     ...
;             PG8_LDB(B0, 1, 0); PG8_LDB(B1, 1, 1); PG8_SCHED; PG8_LDA(At, 1, 0); PG8_STAGE(PG8_SA(0, 1), a2 + hstepA, voffA);
;             PG8_WAIT_V(8); PG8_WAIT_L(0); PG8_BAR; PG8_MMA(0, 0, At, B0); PG8_MMA(0, 1, At, B1); PG8_BAR; PG8_SCHED;
;             PG8_LDA(At, 1, 1); PG8_STAGE(PG8_SB(1, 0), b3, voffB); PG8_STAGE(PG8_SB(1, 1), b3 + hstepB, voffB); PG8_STAGE(PG8_SA(1, 0), a3, voffA);
;             PG8_WAIT_V(8); PG8_WAIT_L(0); PG8_BAR; PG8_MMA(1, 0, At, B0); PG8_MMA(1, 1, At, B1); PG8_BAR; PG8_SCHED;
;         }
;         if constexpr (ALIGN_EPI) { if (wr == 0) PG8_BAR; }
	s_setprio 0
	v_add_u32_e32 v142, 0x18000, v245
	v_add_u32_e32 v158, 0x1c000, v245
	ds_read_b128 v[130:133], v142
	ds_read_b128 v[134:137], v142 offset:1024
	ds_read_b128 v[138:141], v142 offset:2048
	ds_read_b128 v[142:145], v142 offset:3072
	ds_read_b128 v[146:149], v158
	ds_read_b128 v[150:153], v158 offset:1024
	ds_read_b128 v[154:157], v158 offset:2048
	ds_read_b128 v[158:161], v158 offset:3072
	ds_read_b128 v[162:165], v246 offset:32768
	ds_read_b128 v[166:169], v246 offset:33792
	ds_read_b128 v[170:173], v246 offset:34816
	ds_read_b128 v[174:177], v246 offset:35840
	ds_read_b128 v[178:181], v246 offset:36864
	ds_read_b128 v[182:185], v246 offset:37888
	ds_read_b128 v[186:189], v246 offset:38912
	ds_read_b128 v[190:193], v246 offset:39936
	s_add_u32 s56, s56, s38
	s_addc_u32 s57, s57, 0
	s_mov_b32 m0, s31
	s_nop 0
	global_load_lds_dwordx4 v0, s[56:57]
	s_nop 0
	s_mov_b32 m0, s53
	s_nop 0
	global_load_lds_dwordx4 v206, s[56:57]
	s_waitcnt vmcnt(8)
	s_waitcnt lgkmcnt(0)
	s_setprio 1
	s_barrier
	v_mfma_f32_16x16x32_bf16 v[126:129], v[130:133], v[162:165], v[126:129]
	v_mfma_f32_16x16x32_bf16 v[126:129], v[134:137], v[166:169], v[126:129]
	v_mfma_f32_16x16x32_bf16 v[122:125], v[138:141], v[162:165], v[122:125]
	v_mfma_f32_16x16x32_bf16 v[122:125], v[142:145], v[166:169], v[122:125]
	v_mfma_f32_16x16x32_bf16 v[118:121], v[146:149], v[162:165], v[118:121]
	v_mfma_f32_16x16x32_bf16 v[118:121], v[150:153], v[166:169], v[118:121]
	v_mfma_f32_16x16x32_bf16 v[114:117], v[154:157], v[162:165], v[114:117]
	v_mfma_f32_16x16x32_bf16 v[114:117], v[158:161], v[166:169], v[114:117]
	v_mfma_f32_16x16x32_bf16 v[98:101], v[154:157], v[170:173], v[98:101]
	v_mfma_f32_16x16x32_bf16 v[98:101], v[158:161], v[174:177], v[98:101]
	v_mfma_f32_16x16x32_bf16 v[102:105], v[146:149], v[170:173], v[102:105]
	v_mfma_f32_16x16x32_bf16 v[102:105], v[150:153], v[174:177], v[102:105]
	v_mfma_f32_16x16x32_bf16 v[106:109], v[138:141], v[170:173], v[106:109]
	v_mfma_f32_16x16x32_bf16 v[106:109], v[142:145], v[174:177], v[106:109]
	v_mfma_f32_16x16x32_bf16 v[110:113], v[130:133], v[170:173], v[110:113]
	v_mfma_f32_16x16x32_bf16 v[110:113], v[134:137], v[174:177], v[110:113]
	v_mfma_f32_16x16x32_bf16 v[94:97], v[130:133], v[178:181], v[94:97]
	v_mfma_f32_16x16x32_bf16 v[94:97], v[134:137], v[182:185], v[94:97]
	v_mfma_f32_16x16x32_bf16 v[90:93], v[138:141], v[178:181], v[90:93]
	v_mfma_f32_16x16x32_bf16 v[90:93], v[142:145], v[182:185], v[90:93]
	v_mfma_f32_16x16x32_bf16 v[86:89], v[146:149], v[178:181], v[86:89]
	v_mfma_f32_16x16x32_bf16 v[86:89], v[150:153], v[182:185], v[86:89]
	v_mfma_f32_16x16x32_bf16 v[82:85], v[154:157], v[178:181], v[82:85]
	v_mfma_f32_16x16x32_bf16 v[82:85], v[158:161], v[182:185], v[82:85]
	v_mfma_f32_16x16x32_bf16 v[66:69], v[154:157], v[186:189], v[66:69]
	v_mfma_f32_16x16x32_bf16 v[66:69], v[158:161], v[190:193], v[66:69]
	v_mfma_f32_16x16x32_bf16 v[70:73], v[146:149], v[186:189], v[70:73]
	v_mfma_f32_16x16x32_bf16 v[70:73], v[150:153], v[190:193], v[70:73]
	v_mfma_f32_16x16x32_bf16 v[74:77], v[138:141], v[186:189], v[74:77]
	v_mfma_f32_16x16x32_bf16 v[74:77], v[142:145], v[190:193], v[74:77]
	v_mfma_f32_16x16x32_bf16 v[78:81], v[130:133], v[186:189], v[78:81]
	v_mfma_f32_16x16x32_bf16 v[78:81], v[134:137], v[190:193], v[78:81]
	s_barrier
	s_setprio 0
	ds_read_b128 v[162:165], v246 offset:49152
	ds_read_b128 v[166:169], v246 offset:50176
	ds_read_b128 v[170:173], v246 offset:51200
	ds_read_b128 v[174:177], v246 offset:52224
	ds_read_b128 v[178:181], v246 offset:53248
	ds_read_b128 v[182:185], v246 offset:54272
	ds_read_b128 v[186:189], v246 offset:55296
	ds_read_b128 v[190:193], v246 offset:56320
	s_add_u32 s54, s54, 0x80
	s_addc_u32 s55, s55, 0
	s_mov_b32 m0, s85
	s_nop 0
	global_load_lds_dwordx4 v195, s[54:55]
	s_nop 0
	s_mov_b32 m0, s65
	s_nop 0
	global_load_lds_dwordx4 v207, s[54:55]
	s_add_u32 s54, s58, 0x80
	s_addc_u32 s55, s59, 0
	s_mov_b32 m0, s93
	s_nop 0
	global_load_lds_dwordx4 v195, s[54:55]
	s_nop 0
	s_mov_b32 m0, s28
	s_nop 0
	global_load_lds_dwordx4 v207, s[54:55]
	s_nop 0
	s_mov_b32 m0, s67
	s_nop 0
	global_load_lds_dwordx4 v0, s[48:49]
	s_nop 0
	s_mov_b32 m0, s92
	s_nop 0
	global_load_lds_dwordx4 v206, s[48:49]
	s_waitcnt vmcnt(8)
	s_waitcnt lgkmcnt(0)
	s_setprio 1
	s_barrier
	v_mfma_f32_16x16x32_bf16 v[62:65], v[130:133], v[162:165], v[62:65]
	v_mfma_f32_16x16x32_bf16 v[62:65], v[134:137], v[166:169], v[62:65]
	v_mfma_f32_16x16x32_bf16 v[58:61], v[138:141], v[162:165], v[58:61]
	v_mfma_f32_16x16x32_bf16 v[58:61], v[142:145], v[166:169], v[58:61]
	v_mfma_f32_16x16x32_bf16 v[54:57], v[146:149], v[162:165], v[54:57]
	v_mfma_f32_16x16x32_bf16 v[54:57], v[150:153], v[166:169], v[54:57]
	v_mfma_f32_16x16x32_bf16 v[50:53], v[154:157], v[162:165], v[50:53]
	v_mfma_f32_16x16x32_bf16 v[50:53], v[158:161], v[166:169], v[50:53]
	v_mfma_f32_16x16x32_bf16 v[34:37], v[154:157], v[170:173], v[34:37]
	v_mfma_f32_16x16x32_bf16 v[34:37], v[158:161], v[174:177], v[34:37]
	v_mfma_f32_16x16x32_bf16 v[38:41], v[146:149], v[170:173], v[38:41]
	v_mfma_f32_16x16x32_bf16 v[38:41], v[150:153], v[174:177], v[38:41]
	v_mfma_f32_16x16x32_bf16 v[42:45], v[138:141], v[170:173], v[42:45]
	v_mfma_f32_16x16x32_bf16 v[42:45], v[142:145], v[174:177], v[42:45]
	v_mfma_f32_16x16x32_bf16 v[46:49], v[130:133], v[170:173], v[46:49]
	v_mfma_f32_16x16x32_bf16 v[46:49], v[134:137], v[174:177], v[46:49]
	v_mfma_f32_16x16x32_bf16 v[30:33], v[130:133], v[178:181], v[30:33]
	v_mfma_f32_16x16x32_bf16 v[30:33], v[134:137], v[182:185], v[30:33]
	v_mfma_f32_16x16x32_bf16 v[26:29], v[138:141], v[178:181], v[26:29]
	v_mfma_f32_16x16x32_bf16 v[26:29], v[142:145], v[182:185], v[26:29]
	v_mfma_f32_16x16x32_bf16 v[22:25], v[146:149], v[178:181], v[22:25]
	v_mfma_f32_16x16x32_bf16 v[22:25], v[150:153], v[182:185], v[22:25]
	v_mfma_f32_16x16x32_bf16 v[18:21], v[154:157], v[178:181], v[18:21]
	v_mfma_f32_16x16x32_bf16 v[18:21], v[158:161], v[182:185], v[18:21]
	v_mfma_f32_16x16x32_bf16 v[2:5], v[154:157], v[186:189], v[2:5]
	v_mfma_f32_16x16x32_bf16 v[2:5], v[158:161], v[190:193], v[2:5]
	v_mfma_f32_16x16x32_bf16 v[6:9], v[146:149], v[186:189], v[6:9]
	v_mfma_f32_16x16x32_bf16 v[6:9], v[150:153], v[190:193], v[6:9]
	v_mfma_f32_16x16x32_bf16 v[10:13], v[138:141], v[186:189], v[10:13]
	v_mfma_f32_16x16x32_bf16 v[10:13], v[142:145], v[190:193], v[10:13]
	v_mfma_f32_16x16x32_bf16 v[14:17], v[130:133], v[186:189], v[14:17]
	v_mfma_f32_16x16x32_bf16 v[14:17], v[134:137], v[190:193], v[14:17]
	s_barrier
	s_setprio 0
	s_add_u32 s4, s4, 0x100
	s_addc_u32 s5, s5, 0
	s_add_u32 s15, s15, 0x100
	s_addc_u32 s42, s42, 0
	s_cmp_ge_u32 s44, s36
	s_mov_b32 s43, s44
	s_cbranch_scc0 .LBB0_201
	v_readlane_b32 s4, v255, 6
	v_readlane_b32 s5, v255, 7
	s_and_b64 vcc, exec, s[4:5]
	s_cbranch_vccz .LBB0_204
	s_barrier

; #define PG8_STAGE(bufoff, gbase, voff) do { _Pragma("unroll") for (int _i = 0; _i < 2; ++_i) { \
;         const unsigned _m0 = ldsb + (unsigned)((bufoff) + _i * 8192); const char* _gb = (const char*)(gbase); \
;         asm volatile("s_mov_b32 m0, %0\n\ts_nop 0\n\tglobal_load_lds_dwordx4 %1, %2" :: "s"(_m0), "v"((voff)[_i]), "s"(_gb) : "m0", "memory"); } } while (0)
; #define PG8_LDA(dst, b, h) do { _Pragma("unroll") for (int m = 0; m < 4; ++m) _Pragma("unroll") for (int k = 0; k < 2; ++k) dst[m][k] = *(const LAS bf16x8*)(lds + PG8_SA(b, h) + aoff + m * 2048 + k * 1024); } while (0)
; #define PG8_LDB(dst, b, h) do { _Pragma("unroll") for (int n = 0; n < 2; ++n) _Pragma("unroll") for (int k = 0; k < 2; ++k) dst[n][k] = *(const LAS bf16x8*)(lds + PG8_SB(b, h) + boff + n * 2048 + k * 1024); } while (0)
; #define PG8_WAIT_V(n) asm volatile("s_waitcnt vmcnt(" #n ")" ::: "memory")
; #define PG8_WAIT_L(n) asm volatile("s_waitcnt lgkmcnt(" #n ")" ::: "memory")
; #define PG8_BAR __builtin_amdgcn_s_barrier()
; #define PG8_SCHED __builtin_amdgcn_sched_barrier(0)
; template <class Epi, bool ALIGN_EPI>
; __device__ __forceinline__ void gemm_phase(LAS unsigned char* lds, const Gemm g, const StaticOrder& S, const Epi& E) {
;     ...
;         const char* nA = has_next ? (const char*)g.A + (size_t)nxt.pm * tstepA + (size_t)nxt.pn * g.a_pn_off * 2 + (size_t)(nxt.pm >> 4) * g.a_adj : cA; const char* nB = has_next ? (const char*)g.Bt + (size_t)nxt.pn * tstepB : cB;
;         for (int t = 0; t < nt; t += 2) {
;             const bool last = (t == nt - 2);
;             const char* a1 = cA + (size_t)(t + 1) * kstep;
;             const char* a2 = last ? nA : cA + (size_t)(t + 2) * kstep; const char* b2 = last ? nB : cB + (size_t)(t + 2) * kstep;
;             const char* a3 = a2 + kstep; const char* b3 = b2 + kstep;
;             PG8_LDB(B0, 0, 0); PG8_LDB(B1, 0, 1); PG8_SCHED; PG8_LDA(At, 0, 0); PG8_STAGE(PG8_SA(1, 1), a1 + hstepA, voffA);
;             PG8_WAIT_V(8); PG8_WAIT_L(0); PG8_BAR; PG8_MMA(0, 0, At, B0); PG8_MMA(0, 1, At, B1); PG8_BAR; PG8_SCHED;
;             PG8_LDA(At, 0, 1); PG8_STAGE(PG8_SB(0, 0), b2, voffB); PG8_STAGE(PG8_SB(0, 1), b2 + hstepB, voffB); PG8_STAGE(PG8_SA(0, 0), a2, voffA);
;             PG8_WAIT_V(8); PG8_WAIT_L(0); PG8_BAR; PG8_MMA(1, 0, At, B0); PG8_MMA(1, 1, At, B1); PG8_BAR; PG8_SCHED;
.LBB0_270:
	s_add_u32 s4, s56, 0x100
	s_addc_u32 s5, s57, 0
	s_add_u32 s0, s58, 0x40080
	s_addc_u32 s1, s59, 0
	s_mov_b32 s44, 0
	s_add_i32 s55, s44, 2
	s_add_u32 s45, s0, 0xfffc0080
	s_addc_u32 s56, s1, -1
	s_cmp_eq_u32 s68, s44
	s_cselect_b32 s60, s96, s45
	s_cselect_b32 s61, s97, s56
	s_cselect_b32 s58, s48, s4
	s_cselect_b32 s59, s49, s5
	s_add_u32 s56, s60, 0x80
	s_addc_u32 s57, s61, 0
	s_mov_b32 m0, s41
	s_nop 0
	global_load_lds_dwordx4 v165, s[0:1]
	s_nop 0
	s_mov_b32 m0, s30
	s_nop 0
	global_load_lds_dwordx4 v171, s[0:1]
	s_waitcnt vmcnt(8)
	s_waitcnt lgkmcnt(0)
	s_setprio 1
	s_barrier
	v_mfma_f32_16x16x32_bf16 v[126:129], v[130:133], v[182:185], 0
	v_mfma_f32_16x16x32_bf16 v[126:129], v[134:137], v[186:189], v[126:129]
	v_mfma_f32_16x16x32_bf16 v[122:125], v[138:141], v[182:185], 0
	v_mfma_f32_16x16x32_bf16 v[122:125], v[142:145], v[186:189], v[122:125]
	v_mfma_f32_16x16x32_bf16 v[118:121], v[146:149], v[182:185], 0
	v_mfma_f32_16x16x32_bf16 v[118:121], v[150:153], v[186:189], v[118:121]
	v_mfma_f32_16x16x32_bf16 v[110:113], v[154:157], v[182:185], 0
	v_mfma_f32_16x16x32_bf16 v[110:113], v[158:161], v[186:189], v[110:113]
	v_mfma_f32_16x16x32_bf16 v[94:97], v[154:157], v[190:193], 0
	v_mfma_f32_16x16x32_bf16 v[94:97], v[158:161], v[202:205], v[94:97]
	v_mfma_f32_16x16x32_bf16 v[102:105], v[146:149], v[190:193], 0
	v_mfma_f32_16x16x32_bf16 v[102:105], v[150:153], v[202:205], v[102:105]
	v_mfma_f32_16x16x32_bf16 v[106:109], v[138:141], v[190:193], 0
	v_mfma_f32_16x16x32_bf16 v[106:109], v[142:145], v[202:205], v[106:109]
	v_mfma_f32_16x16x32_bf16 v[114:117], v[130:133], v[190:193], 0
	v_mfma_f32_16x16x32_bf16 v[114:117], v[134:137], v[202:205], v[114:117]
	v_mfma_f32_16x16x32_bf16 v[98:101], v[130:133], v[206:209], 0
	v_mfma_f32_16x16x32_bf16 v[98:101], v[134:137], v[210:213], v[98:101]
	v_mfma_f32_16x16x32_bf16 v[90:93], v[138:141], v[206:209], 0
	v_mfma_f32_16x16x32_bf16 v[90:93], v[142:145], v[210:213], v[90:93]
	v_mfma_f32_16x16x32_bf16 v[86:89], v[146:149], v[206:209], 0
	v_mfma_f32_16x16x32_bf16 v[86:89], v[150:153], v[210:213], v[86:89]
	v_mfma_f32_16x16x32_bf16 v[78:81], v[154:157], v[206:209], 0
	v_mfma_f32_16x16x32_bf16 v[78:81], v[158:161], v[210:213], v[78:81]
	v_mfma_f32_16x16x32_bf16 v[66:69], v[154:157], v[214:217], 0
	v_mfma_f32_16x16x32_bf16 v[66:69], v[158:161], v[240:243], v[66:69]
	v_mfma_f32_16x16x32_bf16 v[70:73], v[146:149], v[214:217], 0
	v_mfma_f32_16x16x32_bf16 v[70:73], v[150:153], v[240:243], v[70:73]
	v_mfma_f32_16x16x32_bf16 v[74:77], v[138:141], v[214:217], 0
	v_mfma_f32_16x16x32_bf16 v[74:77], v[142:145], v[240:243], v[74:77]
	v_mfma_f32_16x16x32_bf16 v[82:85], v[130:133], v[214:217], 0
	v_mfma_f32_16x16x32_bf16 v[82:85], v[134:137], v[240:243], v[82:85]
	s_barrier
	s_setprio 0
	ds_read_b128 v[182:185], v180 offset:16384
	ds_read_b128 v[186:189], v180 offset:17408
	ds_read_b128 v[190:193], v180 offset:18432
	ds_read_b128 v[202:205], v180 offset:19456
	ds_read_b128 v[206:209], v180 offset:20480
	ds_read_b128 v[210:213], v180 offset:21504
	ds_read_b128 v[214:217], v180 offset:22528
	ds_read_b128 v[240:243], v180 offset:23552
	s_mov_b32 m0, s42
	s_nop 0
	global_load_lds_dwordx4 v167, s[58:59]
	s_add_u32 s44, s58, s14
	s_mov_b32 m0, s43
	s_nop 0
	global_load_lds_dwordx4 v175, s[58:59]
	s_addc_u32 s45, s59, 0
	s_mov_b32 m0, s46
	s_nop 0
	global_load_lds_dwordx4 v167, s[44:45]
	s_nop 0
	s_mov_b32 m0, s50
	s_nop 0
	global_load_lds_dwordx4 v175, s[44:45]
	s_nop 0
	s_mov_b32 m0, s17
	s_nop 0
	global_load_lds_dwordx4 v165, s[60:61]
	s_nop 0
	s_mov_b32 m0, s53
	s_nop 0
	global_load_lds_dwordx4 v171, s[60:61]
	s_waitcnt vmcnt(8)
	s_waitcnt lgkmcnt(0)
	s_setprio 1
	s_barrier
	v_mfma_f32_16x16x32_bf16 v[62:65], v[130:133], v[182:185], 0
	v_mfma_f32_16x16x32_bf16 v[62:65], v[134:137], v[186:189], v[62:65]
	v_mfma_f32_16x16x32_bf16 v[58:61], v[138:141], v[182:185], 0
	v_mfma_f32_16x16x32_bf16 v[58:61], v[142:145], v[186:189], v[58:61]
	v_mfma_f32_16x16x32_bf16 v[54:57], v[146:149], v[182:185], 0
	v_mfma_f32_16x16x32_bf16 v[54:57], v[150:153], v[186:189], v[54:57]
	v_mfma_f32_16x16x32_bf16 v[50:53], v[154:157], v[182:185], 0
	v_mfma_f32_16x16x32_bf16 v[50:53], v[158:161], v[186:189], v[50:53]
	v_mfma_f32_16x16x32_bf16 v[30:33], v[154:157], v[190:193], 0
	v_mfma_f32_16x16x32_bf16 v[30:33], v[158:161], v[202:205], v[30:33]
	v_mfma_f32_16x16x32_bf16 v[38:41], v[146:149], v[190:193], 0
	v_mfma_f32_16x16x32_bf16 v[38:41], v[150:153], v[202:205], v[38:41]
	v_mfma_f32_16x16x32_bf16 v[42:45], v[138:141], v[190:193], 0
	v_mfma_f32_16x16x32_bf16 v[42:45], v[142:145], v[202:205], v[42:45]
	v_mfma_f32_16x16x32_bf16 v[46:49], v[130:133], v[190:193], 0
	v_mfma_f32_16x16x32_bf16 v[46:49], v[134:137], v[202:205], v[46:49]
	v_mfma_f32_16x16x32_bf16 v[34:37], v[130:133], v[206:209], 0
	v_mfma_f32_16x16x32_bf16 v[34:37], v[134:137], v[210:213], v[34:37]
	v_mfma_f32_16x16x32_bf16 v[26:29], v[138:141], v[206:209], 0
	v_mfma_f32_16x16x32_bf16 v[26:29], v[142:145], v[210:213], v[26:29]
	v_mfma_f32_16x16x32_bf16 v[22:25], v[146:149], v[206:209], 0
	v_mfma_f32_16x16x32_bf16 v[22:25], v[150:153], v[210:213], v[22:25]
	v_mfma_f32_16x16x32_bf16 v[14:17], v[154:157], v[206:209], 0
	v_mfma_f32_16x16x32_bf16 v[14:17], v[158:161], v[210:213], v[14:17]
	v_mfma_f32_16x16x32_bf16 v[2:5], v[154:157], v[214:217], 0
	v_mfma_f32_16x16x32_bf16 v[2:5], v[158:161], v[240:243], v[2:5]
	v_mfma_f32_16x16x32_bf16 v[6:9], v[146:149], v[214:217], 0
	v_mfma_f32_16x16x32_bf16 v[6:9], v[150:153], v[240:243], v[6:9]
	v_mfma_f32_16x16x32_bf16 v[10:13], v[138:141], v[214:217], 0
	v_mfma_f32_16x16x32_bf16 v[10:13], v[142:145], v[240:243], v[10:13]
	v_mfma_f32_16x16x32_bf16 v[18:21], v[130:133], v[214:217], 0
	v_mfma_f32_16x16x32_bf16 v[18:21], v[134:137], v[240:243], v[18:21]
	s_barrier
; #define PG8_STAGE(bufoff, gbase, voff) do { _Pragma("unroll") for (int _i = 0; _i < 2; ++_i) { \
;         const unsigned _m0 = ldsb + (unsigned)((bufoff) + _i * 8192); const char* _gb = (const char*)(gbase); \
;         asm volatile("s_mov_b32 m0, %0\n\ts_nop 0\n\tglobal_load_lds_dwordx4 %1, %2" :: "s"(_m0), "v"((voff)[_i]), "s"(_gb) : "m0", "memory"); } } while (0)
; #define PG8_LDA(dst, b, h) do { _Pragma("unroll") for (int m = 0; m < 4; ++m) _Pragma("unroll") for (int k = 0; k < 2; ++k) dst[m][k] = *(const LAS bf16x8*)(lds + PG8_SA(b, h) + aoff + m * 2048 + k * 1024); } while (0)
; #define PG8_LDB(dst, b, h) do { _Pragma("unroll") for (int n = 0; n < 2; ++n) _Pragma("unroll") for (int k = 0; k < 2; ++k) dst[n][k] = *(const LAS bf16x8*)(lds + PG8_SB(b, h) + boff + n * 2048 + k * 1024); } while (0)
; #define PG8_MMA(ai, bj, At, Bt) do { __builtin_amdgcn_s_setprio(1); _Pragma("unroll") for (int m = 0; m < 4; ++m) _Pragma("unroll") for (int n = 0; n < 2; ++n) _Pragma("unroll") for (int k = 0; k < 2; ++k) \
;         acc[ai][bj][m][n] = __builtin_amdgcn_mfma_f32_16x16x32_bf16(Bt[n][k], At[m][k], acc[ai][bj][m][n], 0, 0, 0); __builtin_amdgcn_s_setprio(0); } while (0)
; #define PG8_WAIT_V(n) asm volatile("s_waitcnt vmcnt(" #n ")" ::: "memory")
; #define PG8_WAIT_L(n) asm volatile("s_waitcnt lgkmcnt(" #n ")" ::: "memory")
; #define PG8_BAR __builtin_amdgcn_s_barrier()
; #define PG8_SCHED __builtin_amdgcn_sched_barrier(0)
; template <class Epi, bool ALIGN_EPI>
; __device__ __forceinline__ void gemm_phase(LAS unsigned char* lds, const Gemm g, const StaticOrder& S, const Epi& E) {
;     ...
;             PG8_LDB(B0, 1, 0); PG8_LDB(B1, 1, 1); PG8_SCHED; PG8_LDA(At, 1, 0); PG8_STAGE(PG8_SA(0, 1), a2 + hstepA, voffA);
;             PG8_WAIT_V(8); PG8_WAIT_L(0); PG8_BAR; PG8_MMA(0, 0, At, B0); PG8_MMA(0, 1, At, B1); PG8_BAR; PG8_SCHED;
;             PG8_LDA(At, 1, 1); PG8_STAGE(PG8_SB(1, 0), b3, voffB); PG8_STAGE(PG8_SB(1, 1), b3 + hstepB, voffB); PG8_STAGE(PG8_SA(1, 0), a3, voffA);
;             PG8_WAIT_V(8); PG8_WAIT_L(0); PG8_BAR; PG8_MMA(1, 0, At, B0); PG8_MMA(1, 1, At, B1); PG8_BAR; PG8_SCHED;
	s_setprio 0
	v_add_u32_e32 v0, 0x18000, v179
	ds_read_b128 v[130:133], v0
	ds_read_b128 v[134:137], v0 offset:1024
	ds_read_b128 v[138:141], v0 offset:2048
	ds_read_b128 v[142:145], v0 offset:3072
	v_add_u32_e32 v0, 0x1c000, v179
	ds_read_b128 v[146:149], v0
	ds_read_b128 v[150:153], v0 offset:1024
	ds_read_b128 v[154:157], v0 offset:2048
	ds_read_b128 v[158:161], v0 offset:3072
	ds_read_b128 v[182:185], v180 offset:32768
	ds_read_b128 v[186:189], v180 offset:33792
	ds_read_b128 v[190:193], v180 offset:34816
	ds_read_b128 v[202:205], v180 offset:35840
	ds_read_b128 v[206:209], v180 offset:36864
	ds_read_b128 v[210:213], v180 offset:37888
	ds_read_b128 v[214:217], v180 offset:38912
	ds_read_b128 v[240:243], v180 offset:39936
	s_add_u32 s60, s60, 0x40000
	s_addc_u32 s61, s61, 0
	s_mov_b32 m0, s65
	s_nop 0
	global_load_lds_dwordx4 v165, s[60:61]
	s_nop 0
	s_mov_b32 m0, s67
	s_nop 0
	global_load_lds_dwordx4 v171, s[60:61]
	s_waitcnt vmcnt(8)
	s_waitcnt lgkmcnt(0)
	s_setprio 1
	s_barrier
	v_mfma_f32_16x16x32_bf16 v[126:129], v[130:133], v[182:185], v[126:129]
	v_mfma_f32_16x16x32_bf16 v[126:129], v[134:137], v[186:189], v[126:129]
	v_mfma_f32_16x16x32_bf16 v[122:125], v[138:141], v[182:185], v[122:125]
	v_mfma_f32_16x16x32_bf16 v[122:125], v[142:145], v[186:189], v[122:125]
	v_mfma_f32_16x16x32_bf16 v[118:121], v[146:149], v[182:185], v[118:121]
	v_mfma_f32_16x16x32_bf16 v[118:121], v[150:153], v[186:189], v[118:121]
	v_mfma_f32_16x16x32_bf16 v[110:113], v[154:157], v[182:185], v[110:113]
	v_mfma_f32_16x16x32_bf16 v[110:113], v[158:161], v[186:189], v[110:113]
	v_mfma_f32_16x16x32_bf16 v[94:97], v[154:157], v[190:193], v[94:97]
	v_mfma_f32_16x16x32_bf16 v[94:97], v[158:161], v[202:205], v[94:97]
	v_mfma_f32_16x16x32_bf16 v[102:105], v[146:149], v[190:193], v[102:105]
	v_mfma_f32_16x16x32_bf16 v[102:105], v[150:153], v[202:205], v[102:105]
	v_mfma_f32_16x16x32_bf16 v[106:109], v[138:141], v[190:193], v[106:109]
	v_mfma_f32_16x16x32_bf16 v[106:109], v[142:145], v[202:205], v[106:109]
	v_mfma_f32_16x16x32_bf16 v[114:117], v[130:133], v[190:193], v[114:117]
	v_mfma_f32_16x16x32_bf16 v[114:117], v[134:137], v[202:205], v[114:117]
	v_mfma_f32_16x16x32_bf16 v[98:101], v[130:133], v[206:209], v[98:101]
	v_mfma_f32_16x16x32_bf16 v[98:101], v[134:137], v[210:213], v[98:101]
	v_mfma_f32_16x16x32_bf16 v[90:93], v[138:141], v[206:209], v[90:93]
	v_mfma_f32_16x16x32_bf16 v[90:93], v[142:145], v[210:213], v[90:93]
	v_mfma_f32_16x16x32_bf16 v[86:89], v[146:149], v[206:209], v[86:89]
	v_mfma_f32_16x16x32_bf16 v[86:89], v[150:153], v[210:213], v[86:89]
	v_mfma_f32_16x16x32_bf16 v[78:81], v[154:157], v[206:209], v[78:81]
	v_mfma_f32_16x16x32_bf16 v[78:81], v[158:161], v[210:213], v[78:81]
	v_mfma_f32_16x16x32_bf16 v[66:69], v[154:157], v[214:217], v[66:69]
	v_mfma_f32_16x16x32_bf16 v[66:69], v[158:161], v[240:243], v[66:69]
	v_mfma_f32_16x16x32_bf16 v[70:73], v[146:149], v[214:217], v[70:73]
	v_mfma_f32_16x16x32_bf16 v[70:73], v[150:153], v[240:243], v[70:73]
	v_mfma_f32_16x16x32_bf16 v[74:77], v[138:141], v[214:217], v[74:77]
	v_mfma_f32_16x16x32_bf16 v[74:77], v[142:145], v[240:243], v[74:77]
	v_mfma_f32_16x16x32_bf16 v[82:85], v[130:133], v[214:217], v[82:85]
	v_mfma_f32_16x16x32_bf16 v[82:85], v[134:137], v[240:243], v[82:85]
	s_barrier
	s_setprio 0
	ds_read_b128 v[182:185], v180 offset:49152
	ds_read_b128 v[186:189], v180 offset:50176
	ds_read_b128 v[190:193], v180 offset:51200
	ds_read_b128 v[202:205], v180 offset:52224
	ds_read_b128 v[206:209], v180 offset:53248
	ds_read_b128 v[210:213], v180 offset:54272
	ds_read_b128 v[214:217], v180 offset:55296
	ds_read_b128 v[240:243], v180 offset:56320
	s_add_u32 s58, s58, 0x80
	s_addc_u32 s59, s59, 0
	s_mov_b32 m0, s89
	s_nop 0
	global_load_lds_dwordx4 v167, s[58:59]
	s_add_u32 s44, s44, 0x80
	s_mov_b32 m0, s95
	s_nop 0
	global_load_lds_dwordx4 v175, s[58:59]
	s_addc_u32 s45, s45, 0
	s_mov_b32 m0, s26
	s_nop 0
	global_load_lds_dwordx4 v167, s[44:45]
	s_nop 0
	s_mov_b32 m0, s27
	s_nop 0
	global_load_lds_dwordx4 v175, s[44:45]
	s_nop 0
	s_mov_b32 m0, s36
	s_nop 0
	global_load_lds_dwordx4 v165, s[56:57]
	s_nop 0
	s_mov_b32 m0, s37
	s_nop 0
	global_load_lds_dwordx4 v171, s[56:57]
	s_waitcnt vmcnt(8)
	s_waitcnt lgkmcnt(0)
	s_setprio 1
	s_barrier
	v_mfma_f32_16x16x32_bf16 v[62:65], v[130:133], v[182:185], v[62:65]
	v_mfma_f32_16x16x32_bf16 v[62:65], v[134:137], v[186:189], v[62:65]
	v_mfma_f32_16x16x32_bf16 v[58:61], v[138:141], v[182:185], v[58:61]
	v_mfma_f32_16x16x32_bf16 v[58:61], v[142:145], v[186:189], v[58:61]
	v_mfma_f32_16x16x32_bf16 v[54:57], v[146:149], v[182:185], v[54:57]
	v_mfma_f32_16x16x32_bf16 v[54:57], v[150:153], v[186:189], v[54:57]
	v_mfma_f32_16x16x32_bf16 v[50:53], v[154:157], v[182:185], v[50:53]
	v_mfma_f32_16x16x32_bf16 v[50:53], v[158:161], v[186:189], v[50:53]
	v_mfma_f32_16x16x32_bf16 v[30:33], v[154:157], v[190:193], v[30:33]
	v_mfma_f32_16x16x32_bf16 v[30:33], v[158:161], v[202:205], v[30:33]
	v_mfma_f32_16x16x32_bf16 v[38:41], v[146:149], v[190:193], v[38:41]
	v_mfma_f32_16x16x32_bf16 v[38:41], v[150:153], v[202:205], v[38:41]
	v_mfma_f32_16x16x32_bf16 v[42:45], v[138:141], v[190:193], v[42:45]
	v_mfma_f32_16x16x32_bf16 v[42:45], v[142:145], v[202:205], v[42:45]
	v_mfma_f32_16x16x32_bf16 v[46:49], v[130:133], v[190:193], v[46:49]
	v_mfma_f32_16x16x32_bf16 v[46:49], v[134:137], v[202:205], v[46:49]
	v_mfma_f32_16x16x32_bf16 v[34:37], v[130:133], v[206:209], v[34:37]
	v_mfma_f32_16x16x32_bf16 v[34:37], v[134:137], v[210:213], v[34:37]
	v_mfma_f32_16x16x32_bf16 v[26:29], v[138:141], v[206:209], v[26:29]
	v_mfma_f32_16x16x32_bf16 v[26:29], v[142:145], v[210:213], v[26:29]
	v_mfma_f32_16x16x32_bf16 v[22:25], v[146:149], v[206:209], v[22:25]
	v_mfma_f32_16x16x32_bf16 v[22:25], v[150:153], v[210:213], v[22:25]
	v_mfma_f32_16x16x32_bf16 v[14:17], v[154:157], v[206:209], v[14:17]
	v_mfma_f32_16x16x32_bf16 v[14:17], v[158:161], v[210:213], v[14:17]
	v_mfma_f32_16x16x32_bf16 v[2:5], v[154:157], v[214:217], v[2:5]
	v_mfma_f32_16x16x32_bf16 v[2:5], v[158:161], v[240:243], v[2:5]
	v_mfma_f32_16x16x32_bf16 v[6:9], v[146:149], v[214:217], v[6:9]
	v_mfma_f32_16x16x32_bf16 v[6:9], v[150:153], v[240:243], v[6:9]
	v_mfma_f32_16x16x32_bf16 v[10:13], v[138:141], v[214:217], v[10:13]
	v_mfma_f32_16x16x32_bf16 v[10:13], v[142:145], v[240:243], v[10:13]
	v_mfma_f32_16x16x32_bf16 v[18:21], v[130:133], v[214:217], v[18:21]
	v_mfma_f32_16x16x32_bf16 v[18:21], v[134:137], v[240:243], v[18:21]
	s_barrier
	s_setprio 0
	s_add_u32 s4, s4, 0x100
	s_addc_u32 s5, s5, 0
	s_add_u32 s0, s0, 0x100
	s_addc_u32 s1, s1, 0
	s_cmp_ge_u32 s55, s31
	s_mov_b32 s44, s55
; #define PG8_STAGE(bufoff, gbase, voff) do { _Pragma("unroll") for (int _i = 0; _i < 2; ++_i) { \
;         const unsigned _m0 = ldsb + (unsigned)((bufoff) + _i * 8192); const char* _gb = (const char*)(gbase); \
;         asm volatile("s_mov_b32 m0, %0\n\ts_nop 0\n\tglobal_load_lds_dwordx4 %1, %2" :: "s"(_m0), "v"((voff)[_i]), "s"(_gb) : "m0", "memory"); } } while (0)
; #define PG8_LDA(dst, b, h) do { _Pragma("unroll") for (int m = 0; m < 4; ++m) _Pragma("unroll") for (int k = 0; k < 2; ++k) dst[m][k] = *(const LAS bf16x8*)(lds + PG8_SA(b, h) + aoff + m * 2048 + k * 1024); } while (0)
; #define PG8_LDB(dst, b, h) do { _Pragma("unroll") for (int n = 0; n < 2; ++n) _Pragma("unroll") for (int k = 0; k < 2; ++k) dst[n][k] = *(const LAS bf16x8*)(lds + PG8_SB(b, h) + boff + n * 2048 + k * 1024); } while (0)
; template <class Epi, bool ALIGN_EPI>
; __device__ __forceinline__ void gemm_phase(LAS unsigned char* lds, const Gemm g, const StaticOrder& S, const Epi& E) {
;     ...
;         for (int t = 0; t < nt; t += 2) {
;             const bool last = (t == nt - 2);
;             const char* a1 = cA + (size_t)(t + 1) * kstep;
;             const char* a2 = last ? nA : cA + (size_t)(t + 2) * kstep; const char* b2 = last ? nB : cB + (size_t)(t + 2) * kstep;
;             const char* a3 = a2 + kstep; const char* b3 = b2 + kstep;
;             PG8_LDB(B0, 0, 0); PG8_LDB(B1, 0, 1); PG8_SCHED; PG8_LDA(At, 0, 0); PG8_STAGE(PG8_SA(1, 1), a1 + hstepA, voffA);
;             PG8_WAIT_V(8); PG8_WAIT_L(0); PG8_BAR; PG8_MMA(0, 0, At, B0); PG8_MMA(0, 1, At, B1); PG8_BAR; PG8_SCHED;
;             PG8_LDA(At, 0, 1); PG8_STAGE(PG8_SB(0, 0), b2, voffB); PG8_STAGE(PG8_SB(0, 1), b2 + hstepB, voffB); PG8_STAGE(PG8_SA(0, 0), a2, voffA);
;             PG8_WAIT_V(8); PG8_WAIT_L(0); PG8_BAR; PG8_MMA(1, 0, At, B0); PG8_MMA(1, 1, At, B1); PG8_BAR; PG8_SCHED;
;             PG8_LDB(B0, 1, 0); PG8_LDB(B1, 1, 1); PG8_SCHED; PG8_LDA(At, 1, 0); PG8_STAGE(PG8_SA(0, 1), a2 + hstepA, voffA);
;             PG8_WAIT_V(8); PG8_WAIT_L(0); PG8_BAR; PG8_MMA(0, 0, At, B0); PG8_MMA(0, 1, At, B1); PG8_BAR; PG8_SCHED;
;             PG8_LDA(At, 1, 1); PG8_STAGE(PG8_SB(1, 0), b3, voffB); PG8_STAGE(PG8_SB(1, 1), b3 + hstepB, voffB); PG8_STAGE(PG8_SA(1, 0), a3, voffA);
;             PG8_WAIT_V(8); PG8_WAIT_L(0); PG8_BAR; PG8_MMA(1, 0, At, B0); PG8_MMA(1, 1, At, B1); PG8_BAR; PG8_SCHED;
.LBB0_271:
	v_add_u32_e32 v0, 0x10000, v179
	ds_read_b128 v[130:133], v0
	ds_read_b128 v[134:137], v0 offset:1024
	ds_read_b128 v[138:141], v0 offset:2048
	ds_read_b128 v[142:145], v0 offset:3072
	v_add_u32_e32 v0, 0x14000, v179
	ds_read_b128 v[146:149], v0
	ds_read_b128 v[150:153], v0 offset:1024
	ds_read_b128 v[154:157], v0 offset:2048
	ds_read_b128 v[158:161], v0 offset:3072
	s_add_i32 s55, s44, 2
	s_add_u32 s45, s0, 0xfffc0080
	s_addc_u32 s56, s1, -1
	s_cmp_eq_u32 s68, s44
	s_cselect_b32 s60, s96, s45
	s_cselect_b32 s61, s97, s56
	s_cselect_b32 s58, s48, s4
	s_cselect_b32 s59, s49, s5
	s_add_u32 s56, s60, 0x80
	s_addc_u32 s57, s61, 0
	ds_read_b128 v[182:185], v180
	ds_read_b128 v[186:189], v180 offset:1024
	ds_read_b128 v[190:193], v180 offset:2048
	ds_read_b128 v[202:205], v180 offset:3072
	ds_read_b128 v[206:209], v180 offset:4096
	ds_read_b128 v[210:213], v180 offset:5120
	ds_read_b128 v[214:217], v180 offset:6144
	ds_read_b128 v[240:243], v180 offset:7168
	s_mov_b32 m0, s41
	s_nop 0
	global_load_lds_dwordx4 v165, s[0:1]
	s_nop 0
	s_mov_b32 m0, s30
	s_nop 0
	global_load_lds_dwordx4 v171, s[0:1]
	s_waitcnt vmcnt(8)
	s_waitcnt lgkmcnt(0)
	s_setprio 1
	s_barrier
	v_mfma_f32_16x16x32_bf16 v[126:129], v[130:133], v[182:185], v[126:129]
	v_mfma_f32_16x16x32_bf16 v[126:129], v[134:137], v[186:189], v[126:129]
	v_mfma_f32_16x16x32_bf16 v[122:125], v[138:141], v[182:185], v[122:125]
	v_mfma_f32_16x16x32_bf16 v[122:125], v[142:145], v[186:189], v[122:125]
	v_mfma_f32_16x16x32_bf16 v[118:121], v[146:149], v[182:185], v[118:121]
	v_mfma_f32_16x16x32_bf16 v[118:121], v[150:153], v[186:189], v[118:121]
	v_mfma_f32_16x16x32_bf16 v[110:113], v[154:157], v[182:185], v[110:113]
	v_mfma_f32_16x16x32_bf16 v[110:113], v[158:161], v[186:189], v[110:113]
	v_mfma_f32_16x16x32_bf16 v[94:97], v[154:157], v[190:193], v[94:97]
	v_mfma_f32_16x16x32_bf16 v[94:97], v[158:161], v[202:205], v[94:97]
	v_mfma_f32_16x16x32_bf16 v[102:105], v[146:149], v[190:193], v[102:105]
	v_mfma_f32_16x16x32_bf16 v[102:105], v[150:153], v[202:205], v[102:105]
	v_mfma_f32_16x16x32_bf16 v[106:109], v[138:141], v[190:193], v[106:109]
	v_mfma_f32_16x16x32_bf16 v[106:109], v[142:145], v[202:205], v[106:109]
	v_mfma_f32_16x16x32_bf16 v[114:117], v[130:133], v[190:193], v[114:117]
	v_mfma_f32_16x16x32_bf16 v[114:117], v[134:137], v[202:205], v[114:117]
	v_mfma_f32_16x16x32_bf16 v[98:101], v[130:133], v[206:209], v[98:101]
	v_mfma_f32_16x16x32_bf16 v[98:101], v[134:137], v[210:213], v[98:101]
	v_mfma_f32_16x16x32_bf16 v[90:93], v[138:141], v[206:209], v[90:93]
	v_mfma_f32_16x16x32_bf16 v[90:93], v[142:145], v[210:213], v[90:93]
	v_mfma_f32_16x16x32_bf16 v[86:89], v[146:149], v[206:209], v[86:89]
	v_mfma_f32_16x16x32_bf16 v[86:89], v[150:153], v[210:213], v[86:89]
	v_mfma_f32_16x16x32_bf16 v[78:81], v[154:157], v[206:209], v[78:81]
	v_mfma_f32_16x16x32_bf16 v[78:81], v[158:161], v[210:213], v[78:81]
	v_mfma_f32_16x16x32_bf16 v[66:69], v[154:157], v[214:217], v[66:69]
	v_mfma_f32_16x16x32_bf16 v[66:69], v[158:161], v[240:243], v[66:69]
	v_mfma_f32_16x16x32_bf16 v[70:73], v[146:149], v[214:217], v[70:73]
	v_mfma_f32_16x16x32_bf16 v[70:73], v[150:153], v[240:243], v[70:73]
	v_mfma_f32_16x16x32_bf16 v[74:77], v[138:141], v[214:217], v[74:77]
	v_mfma_f32_16x16x32_bf16 v[74:77], v[142:145], v[240:243], v[74:77]
	v_mfma_f32_16x16x32_bf16 v[82:85], v[130:133], v[214:217], v[82:85]
	v_mfma_f32_16x16x32_bf16 v[82:85], v[134:137], v[240:243], v[82:85]
	s_barrier
	s_setprio 0
	ds_read_b128 v[182:185], v180 offset:16384
	ds_read_b128 v[186:189], v180 offset:17408
	ds_read_b128 v[190:193], v180 offset:18432
	ds_read_b128 v[202:205], v180 offset:19456
	ds_read_b128 v[206:209], v180 offset:20480
	ds_read_b128 v[210:213], v180 offset:21504
	ds_read_b128 v[214:217], v180 offset:22528
	ds_read_b128 v[240:243], v180 offset:23552
	s_mov_b32 m0, s42
	s_nop 0
	global_load_lds_dwordx4 v167, s[58:59]
	s_add_u32 s44, s58, s14
	s_mov_b32 m0, s43
	s_nop 0
	global_load_lds_dwordx4 v175, s[58:59]
	s_addc_u32 s45, s59, 0
	s_mov_b32 m0, s46
	s_nop 0
	global_load_lds_dwordx4 v167, s[44:45]
	s_nop 0
	s_mov_b32 m0, s50
	s_nop 0
	global_load_lds_dwordx4 v175, s[44:45]
	s_nop 0
	s_mov_b32 m0, s17
	s_nop 0
	global_load_lds_dwordx4 v165, s[60:61]
	s_nop 0
	s_mov_b32 m0, s53
	s_nop 0
	global_load_lds_dwordx4 v171, s[60:61]
	s_waitcnt vmcnt(8)
	s_waitcnt lgkmcnt(0)
	s_setprio 1
	s_barrier
	v_mfma_f32_16x16x32_bf16 v[62:65], v[130:133], v[182:185], v[62:65]
	v_mfma_f32_16x16x32_bf16 v[62:65], v[134:137], v[186:189], v[62:65]
	v_mfma_f32_16x16x32_bf16 v[58:61], v[138:141], v[182:185], v[58:61]
	v_mfma_f32_16x16x32_bf16 v[58:61], v[142:145], v[186:189], v[58:61]
	v_mfma_f32_16x16x32_bf16 v[54:57], v[146:149], v[182:185], v[54:57]
	v_mfma_f32_16x16x32_bf16 v[54:57], v[150:153], v[186:189], v[54:57]
	v_mfma_f32_16x16x32_bf16 v[50:53], v[154:157], v[182:185], v[50:53]
	v_mfma_f32_16x16x32_bf16 v[50:53], v[158:161], v[186:189], v[50:53]
	v_mfma_f32_16x16x32_bf16 v[30:33], v[154:157], v[190:193], v[30:33]
	v_mfma_f32_16x16x32_bf16 v[30:33], v[158:161], v[202:205], v[30:33]
	v_mfma_f32_16x16x32_bf16 v[38:41], v[146:149], v[190:193], v[38:41]
	v_mfma_f32_16x16x32_bf16 v[38:41], v[150:153], v[202:205], v[38:41]
	v_mfma_f32_16x16x32_bf16 v[42:45], v[138:141], v[190:193], v[42:45]
	v_mfma_f32_16x16x32_bf16 v[42:45], v[142:145], v[202:205], v[42:45]
	v_mfma_f32_16x16x32_bf16 v[46:49], v[130:133], v[190:193], v[46:49]
	v_mfma_f32_16x16x32_bf16 v[46:49], v[134:137], v[202:205], v[46:49]
	v_mfma_f32_16x16x32_bf16 v[34:37], v[130:133], v[206:209], v[34:37]
	v_mfma_f32_16x16x32_bf16 v[34:37], v[134:137], v[210:213], v[34:37]
	v_mfma_f32_16x16x32_bf16 v[26:29], v[138:141], v[206:209], v[26:29]
	v_mfma_f32_16x16x32_bf16 v[26:29], v[142:145], v[210:213], v[26:29]
	v_mfma_f32_16x16x32_bf16 v[22:25], v[146:149], v[206:209], v[22:25]
	v_mfma_f32_16x16x32_bf16 v[22:25], v[150:153], v[210:213], v[22:25]
	v_mfma_f32_16x16x32_bf16 v[14:17], v[154:157], v[206:209], v[14:17]
	v_mfma_f32_16x16x32_bf16 v[14:17], v[158:161], v[210:213], v[14:17]
	v_mfma_f32_16x16x32_bf16 v[2:5], v[154:157], v[214:217], v[2:5]
	v_mfma_f32_16x16x32_bf16 v[2:5], v[158:161], v[240:243], v[2:5]
	v_mfma_f32_16x16x32_bf16 v[6:9], v[146:149], v[214:217], v[6:9]
	v_mfma_f32_16x16x32_bf16 v[6:9], v[150:153], v[240:243], v[6:9]
	v_mfma_f32_16x16x32_bf16 v[10:13], v[138:141], v[214:217], v[10:13]
	v_mfma_f32_16x16x32_bf16 v[10:13], v[142:145], v[240:243], v[10:13]
	v_mfma_f32_16x16x32_bf16 v[18:21], v[130:133], v[214:217], v[18:21]
	v_mfma_f32_16x16x32_bf16 v[18:21], v[134:137], v[240:243], v[18:21]
	s_barrier
; #define PG8_STAGE(bufoff, gbase, voff) do { _Pragma("unroll") for (int _i = 0; _i < 2; ++_i) { \
;         const unsigned _m0 = ldsb + (unsigned)((bufoff) + _i * 8192); const char* _gb = (const char*)(gbase); \
;         asm volatile("s_mov_b32 m0, %0\n\ts_nop 0\n\tglobal_load_lds_dwordx4 %1, %2" :: "s"(_m0), "v"((voff)[_i]), "s"(_gb) : "m0", "memory"); } } while (0)
; #define PG8_LDA(dst, b, h) do { _Pragma("unroll") for (int m = 0; m < 4; ++m) _Pragma("unroll") for (int k = 0; k < 2; ++k) dst[m][k] = *(const LAS bf16x8*)(lds + PG8_SA(b, h) + aoff + m * 2048 + k * 1024); } while (0)
; #define PG8_LDB(dst, b, h) do { _Pragma("unroll") for (int n = 0; n < 2; ++n) _Pragma("unroll") for (int k = 0; k < 2; ++k) dst[n][k] = *(const LAS bf16x8*)(lds + PG8_SB(b, h) + boff + n * 2048 + k * 1024); } while (0)
; #define PG8_MMA(ai, bj, At, Bt) do { __builtin_amdgcn_s_setprio(1); _Pragma("unroll") for (int m = 0; m < 4; ++m) _Pragma("unroll") for (int n = 0; n < 2; ++n) _Pragma("unroll") for (int k = 0; k < 2; ++k) \
;         acc[ai][bj][m][n] = __builtin_amdgcn_mfma_f32_16x16x32_bf16(Bt[n][k], At[m][k], acc[ai][bj][m][n], 0, 0, 0); __builtin_amdgcn_s_setprio(0); } while (0)
; #define PG8_WAIT_V(n) asm volatile("s_waitcnt vmcnt(" #n ")" ::: "memory")
; #define PG8_WAIT_L(n) asm volatile("s_waitcnt lgkmcnt(" #n ")" ::: "memory")
; #define PG8_BAR __builtin_amdgcn_s_barrier()
; #define PG8_SCHED __builtin_amdgcn_sched_barrier(0)
; template <class Epi, bool ALIGN_EPI>
; __device__ __forceinline__ void gemm_phase(LAS unsigned char* lds, const Gemm g, const StaticOrder& S, const Epi& E) {
;     ...
;             PG8_LDB(B0, 1, 0); PG8_LDB(B1, 1, 1); PG8_SCHED; PG8_LDA(At, 1, 0); PG8_STAGE(PG8_SA(0, 1), a2 + hstepA, voffA);
;             PG8_WAIT_V(8); PG8_WAIT_L(0); PG8_BAR; PG8_MMA(0, 0, At, B0); PG8_MMA(0, 1, At, B1); PG8_BAR; PG8_SCHED;
;             PG8_LDA(At, 1, 1); PG8_STAGE(PG8_SB(1, 0), b3, voffB); PG8_STAGE(PG8_SB(1, 1), b3 + hstepB, voffB); PG8_STAGE(PG8_SA(1, 0), a3, voffA);
;             PG8_WAIT_V(8); PG8_WAIT_L(0); PG8_BAR; PG8_MMA(1, 0, At, B0); PG8_MMA(1, 1, At, B1); PG8_BAR; PG8_SCHED;
;         }
;         if constexpr (ALIGN_EPI) { if (wr == 0) PG8_BAR; }
	s_setprio 0
	v_add_u32_e32 v0, 0x18000, v179
	ds_read_b128 v[130:133], v0
	ds_read_b128 v[134:137], v0 offset:1024
	ds_read_b128 v[138:141], v0 offset:2048
	ds_read_b128 v[142:145], v0 offset:3072
	v_add_u32_e32 v0, 0x1c000, v179
	ds_read_b128 v[146:149], v0
	ds_read_b128 v[150:153], v0 offset:1024
	ds_read_b128 v[154:157], v0 offset:2048
	ds_read_b128 v[158:161], v0 offset:3072
	ds_read_b128 v[182:185], v180 offset:32768
	ds_read_b128 v[186:189], v180 offset:33792
	ds_read_b128 v[190:193], v180 offset:34816
	ds_read_b128 v[202:205], v180 offset:35840
	ds_read_b128 v[206:209], v180 offset:36864
	ds_read_b128 v[210:213], v180 offset:37888
	ds_read_b128 v[214:217], v180 offset:38912
	ds_read_b128 v[240:243], v180 offset:39936
	s_add_u32 s60, s60, 0x40000
	s_addc_u32 s61, s61, 0
	s_mov_b32 m0, s65
	s_nop 0
	global_load_lds_dwordx4 v165, s[60:61]
	s_nop 0
	s_mov_b32 m0, s67
	s_nop 0
	global_load_lds_dwordx4 v171, s[60:61]
	s_waitcnt vmcnt(8)
	s_waitcnt lgkmcnt(0)
	s_setprio 1
	s_barrier
	v_mfma_f32_16x16x32_bf16 v[126:129], v[130:133], v[182:185], v[126:129]
	v_mfma_f32_16x16x32_bf16 v[126:129], v[134:137], v[186:189], v[126:129]
	v_mfma_f32_16x16x32_bf16 v[122:125], v[138:141], v[182:185], v[122:125]
	v_mfma_f32_16x16x32_bf16 v[122:125], v[142:145], v[186:189], v[122:125]
	v_mfma_f32_16x16x32_bf16 v[118:121], v[146:149], v[182:185], v[118:121]
	v_mfma_f32_16x16x32_bf16 v[118:121], v[150:153], v[186:189], v[118:121]
	v_mfma_f32_16x16x32_bf16 v[110:113], v[154:157], v[182:185], v[110:113]
	v_mfma_f32_16x16x32_bf16 v[110:113], v[158:161], v[186:189], v[110:113]
	v_mfma_f32_16x16x32_bf16 v[94:97], v[154:157], v[190:193], v[94:97]
	v_mfma_f32_16x16x32_bf16 v[94:97], v[158:161], v[202:205], v[94:97]
	v_mfma_f32_16x16x32_bf16 v[102:105], v[146:149], v[190:193], v[102:105]
	v_mfma_f32_16x16x32_bf16 v[102:105], v[150:153], v[202:205], v[102:105]
	v_mfma_f32_16x16x32_bf16 v[106:109], v[138:141], v[190:193], v[106:109]
	v_mfma_f32_16x16x32_bf16 v[106:109], v[142:145], v[202:205], v[106:109]
	v_mfma_f32_16x16x32_bf16 v[114:117], v[130:133], v[190:193], v[114:117]
	v_mfma_f32_16x16x32_bf16 v[114:117], v[134:137], v[202:205], v[114:117]
	v_mfma_f32_16x16x32_bf16 v[98:101], v[130:133], v[206:209], v[98:101]
	v_mfma_f32_16x16x32_bf16 v[98:101], v[134:137], v[210:213], v[98:101]
	v_mfma_f32_16x16x32_bf16 v[90:93], v[138:141], v[206:209], v[90:93]
	v_mfma_f32_16x16x32_bf16 v[90:93], v[142:145], v[210:213], v[90:93]
	v_mfma_f32_16x16x32_bf16 v[86:89], v[146:149], v[206:209], v[86:89]
	v_mfma_f32_16x16x32_bf16 v[86:89], v[150:153], v[210:213], v[86:89]
	v_mfma_f32_16x16x32_bf16 v[78:81], v[154:157], v[206:209], v[78:81]
	v_mfma_f32_16x16x32_bf16 v[78:81], v[158:161], v[210:213], v[78:81]
	v_mfma_f32_16x16x32_bf16 v[66:69], v[154:157], v[214:217], v[66:69]
	v_mfma_f32_16x16x32_bf16 v[66:69], v[158:161], v[240:243], v[66:69]
	v_mfma_f32_16x16x32_bf16 v[70:73], v[146:149], v[214:217], v[70:73]
	v_mfma_f32_16x16x32_bf16 v[70:73], v[150:153], v[240:243], v[70:73]
	v_mfma_f32_16x16x32_bf16 v[74:77], v[138:141], v[214:217], v[74:77]
	v_mfma_f32_16x16x32_bf16 v[74:77], v[142:145], v[240:243], v[74:77]
	v_mfma_f32_16x16x32_bf16 v[82:85], v[130:133], v[214:217], v[82:85]
	v_mfma_f32_16x16x32_bf16 v[82:85], v[134:137], v[240:243], v[82:85]
	s_barrier
	s_setprio 0
	ds_read_b128 v[182:185], v180 offset:49152
	ds_read_b128 v[186:189], v180 offset:50176
	ds_read_b128 v[190:193], v180 offset:51200
	ds_read_b128 v[202:205], v180 offset:52224
	ds_read_b128 v[206:209], v180 offset:53248
	ds_read_b128 v[210:213], v180 offset:54272
	ds_read_b128 v[214:217], v180 offset:55296
	ds_read_b128 v[240:243], v180 offset:56320
	s_add_u32 s58, s58, 0x80
	s_addc_u32 s59, s59, 0
	s_mov_b32 m0, s89
	s_nop 0
	global_load_lds_dwordx4 v167, s[58:59]
	s_add_u32 s44, s44, 0x80
	s_mov_b32 m0, s95
	s_nop 0
	global_load_lds_dwordx4 v175, s[58:59]
	s_addc_u32 s45, s45, 0
	s_mov_b32 m0, s26
	s_nop 0
	global_load_lds_dwordx4 v167, s[44:45]
	s_nop 0
	s_mov_b32 m0, s27
	s_nop 0
	global_load_lds_dwordx4 v175, s[44:45]
	s_nop 0
	s_mov_b32 m0, s36
	s_nop 0
	global_load_lds_dwordx4 v165, s[56:57]
	s_nop 0
	s_mov_b32 m0, s37
	s_nop 0
	global_load_lds_dwordx4 v171, s[56:57]
	s_waitcnt vmcnt(8)
	s_waitcnt lgkmcnt(0)
	s_setprio 1
	s_barrier
	v_mfma_f32_16x16x32_bf16 v[62:65], v[130:133], v[182:185], v[62:65]
	v_mfma_f32_16x16x32_bf16 v[62:65], v[134:137], v[186:189], v[62:65]
	v_mfma_f32_16x16x32_bf16 v[58:61], v[138:141], v[182:185], v[58:61]
	v_mfma_f32_16x16x32_bf16 v[58:61], v[142:145], v[186:189], v[58:61]
	v_mfma_f32_16x16x32_bf16 v[54:57], v[146:149], v[182:185], v[54:57]
	v_mfma_f32_16x16x32_bf16 v[54:57], v[150:153], v[186:189], v[54:57]
	v_mfma_f32_16x16x32_bf16 v[50:53], v[154:157], v[182:185], v[50:53]
	v_mfma_f32_16x16x32_bf16 v[50:53], v[158:161], v[186:189], v[50:53]
	v_mfma_f32_16x16x32_bf16 v[30:33], v[154:157], v[190:193], v[30:33]
	v_mfma_f32_16x16x32_bf16 v[30:33], v[158:161], v[202:205], v[30:33]
	v_mfma_f32_16x16x32_bf16 v[38:41], v[146:149], v[190:193], v[38:41]
	v_mfma_f32_16x16x32_bf16 v[38:41], v[150:153], v[202:205], v[38:41]
	v_mfma_f32_16x16x32_bf16 v[42:45], v[138:141], v[190:193], v[42:45]
	v_mfma_f32_16x16x32_bf16 v[42:45], v[142:145], v[202:205], v[42:45]
	v_mfma_f32_16x16x32_bf16 v[46:49], v[130:133], v[190:193], v[46:49]
	v_mfma_f32_16x16x32_bf16 v[46:49], v[134:137], v[202:205], v[46:49]
	v_mfma_f32_16x16x32_bf16 v[34:37], v[130:133], v[206:209], v[34:37]
	v_mfma_f32_16x16x32_bf16 v[34:37], v[134:137], v[210:213], v[34:37]
	v_mfma_f32_16x16x32_bf16 v[26:29], v[138:141], v[206:209], v[26:29]
	v_mfma_f32_16x16x32_bf16 v[26:29], v[142:145], v[210:213], v[26:29]
	v_mfma_f32_16x16x32_bf16 v[22:25], v[146:149], v[206:209], v[22:25]
	v_mfma_f32_16x16x32_bf16 v[22:25], v[150:153], v[210:213], v[22:25]
	v_mfma_f32_16x16x32_bf16 v[14:17], v[154:157], v[206:209], v[14:17]
	v_mfma_f32_16x16x32_bf16 v[14:17], v[158:161], v[210:213], v[14:17]
	v_mfma_f32_16x16x32_bf16 v[2:5], v[154:157], v[214:217], v[2:5]
	v_mfma_f32_16x16x32_bf16 v[2:5], v[158:161], v[240:243], v[2:5]
	v_mfma_f32_16x16x32_bf16 v[6:9], v[146:149], v[214:217], v[6:9]
	v_mfma_f32_16x16x32_bf16 v[6:9], v[150:153], v[240:243], v[6:9]
	v_mfma_f32_16x16x32_bf16 v[10:13], v[138:141], v[214:217], v[10:13]
	v_mfma_f32_16x16x32_bf16 v[10:13], v[142:145], v[240:243], v[10:13]
	v_mfma_f32_16x16x32_bf16 v[18:21], v[130:133], v[214:217], v[18:21]
	v_mfma_f32_16x16x32_bf16 v[18:21], v[134:137], v[240:243], v[18:21]
	s_barrier
	s_setprio 0
	s_add_u32 s4, s4, 0x100
	s_addc_u32 s5, s5, 0
	s_add_u32 s0, s0, 0x100
	s_addc_u32 s1, s1, 0
	s_cmp_ge_u32 s55, s31
	s_mov_b32 s44, s55
	s_cbranch_scc0 .LBB0_271
	v_readlane_b32 s0, v254, 44
	v_readlane_b32 s1, v254, 45
	s_and_b64 vcc, exec, s[0:1]
	s_cbranch_vccz .LBB0_274
	s_barrier

; #define PG8_LDA(dst, b, h) do { _Pragma("unroll") for (int m = 0; m < 4; ++m) _Pragma("unroll") for (int k = 0; k < 2; ++k) dst[m][k] = *(const LAS bf16x8*)(lds + PG8_SA(b, h) + aoff + m * 2048 + k * 1024); } while (0)
; #define PG8_WAIT_V(n) asm volatile("s_waitcnt vmcnt(" #n ")" ::: "memory")
; #define PG8_BAR __builtin_amdgcn_s_barrier()
;     __device__ bool next(int i, Unit& u) const {
;         const long L = (long)i * G + c; if (L >= nwg) return false;
;         int wgid = (int)L; { const int q = nwg / NXCD, r = nwg % NXCD, xcd = wgid % NXCD, off = wgid / NXCD; wgid = (xcd < r ? xcd * (q + 1) : r * (q + 1) + (xcd - r) * q) + off; }
;         const int nig = WGM * nN, gid = wgid / nig, fm = gid * WGM, gsz = (nM - fm) < WGM ? (nM - fm) : WGM;
;         u.pm = fm + ((wgid % nig) % gsz); u.pn = (wgid % nig) / gsz; return true;
; template <class Epi, bool ALIGN_EPI>
; __device__ __forceinline__ void gemm_phase(LAS unsigned char* lds, const Gemm g, const StaticOrder& S, const Epi& E) {
;     ...
;         for (int t = 0; t < nt; t += 2) {
;             const bool last = (t == nt - 2);
;             const char* a1 = cA + (size_t)(t + 1) * kstep;
;             const char* a2 = last ? nA : cA + (size_t)(t + 2) * kstep; const char* b2 = last ? nB : cB + (size_t)(t + 2) * kstep;
;             const char* a3 = a2 + kstep; const char* b3 = b2 + kstep;
;             PG8_LDB(B0, 0, 0); PG8_LDB(B1, 0, 1); PG8_SCHED; PG8_LDA(At, 0, 0); PG8_STAGE(PG8_SA(1, 1), a1 + hstepA, voffA);
;             PG8_WAIT_V(8); PG8_WAIT_L(0); PG8_BAR; PG8_MMA(0, 0, At, B0); PG8_MMA(0, 1, At, B1); PG8_BAR; PG8_SCHED;
;             PG8_LDA(At, 0, 1); PG8_STAGE(PG8_SB(0, 0), b2, voffB); PG8_STAGE(PG8_SB(0, 1), b2 + hstepB, voffB); PG8_STAGE(PG8_SA(0, 0), a2, voffA);
;             PG8_WAIT_V(8); PG8_WAIT_L(0); PG8_BAR; PG8_MMA(1, 0, At, B0); PG8_MMA(1, 1, At, B1); PG8_BAR; PG8_SCHED;
;             PG8_LDB(B0, 1, 0); PG8_LDB(B1, 1, 1); PG8_SCHED; PG8_LDA(At, 1, 0); PG8_STAGE(PG8_SA(0, 1), a2 + hstepA, voffA);
;             PG8_WAIT_V(8); PG8_WAIT_L(0); PG8_BAR; PG8_MMA(0, 0, At, B0); PG8_MMA(0, 1, At, B1); PG8_BAR; PG8_SCHED;
;             PG8_LDA(At, 1, 1); PG8_STAGE(PG8_SB(1, 0), b3, voffB); PG8_STAGE(PG8_SB(1, 1), b3 + hstepB, voffB); PG8_STAGE(PG8_SA(1, 0), a3, voffA);
;             PG8_WAIT_V(8); PG8_WAIT_L(0); PG8_BAR; PG8_MMA(1, 0, At, B0); PG8_MMA(1, 1, At, B1); PG8_BAR; PG8_SCHED;
.LBB0_305:
	s_add_u32 s41, s56, 0x100
	s_addc_u32 s49, s57, 0
	s_add_u32 s92, s58, 0x40080
	s_addc_u32 s93, s59, 0
	s_mov_b32 s50, -2
	s_add_u32 s30, s92, 0xfffc0080
	s_addc_u32 s31, s93, -1
	s_cmp_eq_u32 s50, 12
	s_cselect_b32 s60, s5, s30
	s_cselect_b32 s61, s4, s31
	s_cselect_b32 s58, s37, s41
	s_cselect_b32 s59, s35, s49
	s_add_u32 s56, s60, 0x80
	s_addc_u32 s57, s61, 0
	s_mov_b32 m0, s67
	s_nop 0
	global_load_lds_dwordx4 v0, s[92:93]
	s_nop 0
	s_mov_b32 m0, s65
	s_nop 0
	global_load_lds_dwordx4 v181, s[92:93]
	s_waitcnt vmcnt(8)
	s_waitcnt lgkmcnt(0)
	s_setprio 1
	s_barrier
	v_mfma_f32_16x16x32_bf16 v[142:145], v[74:77], v[162:165], 0
	v_mfma_f32_16x16x32_bf16 v[142:145], v[94:97], v[166:169], v[142:145]
	v_mfma_f32_16x16x32_bf16 v[138:141], v[114:117], v[162:165], 0
	v_mfma_f32_16x16x32_bf16 v[138:141], v[134:137], v[166:169], v[138:141]
	v_mfma_f32_16x16x32_bf16 v[130:133], v[146:149], v[162:165], 0
	v_mfma_f32_16x16x32_bf16 v[130:133], v[150:153], v[166:169], v[130:133]
	v_mfma_f32_16x16x32_bf16 v[126:129], v[154:157], v[162:165], 0
	v_mfma_f32_16x16x32_bf16 v[126:129], v[158:161], v[166:169], v[126:129]
	v_mfma_f32_16x16x32_bf16 v[106:109], v[154:157], v[170:173], 0
	v_mfma_f32_16x16x32_bf16 v[106:109], v[158:161], v[174:177], v[106:109]
	v_mfma_f32_16x16x32_bf16 v[110:113], v[146:149], v[170:173], 0
	v_mfma_f32_16x16x32_bf16 v[110:113], v[150:153], v[174:177], v[110:113]
	v_mfma_f32_16x16x32_bf16 v[118:121], v[114:117], v[170:173], 0
	v_mfma_f32_16x16x32_bf16 v[118:121], v[134:137], v[174:177], v[118:121]
	v_mfma_f32_16x16x32_bf16 v[122:125], v[74:77], v[170:173], 0
	v_mfma_f32_16x16x32_bf16 v[122:125], v[94:97], v[174:177], v[122:125]
	v_mfma_f32_16x16x32_bf16 v[102:105], v[74:77], v[188:191], 0
	v_mfma_f32_16x16x32_bf16 v[102:105], v[94:97], v[202:205], v[102:105]
	v_mfma_f32_16x16x32_bf16 v[98:101], v[114:117], v[188:191], 0
	v_mfma_f32_16x16x32_bf16 v[98:101], v[134:137], v[202:205], v[98:101]
	v_mfma_f32_16x16x32_bf16 v[90:93], v[146:149], v[188:191], 0
	v_mfma_f32_16x16x32_bf16 v[90:93], v[150:153], v[202:205], v[90:93]
	v_mfma_f32_16x16x32_bf16 v[86:89], v[154:157], v[188:191], 0
	v_mfma_f32_16x16x32_bf16 v[86:89], v[158:161], v[202:205], v[86:89]
	v_mfma_f32_16x16x32_bf16 v[66:69], v[154:157], v[206:209], 0
	v_mfma_f32_16x16x32_bf16 v[66:69], v[158:161], v[210:213], v[66:69]
	v_mfma_f32_16x16x32_bf16 v[70:73], v[146:149], v[206:209], 0
	v_mfma_f32_16x16x32_bf16 v[70:73], v[150:153], v[210:213], v[70:73]
	v_mfma_f32_16x16x32_bf16 v[78:81], v[114:117], v[206:209], 0
	v_mfma_f32_16x16x32_bf16 v[78:81], v[134:137], v[210:213], v[78:81]
	v_mfma_f32_16x16x32_bf16 v[82:85], v[74:77], v[206:209], 0
	v_mfma_f32_16x16x32_bf16 v[82:85], v[94:97], v[210:213], v[82:85]
	s_barrier
	s_setprio 0
	ds_read_b128 v[162:165], v186 offset:16384
	ds_read_b128 v[166:169], v186 offset:17408
	ds_read_b128 v[170:173], v186 offset:18432
	ds_read_b128 v[174:177], v186 offset:19456
	ds_read_b128 v[188:191], v186 offset:20480
	ds_read_b128 v[202:205], v186 offset:21504
	ds_read_b128 v[206:209], v186 offset:22528
	ds_read_b128 v[210:213], v186 offset:23552
	s_mov_b32 m0, s29
	s_nop 0
	global_load_lds_dwordx4 v180, s[58:59]
	s_add_u32 s30, s58, 0x40000
	s_mov_b32 m0, s42
	s_nop 0
	global_load_lds_dwordx4 v182, s[58:59]
	s_addc_u32 s31, s59, 0
	s_mov_b32 m0, s43
	s_nop 0
	global_load_lds_dwordx4 v180, s[30:31]
	s_nop 0
	s_mov_b32 m0, s44
	s_nop 0
	global_load_lds_dwordx4 v182, s[30:31]
	s_nop 0
	s_mov_b32 m0, s15
	s_nop 0
	global_load_lds_dwordx4 v0, s[60:61]
	s_nop 0
	s_mov_b32 m0, s45
	s_nop 0
	global_load_lds_dwordx4 v181, s[60:61]
	s_mul_i32 s4, s85, s27
	s_mul_hi_u32 s5, s85, s87
	s_add_i32 s5, s5, s4
	s_mul_i32 s4, s85, s87
	s_add_u32 s4, s4, s16
	s_addc_u32 s5, s5, s68
	v_mov_b64_e32 v[192:193], s[46:47]
	v_cmp_lt_i64_e64 s[8:9], s[4:5], v[192:193]
	s_ashr_i32 s5, s4, 31
	s_lshr_b32 s5, s5, 29
	s_add_i32 s5, s4, s5
	s_ashr_i32 s90, s5, 3
	s_and_b32 s5, s5, -8
	s_sub_i32 s4, s4, s5
	s_lshr_b32 s5, s4, 31
	s_or_b32 s5, s78, s5
	s_mul_i32 s4, s5, s4
	s_add_i32 s4, s4, s90
	s_abs_i32 s90, s4
	v_readlane_b32 s91, v254, 48
	s_mul_hi_u32 s91, s90, s91
	s_mul_i32 s34, s91, s26
	s_sub_i32 s90, s90, s34
	s_ashr_i32 s5, s4, 31
	s_add_i32 s34, s91, 1
	s_sub_i32 s35, s90, s26
	s_cmp_ge_u32 s90, s26
	s_cselect_b32 s91, s34, s91
	s_cselect_b32 s90, s35, s90
	s_waitcnt vmcnt(8)
	s_waitcnt lgkmcnt(0)
	s_setprio 1
	s_barrier
	v_mfma_f32_16x16x32_bf16 v[62:65], v[74:77], v[162:165], 0
	v_mfma_f32_16x16x32_bf16 v[62:65], v[94:97], v[166:169], v[62:65]
	v_mfma_f32_16x16x32_bf16 v[58:61], v[114:117], v[162:165], 0
	v_mfma_f32_16x16x32_bf16 v[58:61], v[134:137], v[166:169], v[58:61]
	v_mfma_f32_16x16x32_bf16 v[54:57], v[146:149], v[162:165], 0
	v_mfma_f32_16x16x32_bf16 v[54:57], v[150:153], v[166:169], v[54:57]
	v_mfma_f32_16x16x32_bf16 v[50:53], v[154:157], v[162:165], 0
	v_mfma_f32_16x16x32_bf16 v[50:53], v[158:161], v[166:169], v[50:53]
	v_mfma_f32_16x16x32_bf16 v[34:37], v[154:157], v[170:173], 0
	v_mfma_f32_16x16x32_bf16 v[34:37], v[158:161], v[174:177], v[34:37]
	v_mfma_f32_16x16x32_bf16 v[38:41], v[146:149], v[170:173], 0
	v_mfma_f32_16x16x32_bf16 v[38:41], v[150:153], v[174:177], v[38:41]
	v_mfma_f32_16x16x32_bf16 v[42:45], v[114:117], v[170:173], 0
	v_mfma_f32_16x16x32_bf16 v[42:45], v[134:137], v[174:177], v[42:45]
	v_mfma_f32_16x16x32_bf16 v[46:49], v[74:77], v[170:173], 0
	v_mfma_f32_16x16x32_bf16 v[46:49], v[94:97], v[174:177], v[46:49]
	v_mfma_f32_16x16x32_bf16 v[30:33], v[74:77], v[188:191], 0
	v_mfma_f32_16x16x32_bf16 v[30:33], v[94:97], v[202:205], v[30:33]
	v_mfma_f32_16x16x32_bf16 v[26:29], v[114:117], v[188:191], 0
	v_mfma_f32_16x16x32_bf16 v[26:29], v[134:137], v[202:205], v[26:29]
	v_mfma_f32_16x16x32_bf16 v[22:25], v[146:149], v[188:191], 0
	v_mfma_f32_16x16x32_bf16 v[22:25], v[150:153], v[202:205], v[22:25]
	v_mfma_f32_16x16x32_bf16 v[18:21], v[154:157], v[188:191], 0
	v_mfma_f32_16x16x32_bf16 v[18:21], v[158:161], v[202:205], v[18:21]
	v_mfma_f32_16x16x32_bf16 v[2:5], v[154:157], v[206:209], 0
	v_mfma_f32_16x16x32_bf16 v[2:5], v[158:161], v[210:213], v[2:5]
	v_mfma_f32_16x16x32_bf16 v[6:9], v[146:149], v[206:209], 0
	v_mfma_f32_16x16x32_bf16 v[6:9], v[150:153], v[210:213], v[6:9]
	v_mfma_f32_16x16x32_bf16 v[10:13], v[114:117], v[206:209], 0
	v_mfma_f32_16x16x32_bf16 v[10:13], v[134:137], v[210:213], v[10:13]
	v_mfma_f32_16x16x32_bf16 v[14:17], v[74:77], v[206:209], 0
	v_mfma_f32_16x16x32_bf16 v[14:17], v[94:97], v[210:213], v[14:17]
	s_barrier
; #define PG8_STAGE(bufoff, gbase, voff) do { _Pragma("unroll") for (int _i = 0; _i < 2; ++_i) { \
;         const unsigned _m0 = ldsb + (unsigned)((bufoff) + _i * 8192); const char* _gb = (const char*)(gbase); \
;         asm volatile("s_mov_b32 m0, %0\n\ts_nop 0\n\tglobal_load_lds_dwordx4 %1, %2" :: "s"(_m0), "v"((voff)[_i]), "s"(_gb) : "m0", "memory"); } } while (0)
; #define PG8_LDA(dst, b, h) do { _Pragma("unroll") for (int m = 0; m < 4; ++m) _Pragma("unroll") for (int k = 0; k < 2; ++k) dst[m][k] = *(const LAS bf16x8*)(lds + PG8_SA(b, h) + aoff + m * 2048 + k * 1024); } while (0)
; #define PG8_WAIT_V(n) asm volatile("s_waitcnt vmcnt(" #n ")" ::: "memory")
; #define PG8_BAR __builtin_amdgcn_s_barrier()
;     __device__ bool next(int i, Unit& u) const {
;         const long L = (long)i * G + c; if (L >= nwg) return false;
;         int wgid = (int)L; { const int q = nwg / NXCD, r = nwg % NXCD, xcd = wgid % NXCD, off = wgid / NXCD; wgid = (xcd < r ? xcd * (q + 1) : r * (q + 1) + (xcd - r) * q) + off; }
;         const int nig = WGM * nN, gid = wgid / nig, fm = gid * WGM, gsz = (nM - fm) < WGM ? (nM - fm) : WGM;
;         u.pm = fm + ((wgid % nig) % gsz); u.pn = (wgid % nig) / gsz; return true;
; template <class Epi, bool ALIGN_EPI>
; __device__ __forceinline__ void gemm_phase(LAS unsigned char* lds, const Gemm g, const StaticOrder& S, const Epi& E) {
;     ...
;         const char* nA = has_next ? (const char*)g.A + (size_t)nxt.pm * tstepA + (size_t)nxt.pn * g.a_pn_off * 2 + (size_t)(nxt.pm >> 4) * g.a_adj : cA; const char* nB = has_next ? (const char*)g.Bt + (size_t)nxt.pn * tstepB : cB;
;     ...
;             PG8_LDA(At, 0, 1); PG8_STAGE(PG8_SB(0, 0), b2, voffB); PG8_STAGE(PG8_SB(0, 1), b2 + hstepB, voffB); PG8_STAGE(PG8_SA(0, 0), a2, voffA);
;             PG8_WAIT_V(8); PG8_WAIT_L(0); PG8_BAR; PG8_MMA(1, 0, At, B0); PG8_MMA(1, 1, At, B1); PG8_BAR; PG8_SCHED;
;             PG8_LDB(B0, 1, 0); PG8_LDB(B1, 1, 1); PG8_SCHED; PG8_LDA(At, 1, 0); PG8_STAGE(PG8_SA(0, 1), a2 + hstepA, voffA);
;             PG8_WAIT_V(8); PG8_WAIT_L(0); PG8_BAR; PG8_MMA(0, 0, At, B0); PG8_MMA(0, 1, At, B1); PG8_BAR; PG8_SCHED;
;             PG8_LDA(At, 1, 1); PG8_STAGE(PG8_SB(1, 0), b3, voffB); PG8_STAGE(PG8_SB(1, 1), b3 + hstepB, voffB); PG8_STAGE(PG8_SA(1, 0), a3, voffA);
;             PG8_WAIT_V(8); PG8_WAIT_L(0); PG8_BAR; PG8_MMA(1, 0, At, B0); PG8_MMA(1, 1, At, B1); PG8_BAR; PG8_SCHED;
	s_setprio 0
	v_add_u32_e32 v134, 0x18000, v185
	v_add_u32_e32 v158, 0x1c000, v185
	ds_read_b128 v[74:77], v134
	ds_read_b128 v[94:97], v134 offset:1024
	ds_read_b128 v[114:117], v134 offset:2048
	ds_read_b128 v[134:137], v134 offset:3072
	ds_read_b128 v[146:149], v158
	ds_read_b128 v[150:153], v158 offset:1024
	ds_read_b128 v[154:157], v158 offset:2048
	ds_read_b128 v[158:161], v158 offset:3072
	ds_read_b128 v[162:165], v186 offset:32768
	ds_read_b128 v[166:169], v186 offset:33792
	ds_read_b128 v[170:173], v186 offset:34816
	ds_read_b128 v[174:177], v186 offset:35840
	ds_read_b128 v[188:191], v186 offset:36864
	ds_read_b128 v[202:205], v186 offset:37888
	ds_read_b128 v[206:209], v186 offset:38912
	ds_read_b128 v[210:213], v186 offset:39936
	s_add_u32 s30, s60, 0x40000
	s_addc_u32 s31, s61, 0
	s_mov_b32 m0, s55
	s_nop 0
	global_load_lds_dwordx4 v0, s[30:31]
	s_nop 0
	s_mov_b32 m0, s88
	s_nop 0
	global_load_lds_dwordx4 v181, s[30:31]
	s_add_i32 s34, s91, 1
	s_cmp_ge_u32 s90, s26
	s_cselect_b32 s90, s34, s91
	s_xor_b32 s90, s90, s5
	s_sub_i32 s5, s90, s5
	s_lshl_b32 s90, s5, 3
	s_sub_i32 s91, 0x80, s90
	s_min_i32 s91, s91, 8
	s_abs_i32 s34, s91
	v_cvt_f32_u32_e32 v192, s34
	s_sub_i32 s36, 0, s34
	s_mul_i32 s5, s5, s26
	s_sub_i32 s4, s4, s5
	v_rcp_iflag_f32_e32 v192, v192
	s_abs_i32 s35, s4
	s_xor_b32 s5, s4, s91
	s_ashr_i32 s5, s5, 31
	v_mul_f32_e32 v192, 0x4f7ffffe, v192
	v_cvt_u32_f32_e32 v192, v192
	s_nop 0
	v_readfirstlane_b32 s37, v192
	s_mul_i32 s36, s36, s37
	s_mul_hi_u32 s36, s37, s36
	s_add_i32 s37, s37, s36
	s_mul_hi_u32 s36, s35, s37
	s_mul_i32 s37, s36, s34
	s_sub_i32 s35, s35, s37
	s_waitcnt vmcnt(8)
	s_waitcnt lgkmcnt(0)
	s_setprio 1
	s_barrier
	v_mfma_f32_16x16x32_bf16 v[142:145], v[74:77], v[162:165], v[142:145]
	v_mfma_f32_16x16x32_bf16 v[142:145], v[94:97], v[166:169], v[142:145]
	v_mfma_f32_16x16x32_bf16 v[138:141], v[114:117], v[162:165], v[138:141]
	v_mfma_f32_16x16x32_bf16 v[138:141], v[134:137], v[166:169], v[138:141]
	v_mfma_f32_16x16x32_bf16 v[130:133], v[146:149], v[162:165], v[130:133]
	v_mfma_f32_16x16x32_bf16 v[130:133], v[150:153], v[166:169], v[130:133]
	v_mfma_f32_16x16x32_bf16 v[126:129], v[154:157], v[162:165], v[126:129]
	v_mfma_f32_16x16x32_bf16 v[126:129], v[158:161], v[166:169], v[126:129]
	v_mfma_f32_16x16x32_bf16 v[106:109], v[154:157], v[170:173], v[106:109]
	v_mfma_f32_16x16x32_bf16 v[106:109], v[158:161], v[174:177], v[106:109]
	v_mfma_f32_16x16x32_bf16 v[110:113], v[146:149], v[170:173], v[110:113]
	v_mfma_f32_16x16x32_bf16 v[110:113], v[150:153], v[174:177], v[110:113]
	v_mfma_f32_16x16x32_bf16 v[118:121], v[114:117], v[170:173], v[118:121]
	v_mfma_f32_16x16x32_bf16 v[118:121], v[134:137], v[174:177], v[118:121]
	v_mfma_f32_16x16x32_bf16 v[122:125], v[74:77], v[170:173], v[122:125]
	v_mfma_f32_16x16x32_bf16 v[122:125], v[94:97], v[174:177], v[122:125]
	v_mfma_f32_16x16x32_bf16 v[102:105], v[74:77], v[188:191], v[102:105]
	v_mfma_f32_16x16x32_bf16 v[102:105], v[94:97], v[202:205], v[102:105]
	v_mfma_f32_16x16x32_bf16 v[98:101], v[114:117], v[188:191], v[98:101]
	v_mfma_f32_16x16x32_bf16 v[98:101], v[134:137], v[202:205], v[98:101]
	v_mfma_f32_16x16x32_bf16 v[90:93], v[146:149], v[188:191], v[90:93]
	v_mfma_f32_16x16x32_bf16 v[90:93], v[150:153], v[202:205], v[90:93]
	v_mfma_f32_16x16x32_bf16 v[86:89], v[154:157], v[188:191], v[86:89]
	v_mfma_f32_16x16x32_bf16 v[86:89], v[158:161], v[202:205], v[86:89]
	v_mfma_f32_16x16x32_bf16 v[66:69], v[154:157], v[206:209], v[66:69]
	v_mfma_f32_16x16x32_bf16 v[66:69], v[158:161], v[210:213], v[66:69]
	v_mfma_f32_16x16x32_bf16 v[70:73], v[146:149], v[206:209], v[70:73]
	v_mfma_f32_16x16x32_bf16 v[70:73], v[150:153], v[210:213], v[70:73]
	v_mfma_f32_16x16x32_bf16 v[78:81], v[114:117], v[206:209], v[78:81]
	v_mfma_f32_16x16x32_bf16 v[78:81], v[134:137], v[210:213], v[78:81]
	v_mfma_f32_16x16x32_bf16 v[82:85], v[74:77], v[206:209], v[82:85]
	v_mfma_f32_16x16x32_bf16 v[82:85], v[94:97], v[210:213], v[82:85]
	s_barrier
	s_setprio 0
	ds_read_b128 v[162:165], v186 offset:49152
	ds_read_b128 v[166:169], v186 offset:50176
	ds_read_b128 v[170:173], v186 offset:51200
	ds_read_b128 v[174:177], v186 offset:52224
	ds_read_b128 v[188:191], v186 offset:53248
	ds_read_b128 v[202:205], v186 offset:54272
	ds_read_b128 v[206:209], v186 offset:55296
	ds_read_b128 v[210:213], v186 offset:56320
	s_add_u32 s30, s58, 0x80
	s_addc_u32 s31, s59, 0
	s_mov_b32 m0, s94
	s_nop 0
	global_load_lds_dwordx4 v180, s[30:31]
	s_nop 0
	s_mov_b32 m0, s95
	s_nop 0
	global_load_lds_dwordx4 v182, s[30:31]
	s_add_u32 s30, s58, 0x40080
	s_addc_u32 s31, s59, 0
	s_mov_b32 m0, s17
	s_nop 0
	global_load_lds_dwordx4 v180, s[30:31]
	s_nop 0
	s_mov_b32 m0, s53
	s_nop 0
	global_load_lds_dwordx4 v182, s[30:31]
	s_nop 0
	s_mov_b32 m0, s96
	s_nop 0
	global_load_lds_dwordx4 v0, s[56:57]
	s_nop 0
	s_mov_b32 m0, s97
	s_nop 0
	global_load_lds_dwordx4 v181, s[56:57]
	s_add_i32 s37, s36, 1
	s_sub_i32 s38, s35, s34
	s_cmp_ge_u32 s35, s34
	s_cselect_b32 s36, s37, s36
	s_cselect_b32 s35, s38, s35
	s_add_i32 s37, s36, 1
	s_cmp_ge_u32 s35, s34
	s_cselect_b32 s34, s37, s36
	s_xor_b32 s34, s34, s5
	s_sub_i32 s34, s34, s5
	s_mul_i32 s5, s34, s91
	s_sub_i32 s4, s4, s5
	s_add_i32 s36, s4, s90
	s_ashr_i32 s37, s36, 31
	s_lshl_b64 s[4:5], s[36:37], 19
	s_add_u32 s38, s18, s4
	s_addc_u32 s39, s19, s5
	s_and_b64 s[4:5], s[8:9], exec
	s_cselect_b32 s4, s39, s59
	s_cselect_b32 s5, s38, s58
	s_ashr_i32 s35, s34, 31
	s_lshl_b64 vcc, s[34:35], 19
	s_add_u32 s90, s1, vcc_lo
	s_addc_u32 s91, s14, vcc_hi
	s_and_b64 vcc, s[8:9], exec
	s_cselect_b32 s35, s91, s57
	s_cselect_b32 s37, s90, s56
	s_waitcnt vmcnt(8)
	s_waitcnt lgkmcnt(0)
	s_setprio 1
	s_barrier
; #define PG8_STAGE(bufoff, gbase, voff) do { _Pragma("unroll") for (int _i = 0; _i < 2; ++_i) { \
;         const unsigned _m0 = ldsb + (unsigned)((bufoff) + _i * 8192); const char* _gb = (const char*)(gbase); \
;         asm volatile("s_mov_b32 m0, %0\n\ts_nop 0\n\tglobal_load_lds_dwordx4 %1, %2" :: "s"(_m0), "v"((voff)[_i]), "s"(_gb) : "m0", "memory"); } } while (0)
; #define PG8_LDA(dst, b, h) do { _Pragma("unroll") for (int m = 0; m < 4; ++m) _Pragma("unroll") for (int k = 0; k < 2; ++k) dst[m][k] = *(const LAS bf16x8*)(lds + PG8_SA(b, h) + aoff + m * 2048 + k * 1024); } while (0)
; #define PG8_LDB(dst, b, h) do { _Pragma("unroll") for (int n = 0; n < 2; ++n) _Pragma("unroll") for (int k = 0; k < 2; ++k) dst[n][k] = *(const LAS bf16x8*)(lds + PG8_SB(b, h) + boff + n * 2048 + k * 1024); } while (0)
; #define PG8_MMA(ai, bj, At, Bt) do { __builtin_amdgcn_s_setprio(1); _Pragma("unroll") for (int m = 0; m < 4; ++m) _Pragma("unroll") for (int n = 0; n < 2; ++n) _Pragma("unroll") for (int k = 0; k < 2; ++k) \
;         acc[ai][bj][m][n] = __builtin_amdgcn_mfma_f32_16x16x32_bf16(Bt[n][k], At[m][k], acc[ai][bj][m][n], 0, 0, 0); __builtin_amdgcn_s_setprio(0); } while (0)
; template <class Epi, bool ALIGN_EPI>
; __device__ __forceinline__ void gemm_phase(LAS unsigned char* lds, const Gemm g, const StaticOrder& S, const Epi& E) {
;     ...
;             PG8_LDB(B0, 0, 0); PG8_LDB(B1, 0, 1); PG8_SCHED; PG8_LDA(At, 0, 0); PG8_STAGE(PG8_SA(1, 1), a1 + hstepA, voffA);
;             PG8_WAIT_V(8); PG8_WAIT_L(0); PG8_BAR; PG8_MMA(0, 0, At, B0); PG8_MMA(0, 1, At, B1); PG8_BAR; PG8_SCHED;
;             PG8_LDA(At, 0, 1); PG8_STAGE(PG8_SB(0, 0), b2, voffB); PG8_STAGE(PG8_SB(0, 1), b2 + hstepB, voffB); PG8_STAGE(PG8_SA(0, 0), a2, voffA);
;             PG8_WAIT_V(8); PG8_WAIT_L(0); PG8_BAR; PG8_MMA(1, 0, At, B0); PG8_MMA(1, 1, At, B1); PG8_BAR; PG8_SCHED;
;             PG8_LDB(B0, 1, 0); PG8_LDB(B1, 1, 1); PG8_SCHED; PG8_LDA(At, 1, 0); PG8_STAGE(PG8_SA(0, 1), a2 + hstepA, voffA);
;             PG8_WAIT_V(8); PG8_WAIT_L(0); PG8_BAR; PG8_MMA(0, 0, At, B0); PG8_MMA(0, 1, At, B1); PG8_BAR; PG8_SCHED;
;             PG8_LDA(At, 1, 1); PG8_STAGE(PG8_SB(1, 0), b3, voffB); PG8_STAGE(PG8_SB(1, 1), b3 + hstepB, voffB); PG8_STAGE(PG8_SA(1, 0), a3, voffA);
;             PG8_WAIT_V(8); PG8_WAIT_L(0); PG8_BAR; PG8_MMA(1, 0, At, B0); PG8_MMA(1, 1, At, B1); PG8_BAR; PG8_SCHED;
	v_mfma_f32_16x16x32_bf16 v[62:65], v[74:77], v[162:165], v[62:65]
	v_mfma_f32_16x16x32_bf16 v[62:65], v[94:97], v[166:169], v[62:65]
	v_mfma_f32_16x16x32_bf16 v[58:61], v[114:117], v[162:165], v[58:61]
	v_mfma_f32_16x16x32_bf16 v[58:61], v[134:137], v[166:169], v[58:61]
	v_mfma_f32_16x16x32_bf16 v[54:57], v[146:149], v[162:165], v[54:57]
	v_mfma_f32_16x16x32_bf16 v[54:57], v[150:153], v[166:169], v[54:57]
	v_mfma_f32_16x16x32_bf16 v[50:53], v[154:157], v[162:165], v[50:53]
	v_mfma_f32_16x16x32_bf16 v[50:53], v[158:161], v[166:169], v[50:53]
	v_mfma_f32_16x16x32_bf16 v[34:37], v[154:157], v[170:173], v[34:37]
	v_mfma_f32_16x16x32_bf16 v[34:37], v[158:161], v[174:177], v[34:37]
	v_mfma_f32_16x16x32_bf16 v[38:41], v[146:149], v[170:173], v[38:41]
	v_mfma_f32_16x16x32_bf16 v[38:41], v[150:153], v[174:177], v[38:41]
	v_mfma_f32_16x16x32_bf16 v[42:45], v[114:117], v[170:173], v[42:45]
	v_mfma_f32_16x16x32_bf16 v[42:45], v[134:137], v[174:177], v[42:45]
	v_mfma_f32_16x16x32_bf16 v[46:49], v[74:77], v[170:173], v[46:49]
	v_mfma_f32_16x16x32_bf16 v[46:49], v[94:97], v[174:177], v[46:49]
	v_mfma_f32_16x16x32_bf16 v[30:33], v[74:77], v[188:191], v[30:33]
	v_mfma_f32_16x16x32_bf16 v[30:33], v[94:97], v[202:205], v[30:33]
	v_mfma_f32_16x16x32_bf16 v[26:29], v[114:117], v[188:191], v[26:29]
	v_mfma_f32_16x16x32_bf16 v[26:29], v[134:137], v[202:205], v[26:29]
	v_mfma_f32_16x16x32_bf16 v[22:25], v[146:149], v[188:191], v[22:25]
	v_mfma_f32_16x16x32_bf16 v[22:25], v[150:153], v[202:205], v[22:25]
	v_mfma_f32_16x16x32_bf16 v[18:21], v[154:157], v[188:191], v[18:21]
	v_mfma_f32_16x16x32_bf16 v[18:21], v[158:161], v[202:205], v[18:21]
	v_mfma_f32_16x16x32_bf16 v[2:5], v[154:157], v[206:209], v[2:5]
	v_mfma_f32_16x16x32_bf16 v[2:5], v[158:161], v[210:213], v[2:5]
	v_mfma_f32_16x16x32_bf16 v[6:9], v[146:149], v[206:209], v[6:9]
	v_mfma_f32_16x16x32_bf16 v[6:9], v[150:153], v[210:213], v[6:9]
	v_mfma_f32_16x16x32_bf16 v[10:13], v[114:117], v[206:209], v[10:13]
	v_mfma_f32_16x16x32_bf16 v[10:13], v[134:137], v[210:213], v[10:13]
	v_mfma_f32_16x16x32_bf16 v[14:17], v[74:77], v[206:209], v[14:17]
	v_mfma_f32_16x16x32_bf16 v[14:17], v[94:97], v[210:213], v[14:17]
	s_barrier
	s_setprio 0
	s_add_i32 s50, s50, 2
	s_add_u32 s41, s41, 0x100
	s_addc_u32 s49, s49, 0
	s_add_u32 s92, s92, 0x100
	s_addc_u32 s93, s93, 0
	s_cmp_gt_u32 s50, 13
.LBB0_306:
	v_add_u32_e32 v134, 0x10000, v185
	v_add_u32_e32 v158, 0x14000, v185
	ds_read_b128 v[74:77], v134
	ds_read_b128 v[94:97], v134 offset:1024
	ds_read_b128 v[114:117], v134 offset:2048
	ds_read_b128 v[134:137], v134 offset:3072
	ds_read_b128 v[146:149], v158
	ds_read_b128 v[150:153], v158 offset:1024
	ds_read_b128 v[154:157], v158 offset:2048
	ds_read_b128 v[158:161], v158 offset:3072
	s_add_u32 s30, s92, 0xfffc0080
	s_addc_u32 s31, s93, -1
	s_cmp_eq_u32 s50, 12
	s_cselect_b32 s60, s5, s30
	s_cselect_b32 s61, s4, s31
	s_cselect_b32 s58, s37, s41
	s_cselect_b32 s59, s35, s49
	s_add_u32 s56, s60, 0x80
	s_addc_u32 s57, s61, 0
	ds_read_b128 v[162:165], v186
	ds_read_b128 v[166:169], v186 offset:1024
	ds_read_b128 v[170:173], v186 offset:2048
	ds_read_b128 v[174:177], v186 offset:3072
	ds_read_b128 v[188:191], v186 offset:4096
	ds_read_b128 v[202:205], v186 offset:5120
	ds_read_b128 v[206:209], v186 offset:6144
	ds_read_b128 v[210:213], v186 offset:7168
	s_mov_b32 m0, s67
	s_nop 0
	global_load_lds_dwordx4 v0, s[92:93]
	s_nop 0
	s_mov_b32 m0, s65
	s_nop 0
	global_load_lds_dwordx4 v181, s[92:93]
	s_waitcnt vmcnt(8)
	s_waitcnt lgkmcnt(0)
	s_setprio 1
	s_barrier
	v_mfma_f32_16x16x32_bf16 v[142:145], v[74:77], v[162:165], v[142:145]
	v_mfma_f32_16x16x32_bf16 v[142:145], v[94:97], v[166:169], v[142:145]
	v_mfma_f32_16x16x32_bf16 v[138:141], v[114:117], v[162:165], v[138:141]
	v_mfma_f32_16x16x32_bf16 v[138:141], v[134:137], v[166:169], v[138:141]
	v_mfma_f32_16x16x32_bf16 v[130:133], v[146:149], v[162:165], v[130:133]
	v_mfma_f32_16x16x32_bf16 v[130:133], v[150:153], v[166:169], v[130:133]
	v_mfma_f32_16x16x32_bf16 v[126:129], v[154:157], v[162:165], v[126:129]
	v_mfma_f32_16x16x32_bf16 v[126:129], v[158:161], v[166:169], v[126:129]
	v_mfma_f32_16x16x32_bf16 v[106:109], v[154:157], v[170:173], v[106:109]
	v_mfma_f32_16x16x32_bf16 v[106:109], v[158:161], v[174:177], v[106:109]
	v_mfma_f32_16x16x32_bf16 v[110:113], v[146:149], v[170:173], v[110:113]
	v_mfma_f32_16x16x32_bf16 v[110:113], v[150:153], v[174:177], v[110:113]
	v_mfma_f32_16x16x32_bf16 v[118:121], v[114:117], v[170:173], v[118:121]
	v_mfma_f32_16x16x32_bf16 v[118:121], v[134:137], v[174:177], v[118:121]
	v_mfma_f32_16x16x32_bf16 v[122:125], v[74:77], v[170:173], v[122:125]
	v_mfma_f32_16x16x32_bf16 v[122:125], v[94:97], v[174:177], v[122:125]
	v_mfma_f32_16x16x32_bf16 v[102:105], v[74:77], v[188:191], v[102:105]
	v_mfma_f32_16x16x32_bf16 v[102:105], v[94:97], v[202:205], v[102:105]
	v_mfma_f32_16x16x32_bf16 v[98:101], v[114:117], v[188:191], v[98:101]
	v_mfma_f32_16x16x32_bf16 v[98:101], v[134:137], v[202:205], v[98:101]
	v_mfma_f32_16x16x32_bf16 v[90:93], v[146:149], v[188:191], v[90:93]
	v_mfma_f32_16x16x32_bf16 v[90:93], v[150:153], v[202:205], v[90:93]
	v_mfma_f32_16x16x32_bf16 v[86:89], v[154:157], v[188:191], v[86:89]
	v_mfma_f32_16x16x32_bf16 v[86:89], v[158:161], v[202:205], v[86:89]
	v_mfma_f32_16x16x32_bf16 v[66:69], v[154:157], v[206:209], v[66:69]
	v_mfma_f32_16x16x32_bf16 v[66:69], v[158:161], v[210:213], v[66:69]
	v_mfma_f32_16x16x32_bf16 v[70:73], v[146:149], v[206:209], v[70:73]
	v_mfma_f32_16x16x32_bf16 v[70:73], v[150:153], v[210:213], v[70:73]
	v_mfma_f32_16x16x32_bf16 v[78:81], v[114:117], v[206:209], v[78:81]
	v_mfma_f32_16x16x32_bf16 v[78:81], v[134:137], v[210:213], v[78:81]
	v_mfma_f32_16x16x32_bf16 v[82:85], v[74:77], v[206:209], v[82:85]
	v_mfma_f32_16x16x32_bf16 v[82:85], v[94:97], v[210:213], v[82:85]
	s_barrier
; #define PG8_STAGE(bufoff, gbase, voff) do { _Pragma("unroll") for (int _i = 0; _i < 2; ++_i) { \
;         const unsigned _m0 = ldsb + (unsigned)((bufoff) + _i * 8192); const char* _gb = (const char*)(gbase); \
;         asm volatile("s_mov_b32 m0, %0\n\ts_nop 0\n\tglobal_load_lds_dwordx4 %1, %2" :: "s"(_m0), "v"((voff)[_i]), "s"(_gb) : "m0", "memory"); } } while (0)
; #define PG8_LDA(dst, b, h) do { _Pragma("unroll") for (int m = 0; m < 4; ++m) _Pragma("unroll") for (int k = 0; k < 2; ++k) dst[m][k] = *(const LAS bf16x8*)(lds + PG8_SA(b, h) + aoff + m * 2048 + k * 1024); } while (0)
; #define PG8_LDB(dst, b, h) do { _Pragma("unroll") for (int n = 0; n < 2; ++n) _Pragma("unroll") for (int k = 0; k < 2; ++k) dst[n][k] = *(const LAS bf16x8*)(lds + PG8_SB(b, h) + boff + n * 2048 + k * 1024); } while (0)
; #define PG8_MMA(ai, bj, At, Bt) do { __builtin_amdgcn_s_setprio(1); _Pragma("unroll") for (int m = 0; m < 4; ++m) _Pragma("unroll") for (int n = 0; n < 2; ++n) _Pragma("unroll") for (int k = 0; k < 2; ++k) \
;         acc[ai][bj][m][n] = __builtin_amdgcn_mfma_f32_16x16x32_bf16(Bt[n][k], At[m][k], acc[ai][bj][m][n], 0, 0, 0); __builtin_amdgcn_s_setprio(0); } while (0)
; #define PG8_WAIT_V(n) asm volatile("s_waitcnt vmcnt(" #n ")" ::: "memory")
; #define PG8_WAIT_L(n) asm volatile("s_waitcnt lgkmcnt(" #n ")" ::: "memory")
; #define PG8_BAR __builtin_amdgcn_s_barrier()
; #define PG8_SCHED __builtin_amdgcn_sched_barrier(0)
; template <class Epi, bool ALIGN_EPI>
; __device__ __forceinline__ void gemm_phase(LAS unsigned char* lds, const Gemm g, const StaticOrder& S, const Epi& E) {
;     ...
;             PG8_LDA(At, 0, 1); PG8_STAGE(PG8_SB(0, 0), b2, voffB); PG8_STAGE(PG8_SB(0, 1), b2 + hstepB, voffB); PG8_STAGE(PG8_SA(0, 0), a2, voffA);
;             PG8_WAIT_V(8); PG8_WAIT_L(0); PG8_BAR; PG8_MMA(1, 0, At, B0); PG8_MMA(1, 1, At, B1); PG8_BAR; PG8_SCHED;
;             PG8_LDB(B0, 1, 0); PG8_LDB(B1, 1, 1); PG8_SCHED; PG8_LDA(At, 1, 0); PG8_STAGE(PG8_SA(0, 1), a2 + hstepA, voffA);
;             PG8_WAIT_V(8); PG8_WAIT_L(0); PG8_BAR; PG8_MMA(0, 0, At, B0); PG8_MMA(0, 1, At, B1); PG8_BAR; PG8_SCHED;
;             PG8_LDA(At, 1, 1); PG8_STAGE(PG8_SB(1, 0), b3, voffB); PG8_STAGE(PG8_SB(1, 1), b3 + hstepB, voffB); PG8_STAGE(PG8_SA(1, 0), a3, voffA);
	s_setprio 0
	ds_read_b128 v[162:165], v186 offset:16384
	ds_read_b128 v[166:169], v186 offset:17408
	ds_read_b128 v[170:173], v186 offset:18432
	ds_read_b128 v[174:177], v186 offset:19456
	ds_read_b128 v[188:191], v186 offset:20480
	ds_read_b128 v[202:205], v186 offset:21504
	ds_read_b128 v[206:209], v186 offset:22528
	ds_read_b128 v[210:213], v186 offset:23552
	s_mov_b32 m0, s29
	s_nop 0
	global_load_lds_dwordx4 v180, s[58:59]
	s_add_u32 s30, s58, 0x40000
	s_mov_b32 m0, s42
	s_nop 0
	global_load_lds_dwordx4 v182, s[58:59]
	s_addc_u32 s31, s59, 0
	s_mov_b32 m0, s43
	s_nop 0
	global_load_lds_dwordx4 v180, s[30:31]
	s_nop 0
	s_mov_b32 m0, s44
	s_nop 0
	global_load_lds_dwordx4 v182, s[30:31]
	s_nop 0
	s_mov_b32 m0, s15
	s_nop 0
	global_load_lds_dwordx4 v0, s[60:61]
	s_nop 0
	s_mov_b32 m0, s45
	s_nop 0
	global_load_lds_dwordx4 v181, s[60:61]
	s_waitcnt vmcnt(8)
	s_waitcnt lgkmcnt(0)
	s_setprio 1
	s_barrier
	v_mfma_f32_16x16x32_bf16 v[62:65], v[74:77], v[162:165], v[62:65]
	v_mfma_f32_16x16x32_bf16 v[62:65], v[94:97], v[166:169], v[62:65]
	v_mfma_f32_16x16x32_bf16 v[58:61], v[114:117], v[162:165], v[58:61]
	v_mfma_f32_16x16x32_bf16 v[58:61], v[134:137], v[166:169], v[58:61]
	v_mfma_f32_16x16x32_bf16 v[54:57], v[146:149], v[162:165], v[54:57]
	v_mfma_f32_16x16x32_bf16 v[54:57], v[150:153], v[166:169], v[54:57]
	v_mfma_f32_16x16x32_bf16 v[50:53], v[154:157], v[162:165], v[50:53]
	v_mfma_f32_16x16x32_bf16 v[50:53], v[158:161], v[166:169], v[50:53]
	v_mfma_f32_16x16x32_bf16 v[34:37], v[154:157], v[170:173], v[34:37]
	v_mfma_f32_16x16x32_bf16 v[34:37], v[158:161], v[174:177], v[34:37]
	v_mfma_f32_16x16x32_bf16 v[38:41], v[146:149], v[170:173], v[38:41]
	v_mfma_f32_16x16x32_bf16 v[38:41], v[150:153], v[174:177], v[38:41]
	v_mfma_f32_16x16x32_bf16 v[42:45], v[114:117], v[170:173], v[42:45]
	v_mfma_f32_16x16x32_bf16 v[42:45], v[134:137], v[174:177], v[42:45]
	v_mfma_f32_16x16x32_bf16 v[46:49], v[74:77], v[170:173], v[46:49]
	v_mfma_f32_16x16x32_bf16 v[46:49], v[94:97], v[174:177], v[46:49]
	v_mfma_f32_16x16x32_bf16 v[30:33], v[74:77], v[188:191], v[30:33]
	v_mfma_f32_16x16x32_bf16 v[30:33], v[94:97], v[202:205], v[30:33]
	v_mfma_f32_16x16x32_bf16 v[26:29], v[114:117], v[188:191], v[26:29]
	v_mfma_f32_16x16x32_bf16 v[26:29], v[134:137], v[202:205], v[26:29]
	v_mfma_f32_16x16x32_bf16 v[22:25], v[146:149], v[188:191], v[22:25]
	v_mfma_f32_16x16x32_bf16 v[22:25], v[150:153], v[202:205], v[22:25]
	v_mfma_f32_16x16x32_bf16 v[18:21], v[154:157], v[188:191], v[18:21]
	v_mfma_f32_16x16x32_bf16 v[18:21], v[158:161], v[202:205], v[18:21]
	v_mfma_f32_16x16x32_bf16 v[2:5], v[154:157], v[206:209], v[2:5]
	v_mfma_f32_16x16x32_bf16 v[2:5], v[158:161], v[210:213], v[2:5]
	v_mfma_f32_16x16x32_bf16 v[6:9], v[146:149], v[206:209], v[6:9]
	v_mfma_f32_16x16x32_bf16 v[6:9], v[150:153], v[210:213], v[6:9]
	v_mfma_f32_16x16x32_bf16 v[10:13], v[114:117], v[206:209], v[10:13]
	v_mfma_f32_16x16x32_bf16 v[10:13], v[134:137], v[210:213], v[10:13]
	v_mfma_f32_16x16x32_bf16 v[14:17], v[74:77], v[206:209], v[14:17]
	v_mfma_f32_16x16x32_bf16 v[14:17], v[94:97], v[210:213], v[14:17]
	s_barrier
	s_setprio 0
	v_add_u32_e32 v134, 0x18000, v185
	v_add_u32_e32 v158, 0x1c000, v185
	ds_read_b128 v[74:77], v134
	ds_read_b128 v[94:97], v134 offset:1024
	ds_read_b128 v[114:117], v134 offset:2048
	ds_read_b128 v[134:137], v134 offset:3072
	ds_read_b128 v[146:149], v158
	ds_read_b128 v[150:153], v158 offset:1024
	ds_read_b128 v[154:157], v158 offset:2048
	ds_read_b128 v[158:161], v158 offset:3072
	ds_read_b128 v[162:165], v186 offset:32768
	ds_read_b128 v[166:169], v186 offset:33792
	ds_read_b128 v[170:173], v186 offset:34816
	ds_read_b128 v[174:177], v186 offset:35840
	ds_read_b128 v[188:191], v186 offset:36864
	ds_read_b128 v[202:205], v186 offset:37888
	ds_read_b128 v[206:209], v186 offset:38912
	ds_read_b128 v[210:213], v186 offset:39936
	s_add_u32 s30, s60, 0x40000
	s_addc_u32 s31, s61, 0
	s_mov_b32 m0, s55
	s_nop 0
	global_load_lds_dwordx4 v0, s[30:31]
	s_nop 0
	s_mov_b32 m0, s88
	s_nop 0
	global_load_lds_dwordx4 v181, s[30:31]
	s_waitcnt vmcnt(8)
	s_waitcnt lgkmcnt(0)
	s_setprio 1
	s_barrier
; #define PG8_STAGE(bufoff, gbase, voff) do { _Pragma("unroll") for (int _i = 0; _i < 2; ++_i) { \
;         const unsigned _m0 = ldsb + (unsigned)((bufoff) + _i * 8192); const char* _gb = (const char*)(gbase); \
;         asm volatile("s_mov_b32 m0, %0\n\ts_nop 0\n\tglobal_load_lds_dwordx4 %1, %2" :: "s"(_m0), "v"((voff)[_i]), "s"(_gb) : "m0", "memory"); } } while (0)
; #define PG8_LDA(dst, b, h) do { _Pragma("unroll") for (int m = 0; m < 4; ++m) _Pragma("unroll") for (int k = 0; k < 2; ++k) dst[m][k] = *(const LAS bf16x8*)(lds + PG8_SA(b, h) + aoff + m * 2048 + k * 1024); } while (0)
; #define PG8_MMA(ai, bj, At, Bt) do { __builtin_amdgcn_s_setprio(1); _Pragma("unroll") for (int m = 0; m < 4; ++m) _Pragma("unroll") for (int n = 0; n < 2; ++n) _Pragma("unroll") for (int k = 0; k < 2; ++k) \
;         acc[ai][bj][m][n] = __builtin_amdgcn_mfma_f32_16x16x32_bf16(Bt[n][k], At[m][k], acc[ai][bj][m][n], 0, 0, 0); __builtin_amdgcn_s_setprio(0); } while (0)
; #define PG8_WAIT_V(n) asm volatile("s_waitcnt vmcnt(" #n ")" ::: "memory")
; #define PG8_WAIT_L(n) asm volatile("s_waitcnt lgkmcnt(" #n ")" ::: "memory")
; #define PG8_BAR __builtin_amdgcn_s_barrier()
; #define PG8_SCHED __builtin_amdgcn_sched_barrier(0)
; template <class Epi, bool ALIGN_EPI>
; __device__ __forceinline__ void gemm_phase(LAS unsigned char* lds, const Gemm g, const StaticOrder& S, const Epi& E) {
;     ...
;             PG8_LDA(At, 1, 1); PG8_STAGE(PG8_SB(1, 0), b3, voffB); PG8_STAGE(PG8_SB(1, 1), b3 + hstepB, voffB); PG8_STAGE(PG8_SA(1, 0), a3, voffA);
;             PG8_WAIT_V(8); PG8_WAIT_L(0); PG8_BAR; PG8_MMA(1, 0, At, B0); PG8_MMA(1, 1, At, B1); PG8_BAR; PG8_SCHED;
;         }
;         if constexpr (ALIGN_EPI) { if (wr == 0) PG8_BAR; }
	v_mfma_f32_16x16x32_bf16 v[142:145], v[74:77], v[162:165], v[142:145]
	v_mfma_f32_16x16x32_bf16 v[142:145], v[94:97], v[166:169], v[142:145]
	v_mfma_f32_16x16x32_bf16 v[138:141], v[114:117], v[162:165], v[138:141]
	v_mfma_f32_16x16x32_bf16 v[138:141], v[134:137], v[166:169], v[138:141]
	v_mfma_f32_16x16x32_bf16 v[130:133], v[146:149], v[162:165], v[130:133]
	v_mfma_f32_16x16x32_bf16 v[130:133], v[150:153], v[166:169], v[130:133]
	v_mfma_f32_16x16x32_bf16 v[126:129], v[154:157], v[162:165], v[126:129]
	v_mfma_f32_16x16x32_bf16 v[126:129], v[158:161], v[166:169], v[126:129]
	v_mfma_f32_16x16x32_bf16 v[106:109], v[154:157], v[170:173], v[106:109]
	v_mfma_f32_16x16x32_bf16 v[106:109], v[158:161], v[174:177], v[106:109]
	v_mfma_f32_16x16x32_bf16 v[110:113], v[146:149], v[170:173], v[110:113]
	v_mfma_f32_16x16x32_bf16 v[110:113], v[150:153], v[174:177], v[110:113]
	v_mfma_f32_16x16x32_bf16 v[118:121], v[114:117], v[170:173], v[118:121]
	v_mfma_f32_16x16x32_bf16 v[118:121], v[134:137], v[174:177], v[118:121]
	v_mfma_f32_16x16x32_bf16 v[122:125], v[74:77], v[170:173], v[122:125]
	v_mfma_f32_16x16x32_bf16 v[122:125], v[94:97], v[174:177], v[122:125]
	v_mfma_f32_16x16x32_bf16 v[102:105], v[74:77], v[188:191], v[102:105]
	v_mfma_f32_16x16x32_bf16 v[102:105], v[94:97], v[202:205], v[102:105]
	v_mfma_f32_16x16x32_bf16 v[98:101], v[114:117], v[188:191], v[98:101]
	v_mfma_f32_16x16x32_bf16 v[98:101], v[134:137], v[202:205], v[98:101]
	v_mfma_f32_16x16x32_bf16 v[90:93], v[146:149], v[188:191], v[90:93]
	v_mfma_f32_16x16x32_bf16 v[90:93], v[150:153], v[202:205], v[90:93]
	v_mfma_f32_16x16x32_bf16 v[86:89], v[154:157], v[188:191], v[86:89]
	v_mfma_f32_16x16x32_bf16 v[86:89], v[158:161], v[202:205], v[86:89]
	v_mfma_f32_16x16x32_bf16 v[66:69], v[154:157], v[206:209], v[66:69]
	v_mfma_f32_16x16x32_bf16 v[66:69], v[158:161], v[210:213], v[66:69]
	v_mfma_f32_16x16x32_bf16 v[70:73], v[146:149], v[206:209], v[70:73]
	v_mfma_f32_16x16x32_bf16 v[70:73], v[150:153], v[210:213], v[70:73]
	v_mfma_f32_16x16x32_bf16 v[78:81], v[114:117], v[206:209], v[78:81]
	v_mfma_f32_16x16x32_bf16 v[78:81], v[134:137], v[210:213], v[78:81]
	v_mfma_f32_16x16x32_bf16 v[82:85], v[74:77], v[206:209], v[82:85]
	v_mfma_f32_16x16x32_bf16 v[82:85], v[94:97], v[210:213], v[82:85]
	s_barrier
	s_setprio 0
	ds_read_b128 v[162:165], v186 offset:49152
	ds_read_b128 v[166:169], v186 offset:50176
	ds_read_b128 v[170:173], v186 offset:51200
	ds_read_b128 v[174:177], v186 offset:52224
	ds_read_b128 v[188:191], v186 offset:53248
	ds_read_b128 v[202:205], v186 offset:54272
	ds_read_b128 v[206:209], v186 offset:55296
	ds_read_b128 v[210:213], v186 offset:56320
	s_add_u32 s30, s58, 0x80
	s_addc_u32 s31, s59, 0
	s_mov_b32 m0, s94
	s_nop 0
	global_load_lds_dwordx4 v180, s[30:31]
	s_nop 0
	s_mov_b32 m0, s95
	s_nop 0
	global_load_lds_dwordx4 v182, s[30:31]
	s_add_u32 s30, s58, 0x40080
	s_addc_u32 s31, s59, 0
	s_mov_b32 m0, s17
	s_nop 0
	global_load_lds_dwordx4 v180, s[30:31]
	s_nop 0
	s_mov_b32 m0, s53
	s_nop 0
	global_load_lds_dwordx4 v182, s[30:31]
	s_nop 0
	s_mov_b32 m0, s96
	s_nop 0
	global_load_lds_dwordx4 v0, s[56:57]
	s_nop 0
	s_mov_b32 m0, s97
	s_nop 0
	global_load_lds_dwordx4 v181, s[56:57]
	s_waitcnt vmcnt(8)
	s_waitcnt lgkmcnt(0)
	s_setprio 1
	s_barrier
	v_mfma_f32_16x16x32_bf16 v[62:65], v[74:77], v[162:165], v[62:65]
	v_mfma_f32_16x16x32_bf16 v[62:65], v[94:97], v[166:169], v[62:65]
	v_mfma_f32_16x16x32_bf16 v[58:61], v[114:117], v[162:165], v[58:61]
	v_mfma_f32_16x16x32_bf16 v[58:61], v[134:137], v[166:169], v[58:61]
	v_mfma_f32_16x16x32_bf16 v[54:57], v[146:149], v[162:165], v[54:57]
	v_mfma_f32_16x16x32_bf16 v[54:57], v[150:153], v[166:169], v[54:57]
	v_mfma_f32_16x16x32_bf16 v[50:53], v[154:157], v[162:165], v[50:53]
	v_mfma_f32_16x16x32_bf16 v[50:53], v[158:161], v[166:169], v[50:53]
	v_mfma_f32_16x16x32_bf16 v[34:37], v[154:157], v[170:173], v[34:37]
	v_mfma_f32_16x16x32_bf16 v[34:37], v[158:161], v[174:177], v[34:37]
	v_mfma_f32_16x16x32_bf16 v[38:41], v[146:149], v[170:173], v[38:41]
	v_mfma_f32_16x16x32_bf16 v[38:41], v[150:153], v[174:177], v[38:41]
	v_mfma_f32_16x16x32_bf16 v[42:45], v[114:117], v[170:173], v[42:45]
	v_mfma_f32_16x16x32_bf16 v[42:45], v[134:137], v[174:177], v[42:45]
	v_mfma_f32_16x16x32_bf16 v[46:49], v[74:77], v[170:173], v[46:49]
	v_mfma_f32_16x16x32_bf16 v[46:49], v[94:97], v[174:177], v[46:49]
	v_mfma_f32_16x16x32_bf16 v[30:33], v[74:77], v[188:191], v[30:33]
	v_mfma_f32_16x16x32_bf16 v[30:33], v[94:97], v[202:205], v[30:33]
	v_mfma_f32_16x16x32_bf16 v[26:29], v[114:117], v[188:191], v[26:29]
	v_mfma_f32_16x16x32_bf16 v[26:29], v[134:137], v[202:205], v[26:29]
	v_mfma_f32_16x16x32_bf16 v[22:25], v[146:149], v[188:191], v[22:25]
	v_mfma_f32_16x16x32_bf16 v[22:25], v[150:153], v[202:205], v[22:25]
	v_mfma_f32_16x16x32_bf16 v[18:21], v[154:157], v[188:191], v[18:21]
	v_mfma_f32_16x16x32_bf16 v[18:21], v[158:161], v[202:205], v[18:21]
	v_mfma_f32_16x16x32_bf16 v[2:5], v[154:157], v[206:209], v[2:5]
	v_mfma_f32_16x16x32_bf16 v[2:5], v[158:161], v[210:213], v[2:5]
	v_mfma_f32_16x16x32_bf16 v[6:9], v[146:149], v[206:209], v[6:9]
	v_mfma_f32_16x16x32_bf16 v[6:9], v[150:153], v[210:213], v[6:9]
	v_mfma_f32_16x16x32_bf16 v[10:13], v[114:117], v[206:209], v[10:13]
	v_mfma_f32_16x16x32_bf16 v[10:13], v[134:137], v[210:213], v[10:13]
	v_mfma_f32_16x16x32_bf16 v[14:17], v[74:77], v[206:209], v[14:17]
	v_mfma_f32_16x16x32_bf16 v[14:17], v[94:97], v[210:213], v[14:17]
	s_barrier
	s_setprio 0
	s_add_i32 s50, s50, 2
	s_add_u32 s41, s41, 0x100
	s_addc_u32 s49, s49, 0
	s_add_u32 s92, s92, 0x100
	s_addc_u32 s93, s93, 0
	s_cmp_gt_u32 s50, 13
	s_cbranch_scc0 .LBB0_306
	v_readlane_b32 s4, v254, 46
	v_readlane_b32 s5, v254, 47
	s_and_b64 vcc, exec, s[4:5]
	s_cbranch_vccz .LBB0_309
	s_barrier

; #define PG8_STAGE(bufoff, gbase, voff) do { _Pragma("unroll") for (int _i = 0; _i < 2; ++_i) { \
;         const unsigned _m0 = ldsb + (unsigned)((bufoff) + _i * 8192); const char* _gb = (const char*)(gbase); \
;         asm volatile("s_mov_b32 m0, %0\n\ts_nop 0\n\tglobal_load_lds_dwordx4 %1, %2" :: "s"(_m0), "v"((voff)[_i]), "s"(_gb) : "m0", "memory"); } } while (0)
; #define PG8_LDA(dst, b, h) do { _Pragma("unroll") for (int m = 0; m < 4; ++m) _Pragma("unroll") for (int k = 0; k < 2; ++k) dst[m][k] = *(const LAS bf16x8*)(lds + PG8_SA(b, h) + aoff + m * 2048 + k * 1024); } while (0)
; #define PG8_LDB(dst, b, h) do { _Pragma("unroll") for (int n = 0; n < 2; ++n) _Pragma("unroll") for (int k = 0; k < 2; ++k) dst[n][k] = *(const LAS bf16x8*)(lds + PG8_SB(b, h) + boff + n * 2048 + k * 1024); } while (0)
; #define PG8_MMA(ai, bj, At, Bt) do { __builtin_amdgcn_s_setprio(1); _Pragma("unroll") for (int m = 0; m < 4; ++m) _Pragma("unroll") for (int n = 0; n < 2; ++n) _Pragma("unroll") for (int k = 0; k < 2; ++k) \
;         acc[ai][bj][m][n] = __builtin_amdgcn_mfma_f32_16x16x32_bf16(Bt[n][k], At[m][k], acc[ai][bj][m][n], 0, 0, 0); __builtin_amdgcn_s_setprio(0); } while (0)
; #define PG8_WAIT_V(n) asm volatile("s_waitcnt vmcnt(" #n ")" ::: "memory")
; #define PG8_WAIT_L(n) asm volatile("s_waitcnt lgkmcnt(" #n ")" ::: "memory")
; #define PG8_BAR __builtin_amdgcn_s_barrier()
; #define PG8_SCHED __builtin_amdgcn_sched_barrier(0)
; template <class Epi, bool ALIGN_EPI>
; __device__ __forceinline__ void gemm_phase(LAS unsigned char* lds, const Gemm g, const StaticOrder& S, const Epi& E) {
;     ...
;             PG8_LDB(B0, 0, 0); PG8_LDB(B1, 0, 1); PG8_SCHED; PG8_LDA(At, 0, 0); PG8_STAGE(PG8_SA(1, 1), a1 + hstepA, voffA);
;             PG8_WAIT_V(8); PG8_WAIT_L(0); PG8_BAR; PG8_MMA(0, 0, At, B0); PG8_MMA(0, 1, At, B1); PG8_BAR; PG8_SCHED;
;             PG8_LDA(At, 0, 1); PG8_STAGE(PG8_SB(0, 0), b2, voffB); PG8_STAGE(PG8_SB(0, 1), b2 + hstepB, voffB); PG8_STAGE(PG8_SA(0, 0), a2, voffA);
;             PG8_WAIT_V(8); PG8_WAIT_L(0); PG8_BAR; PG8_MMA(1, 0, At, B0); PG8_MMA(1, 1, At, B1); PG8_BAR; PG8_SCHED;
;             PG8_LDB(B0, 1, 0); PG8_LDB(B1, 1, 1); PG8_SCHED; PG8_LDA(At, 1, 0); PG8_STAGE(PG8_SA(0, 1), a2 + hstepA, voffA);
;             PG8_WAIT_V(8); PG8_WAIT_L(0); PG8_BAR; PG8_MMA(0, 0, At, B0); PG8_MMA(0, 1, At, B1); PG8_BAR; PG8_SCHED;
.LBB0_349:
	v_add_u32_e32 v0, 0x10000, v187
	ds_read_b128 v[34:37], v0
	ds_read_b128 v[54:57], v0 offset:1024
	ds_read_b128 v[74:77], v0 offset:2048
	ds_read_b128 v[94:97], v0 offset:3072
	v_add_u32_e32 v0, 0x14000, v187
	ds_read_b128 v[110:113], v0
	ds_read_b128 v[126:129], v0 offset:1024
	ds_read_b128 v[146:149], v0 offset:2048
	ds_read_b128 v[160:163], v0 offset:3072
	s_add_u32 s38, s36, 0xfffc0080
	s_addc_u32 s39, s37, -1
	s_cmp_eq_u32 s50, 12
	s_cselect_b32 s54, s5, s38
	s_cselect_b32 s55, s4, s39
	s_cselect_b32 s48, s27, s29
	s_cselect_b32 s49, s11, s41
	s_add_u32 s38, s54, 0x80
	s_addc_u32 s39, s55, 0
	ds_read_b128 v[164:167], v188
	ds_read_b128 v[168:171], v188 offset:1024
	ds_read_b128 v[172:175], v188 offset:2048
	ds_read_b128 v[176:179], v188 offset:3072
	ds_read_b128 v[190:193], v188 offset:4096
	ds_read_b128 v[202:205], v188 offset:5120
	ds_read_b128 v[206:209], v188 offset:6144
	ds_read_b128 v[210:213], v188 offset:7168
	s_mov_b32 m0, s91
	s_nop 0
	global_load_lds_dwordx4 v180, s[36:37]
	s_nop 0
	s_mov_b32 m0, s93
	s_nop 0
	global_load_lds_dwordx4 v182, s[36:37]
	s_waitcnt vmcnt(8)
	s_waitcnt lgkmcnt(0)
	s_setprio 1
	s_barrier
	v_mfma_f32_16x16x32_bf16 v[154:157], v[34:37], v[164:167], v[154:157]
	v_mfma_f32_16x16x32_bf16 v[154:157], v[54:57], v[168:171], v[154:157]
	v_mfma_f32_16x16x32_bf16 v[150:153], v[74:77], v[164:167], v[150:153]
	v_mfma_f32_16x16x32_bf16 v[150:153], v[94:97], v[168:171], v[150:153]
	v_mfma_f32_16x16x32_bf16 v[142:145], v[110:113], v[164:167], v[142:145]
	v_mfma_f32_16x16x32_bf16 v[142:145], v[126:129], v[168:171], v[142:145]
	v_mfma_f32_16x16x32_bf16 v[138:141], v[146:149], v[164:167], v[138:141]
	v_mfma_f32_16x16x32_bf16 v[138:141], v[160:163], v[168:171], v[138:141]
	v_mfma_f32_16x16x32_bf16 v[118:121], v[146:149], v[172:175], v[118:121]
	v_mfma_f32_16x16x32_bf16 v[118:121], v[160:163], v[176:179], v[118:121]
	v_mfma_f32_16x16x32_bf16 v[122:125], v[110:113], v[172:175], v[122:125]
	v_mfma_f32_16x16x32_bf16 v[122:125], v[126:129], v[176:179], v[122:125]
	v_mfma_f32_16x16x32_bf16 v[130:133], v[74:77], v[172:175], v[130:133]
	v_mfma_f32_16x16x32_bf16 v[130:133], v[94:97], v[176:179], v[130:133]
	v_mfma_f32_16x16x32_bf16 v[134:137], v[34:37], v[172:175], v[134:137]
	v_mfma_f32_16x16x32_bf16 v[134:137], v[54:57], v[176:179], v[134:137]
	v_mfma_f32_16x16x32_bf16 v[114:117], v[34:37], v[190:193], v[114:117]
	v_mfma_f32_16x16x32_bf16 v[114:117], v[54:57], v[202:205], v[114:117]
	v_mfma_f32_16x16x32_bf16 v[106:109], v[74:77], v[190:193], v[106:109]
	v_mfma_f32_16x16x32_bf16 v[106:109], v[94:97], v[202:205], v[106:109]
	v_mfma_f32_16x16x32_bf16 v[102:105], v[110:113], v[190:193], v[102:105]
	v_mfma_f32_16x16x32_bf16 v[102:105], v[126:129], v[202:205], v[102:105]
	v_mfma_f32_16x16x32_bf16 v[98:101], v[146:149], v[190:193], v[98:101]
	v_mfma_f32_16x16x32_bf16 v[98:101], v[160:163], v[202:205], v[98:101]
	v_mfma_f32_16x16x32_bf16 v[78:81], v[146:149], v[206:209], v[78:81]
	v_mfma_f32_16x16x32_bf16 v[78:81], v[160:163], v[210:213], v[78:81]
	v_mfma_f32_16x16x32_bf16 v[82:85], v[110:113], v[206:209], v[82:85]
	v_mfma_f32_16x16x32_bf16 v[82:85], v[126:129], v[210:213], v[82:85]
	v_mfma_f32_16x16x32_bf16 v[86:89], v[74:77], v[206:209], v[86:89]
	v_mfma_f32_16x16x32_bf16 v[86:89], v[94:97], v[210:213], v[86:89]
	v_mfma_f32_16x16x32_bf16 v[90:93], v[34:37], v[206:209], v[90:93]
	v_mfma_f32_16x16x32_bf16 v[90:93], v[54:57], v[210:213], v[90:93]
	s_barrier
	s_setprio 0
	ds_read_b128 v[164:167], v188 offset:16384
	ds_read_b128 v[168:171], v188 offset:17408
	ds_read_b128 v[172:175], v188 offset:18432
	ds_read_b128 v[176:179], v188 offset:19456
	ds_read_b128 v[190:193], v188 offset:20480
	ds_read_b128 v[202:205], v188 offset:21504
	ds_read_b128 v[206:209], v188 offset:22528
	ds_read_b128 v[210:213], v188 offset:23552
	s_mov_b32 m0, s43
	s_nop 0
	global_load_lds_dwordx4 v181, s[48:49]
	s_add_u32 s96, s48, 0x40000
	s_mov_b32 m0, s44
	s_nop 0
	global_load_lds_dwordx4 v183, s[48:49]
	s_addc_u32 s97, s49, 0
	s_mov_b32 m0, s45
	s_nop 0
	global_load_lds_dwordx4 v181, s[96:97]
	s_nop 0
	s_mov_b32 m0, s56
	s_nop 0
	global_load_lds_dwordx4 v183, s[96:97]
	s_nop 0
	s_mov_b32 m0, s42
	s_nop 0
	global_load_lds_dwordx4 v180, s[54:55]
	s_nop 0
	s_mov_b32 m0, s57
	s_nop 0
	global_load_lds_dwordx4 v182, s[54:55]
	s_waitcnt vmcnt(8)
	s_waitcnt lgkmcnt(0)
	s_setprio 1
	s_barrier
	v_mfma_f32_16x16x32_bf16 v[70:73], v[34:37], v[164:167], v[70:73]
	v_mfma_f32_16x16x32_bf16 v[66:69], v[74:77], v[164:167], v[66:69]
	v_mfma_f32_16x16x32_bf16 v[50:53], v[34:37], v[172:175], v[50:53]
	v_mfma_f32_16x16x32_bf16 v[46:49], v[74:77], v[172:175], v[46:49]
	v_mfma_f32_16x16x32_bf16 v[30:33], v[34:37], v[190:193], v[30:33]
	v_mfma_f32_16x16x32_bf16 v[26:29], v[74:77], v[190:193], v[26:29]
	v_mfma_f32_16x16x32_bf16 v[14:17], v[34:37], v[206:209], v[14:17]
	v_mfma_f32_16x16x32_bf16 v[10:13], v[74:77], v[206:209], v[10:13]
	v_mfma_f32_16x16x32_bf16 v[70:73], v[54:57], v[168:171], v[70:73]
	v_mfma_f32_16x16x32_bf16 v[66:69], v[94:97], v[168:171], v[66:69]
	v_mfma_f32_16x16x32_bf16 v[50:53], v[54:57], v[176:179], v[50:53]
	v_mfma_f32_16x16x32_bf16 v[46:49], v[94:97], v[176:179], v[46:49]
	v_mfma_f32_16x16x32_bf16 v[30:33], v[54:57], v[202:205], v[30:33]
	v_mfma_f32_16x16x32_bf16 v[26:29], v[94:97], v[202:205], v[26:29]
	v_mfma_f32_16x16x32_bf16 v[14:17], v[54:57], v[210:213], v[14:17]
	v_mfma_f32_16x16x32_bf16 v[10:13], v[94:97], v[210:213], v[10:13]
	s_setprio 0
	s_setprio 1
	v_mfma_f32_16x16x32_bf16 v[42:45], v[110:113], v[172:175], v[42:45]
	v_mfma_f32_16x16x32_bf16 v[38:41], v[146:149], v[172:175], v[38:41]
	v_mfma_f32_16x16x32_bf16 v[22:25], v[110:113], v[190:193], v[22:25]
	v_mfma_f32_16x16x32_bf16 v[18:21], v[146:149], v[190:193], v[18:21]
	v_mfma_f32_16x16x32_bf16 v[6:9], v[110:113], v[206:209], v[6:9]
	v_mfma_f32_16x16x32_bf16 v[2:5], v[146:149], v[206:209], v[2:5]
	v_mfma_f32_16x16x32_bf16 v[34:37], v[110:113], v[164:167], v[62:65]
	v_mfma_f32_16x16x32_bf16 v[54:57], v[146:149], v[164:167], v[58:61]
	v_mfma_f32_16x16x32_bf16 v[42:45], v[126:129], v[176:179], v[42:45]
	v_mfma_f32_16x16x32_bf16 v[38:41], v[160:163], v[176:179], v[38:41]
	v_mfma_f32_16x16x32_bf16 v[22:25], v[126:129], v[202:205], v[22:25]
	v_mfma_f32_16x16x32_bf16 v[18:21], v[160:163], v[202:205], v[18:21]
	v_mfma_f32_16x16x32_bf16 v[6:9], v[126:129], v[210:213], v[6:9]
	v_mfma_f32_16x16x32_bf16 v[2:5], v[160:163], v[210:213], v[2:5]
	v_mfma_f32_16x16x32_bf16 v[34:37], v[126:129], v[168:171], v[34:37]
	v_mfma_f32_16x16x32_bf16 v[54:57], v[160:163], v[168:171], v[54:57]
	s_barrier
; #define PG8_STAGE(bufoff, gbase, voff) do { _Pragma("unroll") for (int _i = 0; _i < 2; ++_i) { \
;         const unsigned _m0 = ldsb + (unsigned)((bufoff) + _i * 8192); const char* _gb = (const char*)(gbase); \
;         asm volatile("s_mov_b32 m0, %0\n\ts_nop 0\n\tglobal_load_lds_dwordx4 %1, %2" :: "s"(_m0), "v"((voff)[_i]), "s"(_gb) : "m0", "memory"); } } while (0)
; #define PG8_LDA(dst, b, h) do { _Pragma("unroll") for (int m = 0; m < 4; ++m) _Pragma("unroll") for (int k = 0; k < 2; ++k) dst[m][k] = *(const LAS bf16x8*)(lds + PG8_SA(b, h) + aoff + m * 2048 + k * 1024); } while (0)
; #define PG8_LDB(dst, b, h) do { _Pragma("unroll") for (int n = 0; n < 2; ++n) _Pragma("unroll") for (int k = 0; k < 2; ++k) dst[n][k] = *(const LAS bf16x8*)(lds + PG8_SB(b, h) + boff + n * 2048 + k * 1024); } while (0)
; #define PG8_MMA(ai, bj, At, Bt) do { __builtin_amdgcn_s_setprio(1); _Pragma("unroll") for (int m = 0; m < 4; ++m) _Pragma("unroll") for (int n = 0; n < 2; ++n) _Pragma("unroll") for (int k = 0; k < 2; ++k) \
;         acc[ai][bj][m][n] = __builtin_amdgcn_mfma_f32_16x16x32_bf16(Bt[n][k], At[m][k], acc[ai][bj][m][n], 0, 0, 0); __builtin_amdgcn_s_setprio(0); } while (0)
; #define PG8_WAIT_V(n) asm volatile("s_waitcnt vmcnt(" #n ")" ::: "memory")
; #define PG8_WAIT_L(n) asm volatile("s_waitcnt lgkmcnt(" #n ")" ::: "memory")
; #define PG8_BAR __builtin_amdgcn_s_barrier()
; #define PG8_SCHED __builtin_amdgcn_sched_barrier(0)
; template <class Epi, bool ALIGN_EPI>
; __device__ __forceinline__ void gemm_phase(LAS unsigned char* lds, const Gemm g, const StaticOrder& S, const Epi& E) {
;     ...
;             PG8_LDB(B0, 1, 0); PG8_LDB(B1, 1, 1); PG8_SCHED; PG8_LDA(At, 1, 0); PG8_STAGE(PG8_SA(0, 1), a2 + hstepA, voffA);
;             PG8_WAIT_V(8); PG8_WAIT_L(0); PG8_BAR; PG8_MMA(0, 0, At, B0); PG8_MMA(0, 1, At, B1); PG8_BAR; PG8_SCHED;
;             PG8_LDA(At, 1, 1); PG8_STAGE(PG8_SB(1, 0), b3, voffB); PG8_STAGE(PG8_SB(1, 1), b3 + hstepB, voffB); PG8_STAGE(PG8_SA(1, 0), a3, voffA);
;             PG8_WAIT_V(8); PG8_WAIT_L(0); PG8_BAR; PG8_MMA(1, 0, At, B0); PG8_MMA(1, 1, At, B1); PG8_BAR; PG8_SCHED;
;         }
;         if constexpr (ALIGN_EPI) { if (wr == 0) PG8_BAR; }
	s_setprio 0
	v_add_u32_e32 v0, 0x18000, v187
	ds_read_b128 v[58:61], v0
	ds_read_b128 v[62:65], v0 offset:1024
	ds_read_b128 v[74:77], v0 offset:2048
	ds_read_b128 v[94:97], v0 offset:3072
	v_add_u32_e32 v0, 0x1c000, v187
	ds_read_b128 v[110:113], v0
	ds_read_b128 v[126:129], v0 offset:1024
	ds_read_b128 v[146:149], v0 offset:2048
	ds_read_b128 v[160:163], v0 offset:3072
	ds_read_b128 v[164:167], v188 offset:32768
	ds_read_b128 v[168:171], v188 offset:33792
	ds_read_b128 v[172:175], v188 offset:34816
	ds_read_b128 v[176:179], v188 offset:35840
	ds_read_b128 v[190:193], v188 offset:36864
	ds_read_b128 v[202:205], v188 offset:37888
	ds_read_b128 v[206:209], v188 offset:38912
	ds_read_b128 v[210:213], v188 offset:39936
	s_add_u32 s54, s54, 0x40000
	s_addc_u32 s55, s55, 0
	s_mov_b32 m0, s58
	s_nop 0
	global_load_lds_dwordx4 v180, s[54:55]
	s_nop 0
	s_mov_b32 m0, s59
	s_nop 0
	global_load_lds_dwordx4 v182, s[54:55]
	s_waitcnt vmcnt(8)
	s_waitcnt lgkmcnt(0)
	s_setprio 1
	s_barrier
	v_mfma_f32_16x16x32_bf16 v[154:157], v[58:61], v[164:167], v[154:157]
	v_mfma_f32_16x16x32_bf16 v[154:157], v[62:65], v[168:171], v[154:157]
	v_mfma_f32_16x16x32_bf16 v[150:153], v[74:77], v[164:167], v[150:153]
	v_mfma_f32_16x16x32_bf16 v[150:153], v[94:97], v[168:171], v[150:153]
	v_mfma_f32_16x16x32_bf16 v[142:145], v[110:113], v[164:167], v[142:145]
	v_mfma_f32_16x16x32_bf16 v[142:145], v[126:129], v[168:171], v[142:145]
	v_mfma_f32_16x16x32_bf16 v[138:141], v[146:149], v[164:167], v[138:141]
	v_mfma_f32_16x16x32_bf16 v[138:141], v[160:163], v[168:171], v[138:141]
	v_mfma_f32_16x16x32_bf16 v[118:121], v[146:149], v[172:175], v[118:121]
	v_mfma_f32_16x16x32_bf16 v[118:121], v[160:163], v[176:179], v[118:121]
	v_mfma_f32_16x16x32_bf16 v[122:125], v[110:113], v[172:175], v[122:125]
	v_mfma_f32_16x16x32_bf16 v[122:125], v[126:129], v[176:179], v[122:125]
	v_mfma_f32_16x16x32_bf16 v[130:133], v[74:77], v[172:175], v[130:133]
	v_mfma_f32_16x16x32_bf16 v[130:133], v[94:97], v[176:179], v[130:133]
	v_mfma_f32_16x16x32_bf16 v[134:137], v[58:61], v[172:175], v[134:137]
	v_mfma_f32_16x16x32_bf16 v[134:137], v[62:65], v[176:179], v[134:137]
	v_mfma_f32_16x16x32_bf16 v[114:117], v[58:61], v[190:193], v[114:117]
	v_mfma_f32_16x16x32_bf16 v[114:117], v[62:65], v[202:205], v[114:117]
	v_mfma_f32_16x16x32_bf16 v[106:109], v[74:77], v[190:193], v[106:109]
	v_mfma_f32_16x16x32_bf16 v[106:109], v[94:97], v[202:205], v[106:109]
	v_mfma_f32_16x16x32_bf16 v[102:105], v[110:113], v[190:193], v[102:105]
	v_mfma_f32_16x16x32_bf16 v[102:105], v[126:129], v[202:205], v[102:105]
	v_mfma_f32_16x16x32_bf16 v[98:101], v[146:149], v[190:193], v[98:101]
	v_mfma_f32_16x16x32_bf16 v[98:101], v[160:163], v[202:205], v[98:101]
	v_mfma_f32_16x16x32_bf16 v[78:81], v[146:149], v[206:209], v[78:81]
	v_mfma_f32_16x16x32_bf16 v[78:81], v[160:163], v[210:213], v[78:81]
	v_mfma_f32_16x16x32_bf16 v[82:85], v[110:113], v[206:209], v[82:85]
	v_mfma_f32_16x16x32_bf16 v[82:85], v[126:129], v[210:213], v[82:85]
	v_mfma_f32_16x16x32_bf16 v[86:89], v[74:77], v[206:209], v[86:89]
	v_mfma_f32_16x16x32_bf16 v[86:89], v[94:97], v[210:213], v[86:89]
	v_mfma_f32_16x16x32_bf16 v[90:93], v[58:61], v[206:209], v[90:93]
	v_mfma_f32_16x16x32_bf16 v[90:93], v[62:65], v[210:213], v[90:93]
	s_barrier
	s_setprio 0
	ds_read_b128 v[164:167], v188 offset:49152
	ds_read_b128 v[168:171], v188 offset:50176
	ds_read_b128 v[172:175], v188 offset:51200
	ds_read_b128 v[176:179], v188 offset:52224
	ds_read_b128 v[190:193], v188 offset:53248
	ds_read_b128 v[202:205], v188 offset:54272
	ds_read_b128 v[206:209], v188 offset:55296
	ds_read_b128 v[210:213], v188 offset:56320
	s_add_u32 s54, s48, 0x80
	s_addc_u32 s55, s49, 0
	s_mov_b32 m0, s17
	s_nop 0
	global_load_lds_dwordx4 v181, s[54:55]
	s_add_u32 s48, s48, 0x40080
	s_mov_b32 m0, s60
	s_nop 0
	global_load_lds_dwordx4 v183, s[54:55]
	s_addc_u32 s49, s49, 0
	s_mov_b32 m0, s89
	s_nop 0
	global_load_lds_dwordx4 v181, s[48:49]
	s_nop 0
	s_mov_b32 m0, s90
	s_nop 0
	global_load_lds_dwordx4 v183, s[48:49]
	s_nop 0
	s_mov_b32 m0, s61
	s_nop 0
	global_load_lds_dwordx4 v180, s[38:39]
	s_nop 0
	s_mov_b32 m0, s88
	s_nop 0
	global_load_lds_dwordx4 v182, s[38:39]
	s_waitcnt vmcnt(8)
	s_waitcnt lgkmcnt(0)
	s_setprio 1
	s_barrier
	v_mfma_f32_16x16x32_bf16 v[70:73], v[58:61], v[164:167], v[70:73]
	v_mfma_f32_16x16x32_bf16 v[66:69], v[74:77], v[164:167], v[66:69]
	v_mfma_f32_16x16x32_bf16 v[50:53], v[58:61], v[172:175], v[50:53]
	v_mfma_f32_16x16x32_bf16 v[46:49], v[74:77], v[172:175], v[46:49]
	v_mfma_f32_16x16x32_bf16 v[30:33], v[58:61], v[190:193], v[30:33]
	v_mfma_f32_16x16x32_bf16 v[26:29], v[74:77], v[190:193], v[26:29]
	v_mfma_f32_16x16x32_bf16 v[14:17], v[58:61], v[206:209], v[14:17]
	v_mfma_f32_16x16x32_bf16 v[10:13], v[74:77], v[206:209], v[10:13]
	v_mfma_f32_16x16x32_bf16 v[70:73], v[62:65], v[168:171], v[70:73]
	v_mfma_f32_16x16x32_bf16 v[66:69], v[94:97], v[168:171], v[66:69]
	v_mfma_f32_16x16x32_bf16 v[50:53], v[62:65], v[176:179], v[50:53]
	v_mfma_f32_16x16x32_bf16 v[46:49], v[94:97], v[176:179], v[46:49]
	v_mfma_f32_16x16x32_bf16 v[30:33], v[62:65], v[202:205], v[30:33]
	v_mfma_f32_16x16x32_bf16 v[26:29], v[94:97], v[202:205], v[26:29]
	v_mfma_f32_16x16x32_bf16 v[14:17], v[62:65], v[210:213], v[14:17]
	v_mfma_f32_16x16x32_bf16 v[10:13], v[94:97], v[210:213], v[10:13]
	s_setprio 0
	s_setprio 1
	v_mfma_f32_16x16x32_bf16 v[34:37], v[110:113], v[164:167], v[34:37]
	v_mfma_f32_16x16x32_bf16 v[62:65], v[126:129], v[168:171], v[34:37]
	v_mfma_f32_16x16x32_bf16 v[34:37], v[146:149], v[164:167], v[54:57]
	v_mfma_f32_16x16x32_bf16 v[58:61], v[160:163], v[168:171], v[34:37]
	v_mfma_f32_16x16x32_bf16 v[34:37], v[110:113], v[172:175], v[42:45]
	v_mfma_f32_16x16x32_bf16 v[42:45], v[126:129], v[176:179], v[34:37]
	v_mfma_f32_16x16x32_bf16 v[34:37], v[146:149], v[172:175], v[38:41]
	v_mfma_f32_16x16x32_bf16 v[22:25], v[110:113], v[190:193], v[22:25]
	v_mfma_f32_16x16x32_bf16 v[18:21], v[146:149], v[190:193], v[18:21]
	v_mfma_f32_16x16x32_bf16 v[6:9], v[110:113], v[206:209], v[6:9]
	v_mfma_f32_16x16x32_bf16 v[2:5], v[146:149], v[206:209], v[2:5]
	v_mfma_f32_16x16x32_bf16 v[38:41], v[160:163], v[176:179], v[34:37]
	v_mfma_f32_16x16x32_bf16 v[22:25], v[126:129], v[202:205], v[22:25]
	v_mfma_f32_16x16x32_bf16 v[18:21], v[160:163], v[202:205], v[18:21]
	v_mfma_f32_16x16x32_bf16 v[6:9], v[126:129], v[210:213], v[6:9]
	v_mfma_f32_16x16x32_bf16 v[2:5], v[160:163], v[210:213], v[2:5]
	s_barrier
	s_setprio 0
	s_add_i32 s50, s50, 2
	s_add_u32 s29, s29, 0x100
	s_addc_u32 s41, s41, 0
	s_add_u32 s36, s36, 0x100
	s_addc_u32 s37, s37, 0
	s_cmp_gt_u32 s50, 13
	s_cbranch_scc0 .LBB0_349
	s_and_b64 vcc, exec, s[24:25]
	s_cbranch_vccz .LBB0_352
	s_barrier
